# speedup vs baseline: 1.0169x; 1.0121x over previous
; #define LOADG(S, GRP) do { const u16* _k = kb + (size_t)(GRP) * 4096; \
;       _Pragma("unroll") for (int _i = 0; _i < 4; ++_i) { kf[S][2 * _i] = *(const bf16x8*)(_k + _i * 1024); kf[S][2 * _i + 1] = *(const bf16x8*)(_k + _i * 1024 + 32); } } while (0)
; DEVINL void phase_topk(const Params& p, int layer, char* smem, int wv, int rep) {
;     ...
;     {
;       int g = wid;
;       if (g < ng) LOADG(0, g);
;       for (; g < ng; g += 16) {
;         if (g + 8 < ng) LOADG(1, g + 8);
;         COMPUTEG(0, g);
;         if (g + 8 < ng) {
;           if (g + 16 < ng) LOADG(0, g + 16);
;           COMPUTEG(1, g + 8);
;         }
;       }
;     }
.LBB0_474:
	v_mfma_f32_16x16x32_bf16 v[170:173], v[0:3], v[96:99], 0
	v_add_u32_e32 v169, 0xffff0800, v165
	v_mfma_f32_16x16x32_bf16 v[170:173], v[4:7], v[92:95], v[170:173]
	v_mfma_f32_16x16x32_bf16 v[178:181], v[0:3], v[88:91], 0
	s_nop 6
	v_max_f32_e32 v171, 0, v171
	v_max_f32_e32 v170, 0, v170
	v_mul_f32_e32 v174, v13, v171
	v_max_f32_e32 v172, 0, v172
	v_fmac_f32_e32 v174, v12, v170
	v_fmac_f32_e32 v174, v14, v172
	v_max_f32_e32 v170, 0, v173
	v_fmac_f32_e32 v174, v15, v170
	v_mfma_f32_16x16x32_bf16 v[170:173], v[4:7], v[84:87], v[178:181]
	v_mfma_f32_16x16x32_bf16 v[178:181], v[0:3], v[120:123], 0
	s_nop 6
	v_max_f32_e32 v171, 0, v171
	v_max_f32_e32 v170, 0, v170
	v_mul_f32_e32 v175, v13, v171
	v_fmac_f32_e32 v175, v12, v170
	v_max_f32_e32 v170, 0, v172
	v_fmac_f32_e32 v175, v14, v170
	v_max_f32_e32 v170, 0, v173
	v_fmac_f32_e32 v175, v15, v170
	v_mfma_f32_16x16x32_bf16 v[170:173], v[4:7], v[116:119], v[178:181]
	s_nop 0
	v_permlane16_swap_b32_e32 v174, v175
	v_add_f32_e32 v174, v174, v175
	v_mfma_f32_16x16x32_bf16 v[178:181], v[0:3], v[112:115], 0
	s_nop 3
	v_max_f32_e32 v171, 0, v171
	v_max_f32_e32 v170, 0, v170
	v_mul_f32_e32 v177, v13, v171
	v_fmac_f32_e32 v177, v12, v170
	v_max_f32_e32 v170, 0, v172
	v_fmac_f32_e32 v177, v14, v170
	v_max_f32_e32 v170, 0, v173
	v_fmac_f32_e32 v177, v15, v170
	v_mfma_f32_16x16x32_bf16 v[170:173], v[4:7], v[108:111], v[178:181]
	v_mfma_f32_16x16x32_bf16 v[178:181], v[16:19], v[88:91], 0
	s_nop 6
	v_max_f32_e32 v171, 0, v171
	v_max_f32_e32 v170, 0, v170
	v_mul_f32_e32 v171, v13, v171
	v_fmac_f32_e32 v171, v12, v170
	v_max_f32_e32 v170, 0, v172
	v_fmac_f32_e32 v171, v14, v170
	v_max_f32_e32 v170, 0, v173
	v_fmac_f32_e32 v171, v15, v170
	s_nop 1
	v_permlane16_swap_b32_e32 v177, v171
	v_add_f32_e32 v175, v177, v171
	v_mfma_f32_16x16x32_bf16 v[170:173], v[16:19], v[96:99], 0
	s_nop 0
	v_permlane32_swap_b32_e32 v174, v175
	v_add_f32_e32 v174, v174, v175
	v_mfma_f32_16x16x32_bf16 v[170:173], v[8:11], v[92:95], v[170:173]
	ds_write_b32 v169, v174
	s_nop 6
	v_max_f32_e32 v169, v170, v170
	v_max_f32_e32 v170, 0, v171
	v_max_f32_e32 v169, 0, v169
	v_mul_f32_e32 v174, v21, v170
	v_fmac_f32_e32 v174, v20, v169
	v_max_f32_e32 v169, 0, v172
	v_fmac_f32_e32 v174, v22, v169
	v_max_f32_e32 v169, v173, v173
	v_mfma_f32_16x16x32_bf16 v[170:173], v[8:11], v[84:87], v[178:181]
	v_max_f32_e32 v169, 0, v169
	v_fmac_f32_e32 v174, v23, v169
	v_mfma_f32_16x16x32_bf16 v[178:181], v[16:19], v[120:123], 0
	s_nop 4
	v_max_f32_e32 v169, v170, v170
	v_max_f32_e32 v170, 0, v171
	v_max_f32_e32 v169, 0, v169
	v_mul_f32_e32 v175, v21, v170
	v_fmac_f32_e32 v175, v20, v169
	v_max_f32_e32 v169, 0, v172
	v_fmac_f32_e32 v175, v22, v169
	v_max_f32_e32 v169, v173, v173
	v_mfma_f32_16x16x32_bf16 v[170:173], v[8:11], v[116:119], v[178:181]
	v_max_f32_e32 v169, 0, v169
	v_fmac_f32_e32 v175, v23, v169
	s_nop 1
	v_permlane16_swap_b32_e32 v174, v175
	v_mfma_f32_16x16x32_bf16 v[178:181], v[16:19], v[112:115], 0
	s_nop 1
	v_max_f32_e32 v169, v170, v170
	v_max_f32_e32 v170, 0, v171
	v_max_f32_e32 v169, 0, v169
	v_mul_f32_e32 v177, v21, v170
	v_fmac_f32_e32 v177, v20, v169
	v_max_f32_e32 v169, 0, v172
	v_fmac_f32_e32 v177, v22, v169
	v_max_f32_e32 v169, v173, v173
	v_mfma_f32_16x16x32_bf16 v[170:173], v[8:11], v[108:111], v[178:181]
	v_max_f32_e32 v169, 0, v169
	v_fmac_f32_e32 v177, v23, v169
	v_mfma_f32_16x16x32_bf16 v[178:181], v[24:27], v[88:91], 0
	s_nop 4
	v_max_f32_e32 v169, v170, v170
	v_max_f32_e32 v170, 0, v171
	v_max_f32_e32 v169, 0, v169
	v_mul_f32_e32 v170, v21, v170
	v_fmac_f32_e32 v170, v20, v169
	v_max_f32_e32 v169, 0, v172
	v_fmac_f32_e32 v170, v22, v169
	v_max_f32_e32 v169, 0, v173
	v_fmac_f32_e32 v170, v23, v169
	s_nop 1
	v_permlane16_swap_b32_e32 v177, v170
	v_add_f32_e32 v169, v174, v175
	v_add_f32_e32 v174, v177, v170
	v_mfma_f32_16x16x32_bf16 v[170:173], v[24:27], v[96:99], 0
	s_nop 0
	v_permlane32_swap_b32_e32 v169, v174
	v_add_f32_e32 v169, v169, v174
	v_mfma_f32_16x16x32_bf16 v[170:173], v[28:31], v[92:95], v[170:173]
	v_add_u32_e32 v174, 0xffff4800, v165
	ds_write_b32 v174, v169
	s_nop 5
	v_max_f32_e32 v169, v170, v170
	v_max_f32_e32 v170, 0, v171
	v_max_f32_e32 v169, 0, v169
	v_mul_f32_e32 v174, v37, v170
	v_fmac_f32_e32 v174, v36, v169
	v_max_f32_e32 v169, 0, v172
	v_fmac_f32_e32 v174, v38, v169
	v_max_f32_e32 v169, v173, v173
	v_mfma_f32_16x16x32_bf16 v[170:173], v[28:31], v[84:87], v[178:181]
	v_max_f32_e32 v169, 0, v169
	v_fmac_f32_e32 v174, v39, v169
	v_mfma_f32_16x16x32_bf16 v[178:181], v[24:27], v[120:123], 0
	s_nop 4
	v_max_f32_e32 v169, v170, v170
	v_max_f32_e32 v170, 0, v171
	v_max_f32_e32 v169, 0, v169
	v_mul_f32_e32 v175, v37, v170
	v_fmac_f32_e32 v175, v36, v169
	v_max_f32_e32 v169, 0, v172
	v_fmac_f32_e32 v175, v38, v169
	v_max_f32_e32 v169, v173, v173
	v_mfma_f32_16x16x32_bf16 v[170:173], v[28:31], v[116:119], v[178:181]
	v_max_f32_e32 v169, 0, v169
	v_fmac_f32_e32 v175, v39, v169
	s_nop 1
	v_permlane16_swap_b32_e32 v174, v175
	v_mfma_f32_16x16x32_bf16 v[178:181], v[24:27], v[112:115], 0
	s_nop 1
	v_max_f32_e32 v169, v170, v170
	v_max_f32_e32 v170, 0, v171
	v_max_f32_e32 v169, 0, v169
	v_mul_f32_e32 v177, v37, v170
	v_fmac_f32_e32 v177, v36, v169
	v_max_f32_e32 v169, 0, v172
	v_fmac_f32_e32 v177, v38, v169
	v_max_f32_e32 v169, v173, v173
	v_mfma_f32_16x16x32_bf16 v[170:173], v[28:31], v[108:111], v[178:181]
	v_max_f32_e32 v169, 0, v169
	v_fmac_f32_e32 v177, v39, v169
	v_mfma_f32_16x16x32_bf16 v[178:181], v[40:43], v[88:91], 0
	s_nop 4
	v_max_f32_e32 v169, v170, v170
	v_max_f32_e32 v170, 0, v171
	v_max_f32_e32 v169, 0, v169
	v_mul_f32_e32 v170, v37, v170
	v_fmac_f32_e32 v170, v36, v169
	v_max_f32_e32 v169, 0, v172
; #define LOADG(S, GRP) do { const u16* _k = kb + (size_t)(GRP) * 4096; \
;       _Pragma("unroll") for (int _i = 0; _i < 4; ++_i) { kf[S][2 * _i] = *(const bf16x8*)(_k + _i * 1024); kf[S][2 * _i + 1] = *(const bf16x8*)(_k + _i * 1024 + 32); } } while (0)
; DEVINL void phase_topk(const Params& p, int layer, char* smem, int wv, int rep) {
;     ...
;     {
;       int g = wid;
;       if (g < ng) LOADG(0, g);
;       for (; g < ng; g += 16) {
;         if (g + 8 < ng) LOADG(1, g + 8);
;         COMPUTEG(0, g);
;         if (g + 8 < ng) {
;           if (g + 16 < ng) LOADG(0, g + 16);
;           COMPUTEG(1, g + 8);
;         }
;       }
;     }
	v_fmac_f32_e32 v170, v38, v169
	v_max_f32_e32 v169, 0, v173
	v_fmac_f32_e32 v170, v39, v169
	s_nop 1
	v_permlane16_swap_b32_e32 v177, v170
	v_add_f32_e32 v169, v174, v175
	v_add_f32_e32 v174, v177, v170
	v_mfma_f32_16x16x32_bf16 v[170:173], v[40:43], v[96:99], 0
	s_nop 0
	v_permlane32_swap_b32_e32 v169, v174
	v_add_f32_e32 v169, v169, v174
	v_mfma_f32_16x16x32_bf16 v[170:173], v[32:35], v[92:95], v[170:173]
	v_add_u32_e32 v174, 0xffff8800, v165
	ds_write_b32 v174, v169
	s_nop 5
	v_max_f32_e32 v169, v170, v170
	v_max_f32_e32 v170, 0, v171
	v_max_f32_e32 v169, 0, v169
	v_mul_f32_e32 v174, v45, v170
	v_fmac_f32_e32 v174, v44, v169
	v_max_f32_e32 v169, 0, v172
	v_fmac_f32_e32 v174, v46, v169
	v_max_f32_e32 v169, v173, v173
	v_mfma_f32_16x16x32_bf16 v[170:173], v[32:35], v[84:87], v[178:181]
	v_max_f32_e32 v169, 0, v169
	v_fmac_f32_e32 v174, v47, v169
	v_mfma_f32_16x16x32_bf16 v[178:181], v[40:43], v[120:123], 0
	s_nop 4
	v_max_f32_e32 v169, v170, v170
	v_max_f32_e32 v170, 0, v171
	v_max_f32_e32 v169, 0, v169
	v_mul_f32_e32 v175, v45, v170
	v_fmac_f32_e32 v175, v44, v169
	v_max_f32_e32 v169, 0, v172
	v_fmac_f32_e32 v175, v46, v169
	v_max_f32_e32 v169, v173, v173
	v_mfma_f32_16x16x32_bf16 v[170:173], v[32:35], v[116:119], v[178:181]
	v_max_f32_e32 v169, 0, v169
	v_fmac_f32_e32 v175, v47, v169
	s_nop 1
	v_permlane16_swap_b32_e32 v174, v175
	v_mfma_f32_16x16x32_bf16 v[178:181], v[40:43], v[112:115], 0
	s_nop 1
	v_max_f32_e32 v169, v170, v170
	v_max_f32_e32 v170, 0, v171
	v_max_f32_e32 v169, 0, v169
	v_mul_f32_e32 v177, v45, v170
	v_fmac_f32_e32 v177, v44, v169
	v_max_f32_e32 v169, 0, v172
	v_fmac_f32_e32 v177, v46, v169
	v_max_f32_e32 v169, v173, v173
	v_mfma_f32_16x16x32_bf16 v[170:173], v[32:35], v[108:111], v[178:181]
	v_max_f32_e32 v169, 0, v169
	v_fmac_f32_e32 v177, v47, v169
	v_mfma_f32_16x16x32_bf16 v[178:181], v[52:55], v[88:91], 0
	s_nop 4
	v_max_f32_e32 v169, v170, v170
	v_max_f32_e32 v170, 0, v171
	v_max_f32_e32 v169, 0, v169
	v_mul_f32_e32 v170, v45, v170
	v_fmac_f32_e32 v170, v44, v169
	v_max_f32_e32 v169, 0, v172
	v_fmac_f32_e32 v170, v46, v169
	v_max_f32_e32 v169, 0, v173
	v_fmac_f32_e32 v170, v47, v169
	s_nop 1
	v_permlane16_swap_b32_e32 v177, v170
	v_add_f32_e32 v169, v174, v175
	v_add_f32_e32 v174, v177, v170
	v_mfma_f32_16x16x32_bf16 v[170:173], v[52:55], v[96:99], 0
	s_nop 0
	v_permlane32_swap_b32_e32 v169, v174
	v_add_f32_e32 v169, v169, v174
	v_mfma_f32_16x16x32_bf16 v[170:173], v[48:51], v[92:95], v[170:173]
	v_add_u32_e32 v174, 0xffffc800, v165
	ds_write_b32 v174, v169
	s_nop 5
	v_max_f32_e32 v169, v170, v170
	v_max_f32_e32 v170, 0, v171
	v_max_f32_e32 v169, 0, v169
	v_mul_f32_e32 v174, v57, v170
	v_fmac_f32_e32 v174, v56, v169
	v_max_f32_e32 v169, 0, v172
	v_fmac_f32_e32 v174, v58, v169
	v_max_f32_e32 v169, v173, v173
	v_mfma_f32_16x16x32_bf16 v[170:173], v[48:51], v[84:87], v[178:181]
	v_max_f32_e32 v169, 0, v169
	v_fmac_f32_e32 v174, v59, v169
	v_mfma_f32_16x16x32_bf16 v[178:181], v[52:55], v[120:123], 0
	s_nop 4
	v_max_f32_e32 v169, v170, v170
	v_max_f32_e32 v170, 0, v171
	v_max_f32_e32 v169, 0, v169
	v_mul_f32_e32 v175, v57, v170
	v_fmac_f32_e32 v175, v56, v169
	v_max_f32_e32 v169, 0, v172
	v_fmac_f32_e32 v175, v58, v169
	v_max_f32_e32 v169, v173, v173
	v_mfma_f32_16x16x32_bf16 v[170:173], v[48:51], v[116:119], v[178:181]
	v_max_f32_e32 v169, 0, v169
	v_fmac_f32_e32 v175, v59, v169
	s_nop 1
	v_permlane16_swap_b32_e32 v174, v175
	v_mfma_f32_16x16x32_bf16 v[178:181], v[52:55], v[112:115], 0
	s_nop 1
	v_max_f32_e32 v169, v170, v170
	v_max_f32_e32 v170, 0, v171
	v_max_f32_e32 v169, 0, v169
	v_mul_f32_e32 v177, v57, v170
	v_fmac_f32_e32 v177, v56, v169
	v_max_f32_e32 v169, 0, v172
	v_fmac_f32_e32 v177, v58, v169
	v_max_f32_e32 v169, v173, v173
	v_mfma_f32_16x16x32_bf16 v[170:173], v[48:51], v[108:111], v[178:181]
	v_max_f32_e32 v169, 0, v169
	v_fmac_f32_e32 v177, v59, v169
	v_mfma_f32_16x16x32_bf16 v[178:181], v[60:63], v[88:91], 0
	s_nop 4
	v_max_f32_e32 v169, v170, v170
	v_max_f32_e32 v170, 0, v171
	v_max_f32_e32 v169, 0, v169
	v_mul_f32_e32 v170, v57, v170
	v_fmac_f32_e32 v170, v56, v169
	v_max_f32_e32 v169, 0, v172
	v_fmac_f32_e32 v170, v58, v169
	v_max_f32_e32 v169, 0, v173
	v_fmac_f32_e32 v170, v59, v169
	s_nop 1
	v_permlane16_swap_b32_e32 v177, v170
	v_add_f32_e32 v169, v174, v175
	v_add_f32_e32 v174, v177, v170
	v_mfma_f32_16x16x32_bf16 v[170:173], v[60:63], v[96:99], 0
	s_nop 0
	v_permlane32_swap_b32_e32 v169, v174
	v_add_f32_e32 v169, v169, v174
	v_mfma_f32_16x16x32_bf16 v[170:173], v[64:67], v[92:95], v[170:173]
	s_nop 7
	v_max_f32_e32 v171, 0, v171
	v_max_f32_e32 v170, 0, v170
	v_mul_f32_e32 v174, v69, v171
	v_fmac_f32_e32 v174, v68, v170
	v_max_f32_e32 v170, 0, v172
	v_fmac_f32_e32 v174, v70, v170
	v_max_f32_e32 v170, 0, v173
	v_fmac_f32_e32 v174, v71, v170
	v_mfma_f32_16x16x32_bf16 v[170:173], v[64:67], v[84:87], v[178:181]
	v_mfma_f32_16x16x32_bf16 v[178:181], v[60:63], v[120:123], 0
	s_nop 6
	v_max_f32_e32 v171, 0, v171
	v_max_f32_e32 v170, 0, v170
	v_mul_f32_e32 v175, v69, v171
; #define LOADG(S, GRP) do { const u16* _k = kb + (size_t)(GRP) * 4096; \
;       _Pragma("unroll") for (int _i = 0; _i < 4; ++_i) { kf[S][2 * _i] = *(const bf16x8*)(_k + _i * 1024); kf[S][2 * _i + 1] = *(const bf16x8*)(_k + _i * 1024 + 32); } } while (0)
; DEVINL void phase_topk(const Params& p, int layer, char* smem, int wv, int rep) {
;     ...
;     {
;       int g = wid;
;       if (g < ng) LOADG(0, g);
;       for (; g < ng; g += 16) {
;         if (g + 8 < ng) LOADG(1, g + 8);
;         COMPUTEG(0, g);
;         if (g + 8 < ng) {
;           if (g + 16 < ng) LOADG(0, g + 16);
;           COMPUTEG(1, g + 8);
;         }
;       }
;     }
	v_fmac_f32_e32 v175, v68, v170
	v_max_f32_e32 v170, 0, v172
	v_fmac_f32_e32 v175, v70, v170
	v_max_f32_e32 v170, 0, v173
	v_fmac_f32_e32 v175, v71, v170
	v_mfma_f32_16x16x32_bf16 v[170:173], v[64:67], v[116:119], v[178:181]
	s_nop 0
	v_permlane16_swap_b32_e32 v174, v175
	v_add_f32_e32 v174, v174, v175
	v_mfma_f32_16x16x32_bf16 v[178:181], v[60:63], v[112:115], 0
	s_nop 3
	v_max_f32_e32 v171, 0, v171
	v_max_f32_e32 v170, 0, v170
	v_mul_f32_e32 v177, v69, v171
	v_fmac_f32_e32 v177, v68, v170
	v_max_f32_e32 v170, 0, v172
	v_fmac_f32_e32 v177, v70, v170
	v_max_f32_e32 v170, 0, v173
	v_fmac_f32_e32 v177, v71, v170
	v_mfma_f32_16x16x32_bf16 v[170:173], v[64:67], v[108:111], v[178:181]
	v_mfma_f32_16x16x32_bf16 v[178:181], v[72:75], v[88:91], 0
	s_nop 6
	v_max_f32_e32 v171, 0, v171
	v_max_f32_e32 v170, 0, v170
	v_mul_f32_e32 v171, v69, v171
	v_fmac_f32_e32 v171, v68, v170
	v_max_f32_e32 v170, 0, v172
	v_fmac_f32_e32 v171, v70, v170
	v_max_f32_e32 v170, 0, v173
	v_fmac_f32_e32 v171, v71, v170
	s_nop 1
	v_permlane16_swap_b32_e32 v177, v171
	v_add_f32_e32 v175, v177, v171
	v_mfma_f32_16x16x32_bf16 v[170:173], v[72:75], v[96:99], 0
	s_nop 0
	v_permlane32_swap_b32_e32 v174, v175
	v_add_f32_e32 v174, v174, v175
	v_mfma_f32_16x16x32_bf16 v[170:173], v[76:79], v[92:95], v[170:173]
	ds_write2st64_b32 v165, v169, v174 offset0:8 offset1:72
	s_nop 6
	v_max_f32_e32 v169, v170, v170
	v_max_f32_e32 v170, 0, v171
	v_max_f32_e32 v169, 0, v169
	v_mul_f32_e32 v174, v81, v170
	v_fmac_f32_e32 v174, v80, v169
	v_max_f32_e32 v169, 0, v172
	v_fmac_f32_e32 v174, v82, v169
	v_max_f32_e32 v169, v173, v173
	v_mfma_f32_16x16x32_bf16 v[170:173], v[76:79], v[84:87], v[178:181]
	v_max_f32_e32 v169, 0, v169
	v_fmac_f32_e32 v174, v83, v169
	v_mfma_f32_16x16x32_bf16 v[178:181], v[72:75], v[120:123], 0
	s_nop 4
	v_max_f32_e32 v169, v170, v170
	v_max_f32_e32 v170, 0, v171
	v_max_f32_e32 v169, 0, v169
	v_mul_f32_e32 v175, v81, v170
	v_fmac_f32_e32 v175, v80, v169
	v_max_f32_e32 v169, 0, v172
	v_fmac_f32_e32 v175, v82, v169
	v_max_f32_e32 v169, v173, v173
	v_mfma_f32_16x16x32_bf16 v[170:173], v[76:79], v[116:119], v[178:181]
	v_max_f32_e32 v169, 0, v169
	v_fmac_f32_e32 v175, v83, v169
	s_nop 1
	v_permlane16_swap_b32_e32 v174, v175
	v_mfma_f32_16x16x32_bf16 v[178:181], v[72:75], v[112:115], 0
	s_nop 1
	v_max_f32_e32 v169, v170, v170
	v_max_f32_e32 v170, 0, v171
	v_max_f32_e32 v169, 0, v169
	v_mul_f32_e32 v177, v81, v170
	v_fmac_f32_e32 v177, v80, v169
	v_max_f32_e32 v169, 0, v172
	v_fmac_f32_e32 v177, v82, v169
	v_max_f32_e32 v169, v173, v173
	v_mfma_f32_16x16x32_bf16 v[170:173], v[76:79], v[108:111], v[178:181]
	v_max_f32_e32 v169, 0, v169
	v_fmac_f32_e32 v177, v83, v169
	v_mfma_f32_16x16x32_bf16 v[178:181], v[100:103], v[88:91], 0
	s_nop 4
	v_max_f32_e32 v169, v170, v170
	v_max_f32_e32 v170, 0, v171
	v_max_f32_e32 v169, 0, v169
	v_mul_f32_e32 v170, v81, v170
	v_fmac_f32_e32 v170, v80, v169
	v_max_f32_e32 v169, 0, v172
	v_fmac_f32_e32 v170, v82, v169
	v_max_f32_e32 v169, 0, v173
	v_fmac_f32_e32 v170, v83, v169
	s_nop 1
	v_permlane16_swap_b32_e32 v177, v170
	v_add_f32_e32 v169, v174, v175
	v_add_f32_e32 v174, v177, v170
	v_mfma_f32_16x16x32_bf16 v[170:173], v[100:103], v[96:99], 0
	s_nop 0
	v_permlane32_swap_b32_e32 v169, v174
	v_add_f32_e32 v169, v169, v174
	v_mfma_f32_16x16x32_bf16 v[170:173], v[104:107], v[92:95], v[170:173]
	s_nop 7
	v_max_f32_e32 v171, 0, v171
	v_max_f32_e32 v170, 0, v170
	v_mul_f32_e32 v174, v141, v171
	v_fmac_f32_e32 v174, v140, v170
	v_max_f32_e32 v170, 0, v172
	v_fmac_f32_e32 v174, v142, v170
	v_max_f32_e32 v170, 0, v173
	v_fmac_f32_e32 v174, v143, v170
	v_mfma_f32_16x16x32_bf16 v[170:173], v[104:107], v[84:87], v[178:181]
	v_mfma_f32_16x16x32_bf16 v[178:181], v[100:103], v[120:123], 0
	s_nop 6
	v_max_f32_e32 v171, 0, v171
	v_max_f32_e32 v170, 0, v170
	v_mul_f32_e32 v175, v141, v171
	v_fmac_f32_e32 v175, v140, v170
	v_max_f32_e32 v170, 0, v172
	v_fmac_f32_e32 v175, v142, v170
	v_max_f32_e32 v170, 0, v173
	v_fmac_f32_e32 v175, v143, v170
	v_mfma_f32_16x16x32_bf16 v[170:173], v[104:107], v[116:119], v[178:181]
	s_nop 0
	v_permlane16_swap_b32_e32 v174, v175
	v_mfma_f32_16x16x32_bf16 v[178:181], v[100:103], v[112:115], 0
	s_nop 4
	v_max_f32_e32 v171, 0, v171
	v_max_f32_e32 v170, 0, v170
	v_mul_f32_e32 v177, v141, v171
	v_fmac_f32_e32 v177, v140, v170
	v_max_f32_e32 v170, 0, v172
	v_fmac_f32_e32 v177, v142, v170
	v_max_f32_e32 v170, 0, v173
	v_fmac_f32_e32 v177, v143, v170
	v_mfma_f32_16x16x32_bf16 v[170:173], v[104:107], v[108:111], v[178:181]
	s_nop 7
	v_max_f32_e32 v171, 0, v171
	v_max_f32_e32 v170, 0, v170
	v_mul_f32_e32 v171, v141, v171
	v_fmac_f32_e32 v171, v140, v170
	v_max_f32_e32 v170, 0, v172
	v_fmac_f32_e32 v171, v142, v170
	v_max_f32_e32 v170, 0, v173
	v_fmac_f32_e32 v171, v143, v170
	s_nop 1
	v_permlane16_swap_b32_e32 v177, v171
	v_add_f32_e32 v170, v174, v175
	v_add_f32_e32 v171, v177, v171
	s_nop 1
	v_permlane32_swap_b32_e32 v170, v171
	v_add_f32_e32 v170, v170, v171
	ds_write2st64_b32 v165, v169, v170 offset0:136 offset1:200

; #define LOADG(S, GRP) do { const u16* _k = kb + (size_t)(GRP) * 4096; \
;       _Pragma("unroll") for (int _i = 0; _i < 4; ++_i) { kf[S][2 * _i] = *(const bf16x8*)(_k + _i * 1024); kf[S][2 * _i + 1] = *(const bf16x8*)(_k + _i * 1024 + 32); } } while (0)
; DEVINL void phase_topk(const Params& p, int layer, char* smem, int wv, int rep) {
;     ...
;     {
;       int g = wid;
;       if (g < ng) LOADG(0, g);
;       for (; g < ng; g += 16) {
;         if (g + 8 < ng) LOADG(1, g + 8);
;         COMPUTEG(0, g);
;         if (g + 8 < ng) {
;           if (g + 16 < ng) LOADG(0, g + 16);
;           COMPUTEG(1, g + 8);
;         }
;       }
;     }
.LBB0_478:
	s_waitcnt vmcnt(7)
	v_mfma_f32_16x16x32_bf16 v[170:173], v[0:3], v[124:127], 0
	v_add_u32_e32 v169, 0xffff0000, v165
	s_andn2_b64 vcc, exec, s[0:1]
	s_add_i32 s3, s3, 16
	s_waitcnt vmcnt(6)
	v_mfma_f32_16x16x32_bf16 v[170:173], v[4:7], v[128:131], v[170:173]
	s_waitcnt vmcnt(5)
	v_mfma_f32_16x16x32_bf16 v[178:181], v[0:3], v[132:135], 0
	s_nop 5
	v_max_f32_e32 v171, 0, v171
	v_max_f32_e32 v170, 0, v170
	v_mul_f32_e32 v174, v13, v171
	v_max_f32_e32 v172, 0, v172
	v_fmac_f32_e32 v174, v12, v170
	v_fmac_f32_e32 v174, v14, v172
	v_max_f32_e32 v170, 0, v173
	v_fmac_f32_e32 v174, v15, v170
	s_waitcnt vmcnt(4)
	v_mfma_f32_16x16x32_bf16 v[170:173], v[4:7], v[136:139], v[178:181]
	s_waitcnt vmcnt(3)
	v_mfma_f32_16x16x32_bf16 v[178:181], v[0:3], v[144:147], 0
	s_nop 5
	v_max_f32_e32 v171, 0, v171
	v_max_f32_e32 v170, 0, v170
	v_mul_f32_e32 v175, v13, v171
	v_fmac_f32_e32 v175, v12, v170
	v_max_f32_e32 v170, 0, v172
	v_fmac_f32_e32 v175, v14, v170
	v_max_f32_e32 v170, 0, v173
	v_fmac_f32_e32 v175, v15, v170
	s_waitcnt vmcnt(2)
	v_mfma_f32_16x16x32_bf16 v[170:173], v[4:7], v[148:151], v[178:181]
	v_permlane16_swap_b32_e32 v174, v175
	v_add_f32_e32 v174, v174, v175
	s_waitcnt vmcnt(1)
	v_mfma_f32_16x16x32_bf16 v[178:181], v[0:3], v[152:155], 0
	s_nop 3
	v_max_f32_e32 v171, 0, v171
	v_max_f32_e32 v170, 0, v170
	v_mul_f32_e32 v177, v13, v171
	v_fmac_f32_e32 v177, v12, v170
	v_max_f32_e32 v170, 0, v172
	v_fmac_f32_e32 v177, v14, v170
	v_max_f32_e32 v170, 0, v173
	v_fmac_f32_e32 v177, v15, v170
	s_waitcnt vmcnt(0)
	v_mfma_f32_16x16x32_bf16 v[170:173], v[4:7], v[156:159], v[178:181]
	v_mfma_f32_16x16x32_bf16 v[178:181], v[16:19], v[132:135], 0
	s_nop 6
	v_max_f32_e32 v171, 0, v171
	v_max_f32_e32 v170, 0, v170
	v_mul_f32_e32 v171, v13, v171
	v_fmac_f32_e32 v171, v12, v170
	v_max_f32_e32 v170, 0, v172
	v_fmac_f32_e32 v171, v14, v170
	v_max_f32_e32 v170, 0, v173
	v_fmac_f32_e32 v171, v15, v170
	s_nop 1
	v_permlane16_swap_b32_e32 v177, v171
	v_add_f32_e32 v175, v177, v171
	v_mfma_f32_16x16x32_bf16 v[170:173], v[16:19], v[124:127], 0
	s_nop 0
	v_permlane32_swap_b32_e32 v174, v175
	v_add_f32_e32 v174, v174, v175
	v_mfma_f32_16x16x32_bf16 v[170:173], v[8:11], v[128:131], v[170:173]
	ds_write_b32 v169, v174
	s_nop 6
	v_max_f32_e32 v169, v170, v170
	v_max_f32_e32 v170, 0, v171
	v_max_f32_e32 v169, 0, v169
	v_mul_f32_e32 v174, v21, v170
	v_fmac_f32_e32 v174, v20, v169
	v_max_f32_e32 v169, 0, v172
	v_fmac_f32_e32 v174, v22, v169
	v_max_f32_e32 v169, v173, v173
	v_mfma_f32_16x16x32_bf16 v[170:173], v[8:11], v[136:139], v[178:181]
	v_max_f32_e32 v169, 0, v169
	v_fmac_f32_e32 v174, v23, v169
	v_mfma_f32_16x16x32_bf16 v[178:181], v[16:19], v[144:147], 0
	s_nop 4
	v_max_f32_e32 v169, v170, v170
	v_max_f32_e32 v170, 0, v171
	v_max_f32_e32 v169, 0, v169
	v_mul_f32_e32 v175, v21, v170
	v_fmac_f32_e32 v175, v20, v169
	v_max_f32_e32 v169, 0, v172
	v_fmac_f32_e32 v175, v22, v169
	v_max_f32_e32 v169, v173, v173
	v_mfma_f32_16x16x32_bf16 v[170:173], v[8:11], v[148:151], v[178:181]
	v_max_f32_e32 v169, 0, v169
	v_fmac_f32_e32 v175, v23, v169
	s_nop 1
	v_permlane16_swap_b32_e32 v174, v175
	v_mfma_f32_16x16x32_bf16 v[178:181], v[16:19], v[152:155], 0
	s_nop 1
	v_max_f32_e32 v169, v170, v170
	v_max_f32_e32 v170, 0, v171
	v_max_f32_e32 v169, 0, v169
	v_mul_f32_e32 v177, v21, v170
	v_fmac_f32_e32 v177, v20, v169
	v_max_f32_e32 v169, 0, v172
	v_fmac_f32_e32 v177, v22, v169
	v_max_f32_e32 v169, v173, v173
	v_mfma_f32_16x16x32_bf16 v[170:173], v[8:11], v[156:159], v[178:181]
	v_max_f32_e32 v169, 0, v169
	v_fmac_f32_e32 v177, v23, v169
	v_mfma_f32_16x16x32_bf16 v[178:181], v[24:27], v[132:135], 0
	s_nop 4
	v_max_f32_e32 v169, v170, v170
	v_max_f32_e32 v170, 0, v171
	v_max_f32_e32 v169, 0, v169
	v_mul_f32_e32 v170, v21, v170
	v_fmac_f32_e32 v170, v20, v169
	v_max_f32_e32 v169, 0, v172
	v_fmac_f32_e32 v170, v22, v169
	v_max_f32_e32 v169, 0, v173
	v_fmac_f32_e32 v170, v23, v169
	s_nop 1
	v_permlane16_swap_b32_e32 v177, v170
	v_add_f32_e32 v169, v174, v175
	v_add_f32_e32 v174, v177, v170
	v_mfma_f32_16x16x32_bf16 v[170:173], v[24:27], v[124:127], 0
	s_nop 0
	v_permlane32_swap_b32_e32 v169, v174
	v_add_f32_e32 v169, v169, v174
	v_mfma_f32_16x16x32_bf16 v[170:173], v[28:31], v[128:131], v[170:173]
	v_add_u32_e32 v174, 0xffff4000, v165
	ds_write_b32 v174, v169
	s_nop 5
	v_max_f32_e32 v169, v170, v170
	v_max_f32_e32 v170, 0, v171
	v_max_f32_e32 v169, 0, v169
	v_mul_f32_e32 v174, v37, v170
	v_fmac_f32_e32 v174, v36, v169
	v_max_f32_e32 v169, 0, v172
	v_fmac_f32_e32 v174, v38, v169
	v_max_f32_e32 v169, v173, v173
	v_mfma_f32_16x16x32_bf16 v[170:173], v[28:31], v[136:139], v[178:181]
	v_max_f32_e32 v169, 0, v169
	v_fmac_f32_e32 v174, v39, v169
	v_mfma_f32_16x16x32_bf16 v[178:181], v[24:27], v[144:147], 0
	s_nop 4
	v_max_f32_e32 v169, v170, v170
	v_max_f32_e32 v170, 0, v171
	v_max_f32_e32 v169, 0, v169
	v_mul_f32_e32 v175, v37, v170
	v_fmac_f32_e32 v175, v36, v169
	v_max_f32_e32 v169, 0, v172
	v_fmac_f32_e32 v175, v38, v169
	v_max_f32_e32 v169, v173, v173
	v_mfma_f32_16x16x32_bf16 v[170:173], v[28:31], v[148:151], v[178:181]
	v_max_f32_e32 v169, 0, v169
	v_fmac_f32_e32 v175, v39, v169
	s_nop 1
	v_permlane16_swap_b32_e32 v174, v175
	v_mfma_f32_16x16x32_bf16 v[178:181], v[24:27], v[152:155], 0
	s_nop 1
	v_max_f32_e32 v169, v170, v170
	v_max_f32_e32 v170, 0, v171
	v_max_f32_e32 v169, 0, v169
	v_mul_f32_e32 v177, v37, v170
	v_fmac_f32_e32 v177, v36, v169
	v_max_f32_e32 v169, 0, v172
	v_fmac_f32_e32 v177, v38, v169
	v_max_f32_e32 v169, v173, v173
	v_mfma_f32_16x16x32_bf16 v[170:173], v[28:31], v[156:159], v[178:181]
	v_max_f32_e32 v169, 0, v169
	v_fmac_f32_e32 v177, v39, v169
; #define LOADG(S, GRP) do { const u16* _k = kb + (size_t)(GRP) * 4096; \
;       _Pragma("unroll") for (int _i = 0; _i < 4; ++_i) { kf[S][2 * _i] = *(const bf16x8*)(_k + _i * 1024); kf[S][2 * _i + 1] = *(const bf16x8*)(_k + _i * 1024 + 32); } } while (0)
; DEVINL void phase_topk(const Params& p, int layer, char* smem, int wv, int rep) {
;     ...
;     {
;       int g = wid;
;       if (g < ng) LOADG(0, g);
;       for (; g < ng; g += 16) {
;         if (g + 8 < ng) LOADG(1, g + 8);
;         COMPUTEG(0, g);
;         if (g + 8 < ng) {
;           if (g + 16 < ng) LOADG(0, g + 16);
;           COMPUTEG(1, g + 8);
;         }
;       }
;     }
	v_mfma_f32_16x16x32_bf16 v[178:181], v[40:43], v[132:135], 0
	s_nop 4
	v_max_f32_e32 v169, v170, v170
	v_max_f32_e32 v170, 0, v171
	v_max_f32_e32 v169, 0, v169
	v_mul_f32_e32 v170, v37, v170
	v_fmac_f32_e32 v170, v36, v169
	v_max_f32_e32 v169, 0, v172
	v_fmac_f32_e32 v170, v38, v169
	v_max_f32_e32 v169, 0, v173
	v_fmac_f32_e32 v170, v39, v169
	s_nop 1
	v_permlane16_swap_b32_e32 v177, v170
	v_add_f32_e32 v169, v174, v175
	v_add_f32_e32 v174, v177, v170
	v_mfma_f32_16x16x32_bf16 v[170:173], v[40:43], v[124:127], 0
	s_nop 0
	v_permlane32_swap_b32_e32 v169, v174
	v_add_f32_e32 v169, v169, v174
	v_mfma_f32_16x16x32_bf16 v[170:173], v[32:35], v[128:131], v[170:173]
	v_add_u32_e32 v174, 0xffff8000, v165
	ds_write_b32 v174, v169
	s_nop 5
	v_max_f32_e32 v169, v170, v170
	v_max_f32_e32 v170, 0, v171
	v_max_f32_e32 v169, 0, v169
	v_mul_f32_e32 v174, v45, v170
	v_fmac_f32_e32 v174, v44, v169
	v_max_f32_e32 v169, 0, v172
	v_fmac_f32_e32 v174, v46, v169
	v_max_f32_e32 v169, v173, v173
	v_mfma_f32_16x16x32_bf16 v[170:173], v[32:35], v[136:139], v[178:181]
	v_max_f32_e32 v169, 0, v169
	v_fmac_f32_e32 v174, v47, v169
	v_mfma_f32_16x16x32_bf16 v[178:181], v[40:43], v[144:147], 0
	s_nop 4
	v_max_f32_e32 v169, v170, v170
	v_max_f32_e32 v170, 0, v171
	v_max_f32_e32 v169, 0, v169
	v_mul_f32_e32 v175, v45, v170
	v_fmac_f32_e32 v175, v44, v169
	v_max_f32_e32 v169, 0, v172
	v_fmac_f32_e32 v175, v46, v169
	v_max_f32_e32 v169, v173, v173
	v_mfma_f32_16x16x32_bf16 v[170:173], v[32:35], v[148:151], v[178:181]
	v_max_f32_e32 v169, 0, v169
	v_fmac_f32_e32 v175, v47, v169
	s_nop 1
	v_permlane16_swap_b32_e32 v174, v175
	v_mfma_f32_16x16x32_bf16 v[178:181], v[40:43], v[152:155], 0
	s_nop 1
	v_max_f32_e32 v169, v170, v170
	v_max_f32_e32 v170, 0, v171
	v_max_f32_e32 v169, 0, v169
	v_mul_f32_e32 v177, v45, v170
	v_fmac_f32_e32 v177, v44, v169
	v_max_f32_e32 v169, 0, v172
	v_fmac_f32_e32 v177, v46, v169
	v_max_f32_e32 v169, v173, v173
	v_mfma_f32_16x16x32_bf16 v[170:173], v[32:35], v[156:159], v[178:181]
	v_max_f32_e32 v169, 0, v169
	v_fmac_f32_e32 v177, v47, v169
	v_mfma_f32_16x16x32_bf16 v[178:181], v[52:55], v[132:135], 0
	s_nop 4
	v_max_f32_e32 v169, v170, v170
	v_max_f32_e32 v170, 0, v171
	v_max_f32_e32 v169, 0, v169
	v_mul_f32_e32 v170, v45, v170
	v_fmac_f32_e32 v170, v44, v169
	v_max_f32_e32 v169, 0, v172
	v_fmac_f32_e32 v170, v46, v169
	v_max_f32_e32 v169, 0, v173
	v_fmac_f32_e32 v170, v47, v169
	s_nop 1
	v_permlane16_swap_b32_e32 v177, v170
	v_add_f32_e32 v169, v174, v175
	v_add_f32_e32 v174, v177, v170
	v_mfma_f32_16x16x32_bf16 v[170:173], v[52:55], v[124:127], 0
	s_nop 0
	v_permlane32_swap_b32_e32 v169, v174
	v_add_f32_e32 v169, v169, v174
	v_mfma_f32_16x16x32_bf16 v[170:173], v[48:51], v[128:131], v[170:173]
	v_add_u32_e32 v174, 0xffffc000, v165
	ds_write_b32 v174, v169
	s_nop 5
	v_max_f32_e32 v169, v170, v170
	v_max_f32_e32 v170, 0, v171
	v_max_f32_e32 v169, 0, v169
	v_mul_f32_e32 v174, v57, v170
	v_fmac_f32_e32 v174, v56, v169
	v_max_f32_e32 v169, 0, v172
	v_fmac_f32_e32 v174, v58, v169
	v_max_f32_e32 v169, v173, v173
	v_mfma_f32_16x16x32_bf16 v[170:173], v[48:51], v[136:139], v[178:181]
	v_max_f32_e32 v169, 0, v169
	v_fmac_f32_e32 v174, v59, v169
	v_mfma_f32_16x16x32_bf16 v[178:181], v[52:55], v[144:147], 0
	s_nop 4
	v_max_f32_e32 v169, v170, v170
	v_max_f32_e32 v170, 0, v171
	v_max_f32_e32 v169, 0, v169
	v_mul_f32_e32 v175, v57, v170
	v_fmac_f32_e32 v175, v56, v169
	v_max_f32_e32 v169, 0, v172
	v_fmac_f32_e32 v175, v58, v169
	v_max_f32_e32 v169, v173, v173
	v_mfma_f32_16x16x32_bf16 v[170:173], v[48:51], v[148:151], v[178:181]
	v_max_f32_e32 v169, 0, v169
	v_fmac_f32_e32 v175, v59, v169
	s_nop 1
	v_permlane16_swap_b32_e32 v174, v175
	v_mfma_f32_16x16x32_bf16 v[178:181], v[52:55], v[152:155], 0
	s_nop 1
	v_max_f32_e32 v169, v170, v170
	v_max_f32_e32 v170, 0, v171
	v_max_f32_e32 v169, 0, v169
	v_mul_f32_e32 v177, v57, v170
	v_fmac_f32_e32 v177, v56, v169
	v_max_f32_e32 v169, 0, v172
	v_fmac_f32_e32 v177, v58, v169
	v_max_f32_e32 v169, v173, v173
	v_mfma_f32_16x16x32_bf16 v[170:173], v[48:51], v[156:159], v[178:181]
	v_max_f32_e32 v169, 0, v169
	v_fmac_f32_e32 v177, v59, v169
	v_mfma_f32_16x16x32_bf16 v[178:181], v[60:63], v[132:135], 0
	s_nop 4
	v_max_f32_e32 v169, v170, v170
	v_max_f32_e32 v170, 0, v171
	v_max_f32_e32 v169, 0, v169
	v_mul_f32_e32 v170, v57, v170
	v_fmac_f32_e32 v170, v56, v169
	v_max_f32_e32 v169, 0, v172
	v_fmac_f32_e32 v170, v58, v169
	v_max_f32_e32 v169, 0, v173
	v_fmac_f32_e32 v170, v59, v169
	s_nop 1
	v_permlane16_swap_b32_e32 v177, v170
	v_add_f32_e32 v169, v174, v175
	v_add_f32_e32 v174, v177, v170
	v_mfma_f32_16x16x32_bf16 v[170:173], v[60:63], v[124:127], 0
	s_nop 0
	v_permlane32_swap_b32_e32 v169, v174
	v_add_f32_e32 v169, v169, v174
	v_mfma_f32_16x16x32_bf16 v[170:173], v[64:67], v[128:131], v[170:173]
	s_nop 7
	v_max_f32_e32 v171, 0, v171
	v_max_f32_e32 v170, 0, v170
	v_mul_f32_e32 v174, v69, v171
	v_fmac_f32_e32 v174, v68, v170
	v_max_f32_e32 v170, 0, v172
	v_fmac_f32_e32 v174, v70, v170
	v_max_f32_e32 v170, 0, v173
	v_fmac_f32_e32 v174, v71, v170
	v_mfma_f32_16x16x32_bf16 v[170:173], v[64:67], v[136:139], v[178:181]
	v_mfma_f32_16x16x32_bf16 v[178:181], v[60:63], v[144:147], 0
	s_nop 6
	v_max_f32_e32 v171, 0, v171
	v_max_f32_e32 v170, 0, v170
	v_mul_f32_e32 v175, v69, v171
	v_fmac_f32_e32 v175, v68, v170
	v_max_f32_e32 v170, 0, v172
	v_fmac_f32_e32 v175, v70, v170
	v_max_f32_e32 v170, 0, v173
	v_fmac_f32_e32 v175, v71, v170
	v_mfma_f32_16x16x32_bf16 v[170:173], v[64:67], v[148:151], v[178:181]
; #define LOADG(S, GRP) do { const u16* _k = kb + (size_t)(GRP) * 4096; \
;       _Pragma("unroll") for (int _i = 0; _i < 4; ++_i) { kf[S][2 * _i] = *(const bf16x8*)(_k + _i * 1024); kf[S][2 * _i + 1] = *(const bf16x8*)(_k + _i * 1024 + 32); } } while (0)
; DEVINL void phase_topk(const Params& p, int layer, char* smem, int wv, int rep) {
;     ...
;     {
;       int g = wid;
;       if (g < ng) LOADG(0, g);
;       for (; g < ng; g += 16) {
;         if (g + 8 < ng) LOADG(1, g + 8);
;         COMPUTEG(0, g);
;         if (g + 8 < ng) {
;           if (g + 16 < ng) LOADG(0, g + 16);
;           COMPUTEG(1, g + 8);
;         }
;       }
;     }
	s_nop 0
	v_permlane16_swap_b32_e32 v174, v175
	v_add_f32_e32 v174, v174, v175
	v_mfma_f32_16x16x32_bf16 v[178:181], v[60:63], v[152:155], 0
	s_nop 3
	v_max_f32_e32 v171, 0, v171
	v_max_f32_e32 v170, 0, v170
	v_mul_f32_e32 v177, v69, v171
	v_fmac_f32_e32 v177, v68, v170
	v_max_f32_e32 v170, 0, v172
	v_fmac_f32_e32 v177, v70, v170
	v_max_f32_e32 v170, 0, v173
	v_fmac_f32_e32 v177, v71, v170
	v_mfma_f32_16x16x32_bf16 v[170:173], v[64:67], v[156:159], v[178:181]
	v_mfma_f32_16x16x32_bf16 v[178:181], v[72:75], v[132:135], 0
	s_nop 6
	v_max_f32_e32 v171, 0, v171
	v_max_f32_e32 v170, 0, v170
	v_mul_f32_e32 v171, v69, v171
	v_fmac_f32_e32 v171, v68, v170
	v_max_f32_e32 v170, 0, v172
	v_fmac_f32_e32 v171, v70, v170
	v_max_f32_e32 v170, 0, v173
	v_fmac_f32_e32 v171, v71, v170
	s_nop 1
	v_permlane16_swap_b32_e32 v177, v171
	v_add_f32_e32 v175, v177, v171
	v_mfma_f32_16x16x32_bf16 v[170:173], v[72:75], v[124:127], 0
	s_nop 0
	v_permlane32_swap_b32_e32 v174, v175
	v_add_f32_e32 v174, v174, v175
	v_mfma_f32_16x16x32_bf16 v[170:173], v[76:79], v[128:131], v[170:173]
	ds_write2st64_b32 v165, v169, v174 offset1:64
	s_nop 6
	v_max_f32_e32 v169, v170, v170
	v_max_f32_e32 v170, 0, v171
	v_max_f32_e32 v169, 0, v169
	v_mul_f32_e32 v174, v81, v170
	v_fmac_f32_e32 v174, v80, v169
	v_max_f32_e32 v169, 0, v172
	v_fmac_f32_e32 v174, v82, v169
	v_max_f32_e32 v169, v173, v173
	v_mfma_f32_16x16x32_bf16 v[170:173], v[76:79], v[136:139], v[178:181]
	v_max_f32_e32 v169, 0, v169
	v_fmac_f32_e32 v174, v83, v169
	v_mfma_f32_16x16x32_bf16 v[178:181], v[72:75], v[144:147], 0
	s_nop 4
	v_max_f32_e32 v169, v170, v170
	v_max_f32_e32 v170, 0, v171
	v_max_f32_e32 v169, 0, v169
	v_mul_f32_e32 v175, v81, v170
	v_fmac_f32_e32 v175, v80, v169
	v_max_f32_e32 v169, 0, v172
	v_fmac_f32_e32 v175, v82, v169
	v_max_f32_e32 v169, v173, v173
	v_mfma_f32_16x16x32_bf16 v[170:173], v[76:79], v[148:151], v[178:181]
	v_max_f32_e32 v169, 0, v169
	v_fmac_f32_e32 v175, v83, v169
	s_nop 1
	v_permlane16_swap_b32_e32 v174, v175
	v_mfma_f32_16x16x32_bf16 v[178:181], v[72:75], v[152:155], 0
	s_nop 1
	v_max_f32_e32 v169, v170, v170
	v_max_f32_e32 v170, 0, v171
	v_max_f32_e32 v169, 0, v169
	v_mul_f32_e32 v177, v81, v170
	v_fmac_f32_e32 v177, v80, v169
	v_max_f32_e32 v169, 0, v172
	v_fmac_f32_e32 v177, v82, v169
	v_max_f32_e32 v169, v173, v173
	v_mfma_f32_16x16x32_bf16 v[170:173], v[76:79], v[156:159], v[178:181]
	v_max_f32_e32 v169, 0, v169
	v_fmac_f32_e32 v177, v83, v169
	v_mfma_f32_16x16x32_bf16 v[178:181], v[100:103], v[132:135], 0
	s_nop 4
	v_max_f32_e32 v169, v170, v170
	v_max_f32_e32 v170, 0, v171
	v_max_f32_e32 v169, 0, v169
	v_mul_f32_e32 v170, v81, v170
	v_fmac_f32_e32 v170, v80, v169
	v_max_f32_e32 v169, 0, v172
	v_fmac_f32_e32 v170, v82, v169
	v_max_f32_e32 v169, 0, v173
	v_fmac_f32_e32 v170, v83, v169
	s_nop 1
	v_permlane16_swap_b32_e32 v177, v170
	v_add_f32_e32 v169, v174, v175
	v_add_f32_e32 v174, v177, v170
	v_mfma_f32_16x16x32_bf16 v[170:173], v[100:103], v[124:127], 0
	s_nop 0
	v_permlane32_swap_b32_e32 v169, v174
	v_add_f32_e32 v169, v169, v174
	v_mfma_f32_16x16x32_bf16 v[170:173], v[104:107], v[128:131], v[170:173]
	s_nop 7
	v_max_f32_e32 v171, 0, v171
	v_max_f32_e32 v170, 0, v170
	v_mul_f32_e32 v174, v141, v171
	v_fmac_f32_e32 v174, v140, v170
	v_max_f32_e32 v170, 0, v172
	v_fmac_f32_e32 v174, v142, v170
	v_max_f32_e32 v170, 0, v173
	v_fmac_f32_e32 v174, v143, v170
	v_mfma_f32_16x16x32_bf16 v[170:173], v[104:107], v[136:139], v[178:181]
	v_mfma_f32_16x16x32_bf16 v[178:181], v[100:103], v[144:147], 0
	s_nop 6
	v_max_f32_e32 v171, 0, v171
	v_max_f32_e32 v170, 0, v170
	v_mul_f32_e32 v175, v141, v171
	v_fmac_f32_e32 v175, v140, v170
	v_max_f32_e32 v170, 0, v172
	v_fmac_f32_e32 v175, v142, v170
	v_max_f32_e32 v170, 0, v173
	v_fmac_f32_e32 v175, v143, v170
	v_mfma_f32_16x16x32_bf16 v[170:173], v[104:107], v[148:151], v[178:181]
	s_nop 0
	v_permlane16_swap_b32_e32 v174, v175
	v_mfma_f32_16x16x32_bf16 v[178:181], v[100:103], v[152:155], 0
	s_nop 4
	v_max_f32_e32 v171, 0, v171
	v_max_f32_e32 v170, 0, v170
	v_mul_f32_e32 v177, v141, v171
	v_fmac_f32_e32 v177, v140, v170
	v_max_f32_e32 v170, 0, v172
	v_fmac_f32_e32 v177, v142, v170
	v_max_f32_e32 v170, 0, v173
	v_fmac_f32_e32 v177, v143, v170
	v_mfma_f32_16x16x32_bf16 v[170:173], v[104:107], v[156:159], v[178:181]
	s_nop 7
	v_max_f32_e32 v171, 0, v171
	v_max_f32_e32 v170, 0, v170
	v_mul_f32_e32 v171, v141, v171
	v_fmac_f32_e32 v171, v140, v170
	v_max_f32_e32 v170, 0, v172
	v_fmac_f32_e32 v171, v142, v170
	v_max_f32_e32 v170, 0, v173
	v_fmac_f32_e32 v171, v143, v170
	s_nop 1
	v_permlane16_swap_b32_e32 v177, v171
	v_add_f32_e32 v170, v174, v175
	v_add_f32_e32 v171, v177, v171
	s_nop 1
	v_permlane32_swap_b32_e32 v170, v171
	v_add_f32_e32 v170, v170, v171
	ds_write2st64_b32 v165, v169, v170 offset0:128 offset1:192
	s_cbranch_vccnz .LBB0_475
	s_cmp_gt_i32 s3, s4
	s_cbranch_scc1 .LBB0_474
	v_add_co_u32_e32 v132, vcc, 0xfffff000, v166
	s_nop 1
	v_addc_co_u32_e32 v133, vcc, -1, v167, vcc
	global_load_dwordx4 v[124:127], v[132:133], off offset:-2112
	global_load_dwordx4 v[128:131], v[132:133], off offset:-2048
	s_nop 0
	global_load_dwordx4 v[132:135], v[132:133], off offset:-64
	s_nop 0
	global_load_dwordx4 v[136:139], v[166:167], off offset:-4096
	global_load_dwordx4 v[144:147], v[166:167], off offset:-2112
	global_load_dwordx4 v[148:151], v[166:167], off offset:-2048
	global_load_dwordx4 v[152:155], v[166:167], off offset:-64
	global_load_dwordx4 v[156:159], v[166:167], off
	s_branch .LBB0_474

; DEVINL int opaque_tid(int wv) { int t = (wv << 6) | (int)__builtin_amdgcn_mbcnt_hi(~0u, __builtin_amdgcn_mbcnt_lo(~0u, 0u)); asm volatile("" : "+v"(t)); return t; }
; #define LDK(DST, KQ) _Pragma("unroll") for (int kc = 0; kc < 4; ++kc) DST[kc] = *(const bf16x8*)(Ks + ((KQ) * 16 + fr) * 136 + kc * 32 + fq * 8)
; DEVINL void attn_item(const Params& p, int item, char* smem, int wv) {
;     ...
;   const int tid = opaque_tid(wv), lane = tid & 63, wid = __builtin_amdgcn_readfirstlane(tid >> 6), fr = lane & 15, fq = lane >> 4;
;   const int qblk = 31 - (item >> 4), b = (item >> 2) & 3, kvh = item & 3;
;   const int q0 = qblk * 128, ntile = 2 * qblk + 2;
;   const int qlast = q0 + wid * 16 + 15;
;   u16* Ks = (u16*)smem;
;   u16* Vs = Ks + 64 * 136;
;   const size_t qtok = (size_t)b * SEQ + q0 + wid * 16 + fr;
;   bf16x8 qf[2][4];
; #pragma unroll
;   for (int hh = 0; hh < 2; ++hh)
; #pragma unroll
;     for (int kc = 0; kc < 4; ++kc)
;       qf[hh][kc] = *(const bf16x8*)(hb + qtok * HS + 2560 + (kvh * 2 + hh) * 128 + kc * 32 + fq * 8);
;   f32x4 o[2][8];
; #pragma unroll
;   for (int hh = 0; hh < 2; ++hh)
; #pragma unroll
;     for (int dt = 0; dt < 8; ++dt) o[hh][dt] = f32x4{0.f, 0.f, 0.f, 0.f};
;   float mrun[2] = {0.f, 0.f}, lsum[2] = {0.f, 0.f};
;   unsigned long long mw_next = bits[qtok * 64];
;   u32x4 rk[2], rv[2];
;   const u16* kg = hb + ((size_t)b * SEQ + (tid >> 4)) * HS + 3584 + kvh * 128 + (tid & 15) * 8;
;   const u16* vg = vT + ((size_t)(b * 4 + kvh) * 128 + (tid >> 3)) * SEQ + (tid & 7) * 8;
; #pragma unroll
;   for (int i = 0; i < 2; ++i) {
;     rk[i] = *(const u32x4*)(kg + (size_t)(32 * i) * HS);
;     rv[i] = *(const u32x4*)(vg + (size_t)(64 * i) * SEQ);
;   }
;   for (int kt = 0; kt < ntile; ++kt) {
; #pragma unroll
;     for (int i = 0; i < 2; ++i) {
;       *(u32x4*)(Ks + ((tid >> 4) + 32 * i) * 136 + (tid & 15) * 8) = rk[i];
;       *(u32x4*)(Vs + ((tid >> 3) + 64 * i) * 72 + (tid & 7) * 8) = rv[i];
;     }
;     __syncthreads();
;     ...
;     LDK(kfa, 0);
;     LDK(kfb, 1); MMS(kfa, 0);
;     LDK(kfa, 2); MMS(kfb, 1);
;     LDK(kfb, 3); MMS(kfa, 2);
;     LDV(vfa, 0); MMS(kfb, 3);
.Lprio_skip_a0:
	s_and_b32 s33, s1, 0x3000
	v_and_b32_e32 v60, 15, v120
	s_and_b32 s0, s31, -16
	s_add_i32 s8, s7, s33
	s_ashr_i32 s1, s0, 31
	v_or_b32_e32 v0, s8, v60
	s_waitcnt vmcnt(1)
	v_lshl_add_u64 v[156:157], v[0:1], 0, s[0:1]
	v_mov_b64_e32 v[2:3], s[62:63]
	v_mad_u64_u32 v[4:5], s[0:1], v156, s19, v[2:3]
	s_and_b32 s6, s5, 3
	v_mad_i32_i24 v5, v157, s19, v5
	v_and_b32_e32 v0, 48, v120
	v_lshl_add_u64 v[4:5], v[4:5], 0, v[0:1]
	s_lshl_b32 s8, s6, 9
	v_ashrrev_i32_e32 v14, 4, v120
	v_lshl_add_u64 v[8:9], v[4:5], 0, s[8:9]
	v_add_u32_e32 v4, s33, v14
	s_lshl_b32 s16, s6, 8
	s_mov_b32 s17, s9
	v_mad_i64_i32 v[2:3], s[0:1], v4, s19, v[2:3]
	v_lshlrev_b32_e32 v6, 4, v120
	v_lshl_add_u64 v[2:3], v[2:3], 0, s[16:17]
	v_and_b32_e32 v10, 0xf0, v6
	v_mov_b32_e32 v11, v1
	v_lshl_add_u64 v[116:117], v[2:3], 0, v[10:11]
	s_lshl_b32 s0, s5, 7
	v_ashrrev_i32_e32 v2, 3, v120
	s_and_b32 s8, s0, 0x780
	v_ashrrev_i32_e32 v3, 31, v2
	v_lshl_add_u64 v[4:5], v[2:3], 0, s[8:9]
	v_lshlrev_b64 v[4:5], 13, v[4:5]
	v_lshl_add_u64 v[4:5], s[82:83], 0, v[4:5]
	v_and_b32_e32 v12, 0x70, v6
	v_mov_b32_e32 v13, v1
	v_lshl_add_u64 v[158:159], v[4:5], 0, v[12:13]
	v_add_co_u32_e32 v4, vcc, s20, v116
	global_load_dwordx4 v[36:39], v[158:159], off
	s_nop 0
	v_addc_co_u32_e32 v5, vcc, 0, v117, vcc
	v_add_co_u32_e32 v6, vcc, s21, v116
	v_mul_lo_u32 v2, v2, s24
	s_nop 0
	v_addc_co_u32_e32 v7, vcc, 0, v117, vcc
	global_load_dwordx4 v[40:43], v[4:5], off offset:3072
	global_load_dwordx4 v[44:47], v[6:7], off offset:3072
	v_add_co_u32_e32 v52, vcc, s22, v158
	v_add_u32_e32 v11, 0, v12
	s_nop 0
	v_addc_co_u32_e32 v53, vcc, 0, v159, vcc
	global_load_dwordx4 v[48:51], v[52:53], off
	v_mul_lo_u32 v3, v14, s23
	v_add_u32_e32 v10, 0, v10
	v_and_b32_e32 v173, 64, v12
	v_bfe_u32 v11, v12, 4, 1
	v_lshl_or_b32 v173, v11, 5, v173
	v_bfe_u32 v11, v12, 5, 1
	v_lshl_or_b32 v173, v11, 3, v173
	v_add_u32_e32 v173, v173, v2
	v_add_co_u32_e64 v2, s[0:1], s20, v8
	v_lshl_add_u64 v[28:29], v[8:9], 0, s[10:11]
	v_add_u32_e32 v172, v10, v3
	v_lshlrev_b64 v[118:119], 9, v[156:157]
	v_add_co_u32_e32 v54, vcc, 0xa1000, v116
	v_addc_co_u32_e64 v3, s[0:1], 0, v9, s[0:1]
	global_load_dwordx4 v[4:7], v[28:29], off offset:64
	v_lshl_add_u64 v[56:57], s[80:81], 0, v[118:119]
	v_addc_co_u32_e32 v55, vcc, 0, v117, vcc
	global_load_dwordx4 v[8:11], v[28:29], off offset:128
	global_load_dwordx4 v[12:15], v[28:29], off offset:192
	global_load_dwordx4 v[16:19], v[28:29], off offset:256
	global_load_dwordx4 v[20:23], v[28:29], off offset:320
	global_load_dwordx4 v[24:27], v[28:29], off offset:384
	s_nop 0
	global_load_dwordx4 v[28:31], v[28:29], off offset:448
	s_nop 0
	global_load_dwordx4 v[32:35], v[2:3], off offset:1024
	s_nop 0
	global_load_dwordx2 v[2:3], v[56:57], off
	v_add_co_u32_e32 v58, vcc, 0xf1000, v116
	s_add_i32 s8, s31, s7
	s_nop 0
	v_addc_co_u32_e32 v59, vcc, 0, v117, vcc
	s_cmp_gt_i32 s8, -1
	s_mov_b64 s[0:1], -1
	s_waitcnt vmcnt(11)
	ds_write_b128 v172, v[40:43]
	ds_write_b64 v173, v[36:37] offset:17408
	ds_write_b64 v173, v[38:39] offset:17424
	s_waitcnt vmcnt(10)
	ds_write_b128 v172, v[44:47] offset:8704
	s_waitcnt vmcnt(9)
	ds_write_b64 v173, v[48:49] offset:26624
	ds_write_b64 v173, v[50:51] offset:26640
	s_waitcnt lgkmcnt(0)
	s_barrier
	global_load_dwordx4 v[44:47], v[58:59], off offset:3072
	global_load_dwordx4 v[36:39], v[54:55], off offset:3072
	global_load_dwordx4 v[48:51], v[52:53], off offset:128
	global_load_dwordx4 v[40:43], v[158:159], off offset:128
	global_load_dwordx2 v[162:163], v[56:57], off offset:8
	v_mad_u32_u24 v52, v60, s23, 0
	v_lshlrev_b32_e32 v53, 7, v60
	v_lshrrev_b32_e32 v54, 2, v120
	v_sub_u32_e32 v53, v52, v53
	v_and_b32_e32 v174, 12, v54
	v_add_u32_e32 v175, v52, v0
	v_lshl_add_u32 v177, v174, 2, v53
	s_cbranch_scc0 .LBB0_704
	ds_read_b128 v[52:55], v175
	ds_read_b128 v[56:59], v175 offset:64
	ds_read_b128 v[60:63], v175 offset:128
	ds_read_b128 v[64:67], v175 offset:192
	ds_read_b128 v[68:71], v175 offset:4352
	ds_read_b128 v[72:75], v175 offset:4416
	ds_read_b128 v[76:79], v175 offset:4480
	ds_read_b128 v[80:83], v175 offset:4544
	s_mov_b32 s6, s4
	s_mov_b32 s7, s4
	s_mov_b32 s5, s4
	v_mov_b64_e32 v[86:87], s[6:7]
	v_mov_b64_e32 v[84:85], s[4:5]
	s_waitcnt vmcnt(6) lgkmcnt(7)
	s_nop 0
	v_mfma_f32_16x16x32_bf16 v[88:91], v[52:55], v[32:35], v[84:87]
	v_mfma_f32_16x16x32_bf16 v[52:55], v[52:55], v[16:19], v[84:87]
	s_waitcnt lgkmcnt(6)
	v_mfma_f32_16x16x32_bf16 v[88:91], v[56:59], v[4:7], v[88:91]
	v_mfma_f32_16x16x32_bf16 v[52:55], v[56:59], v[20:23], v[52:55]
	s_waitcnt lgkmcnt(5)
	v_mfma_f32_16x16x32_bf16 v[56:59], v[60:63], v[8:11], v[88:91]
	v_mfma_f32_16x16x32_bf16 v[52:55], v[60:63], v[24:27], v[52:55]
	s_waitcnt lgkmcnt(4)
	v_mfma_f32_16x16x32_bf16 v[60:63], v[64:67], v[12:15], v[56:59]
	v_mfma_f32_16x16x32_bf16 v[64:67], v[64:67], v[28:31], v[52:55]
	s_nop 3
	ds_read_b128 v[52:55], v175 offset:8704
	ds_read_b128 v[56:59], v175 offset:8768
	ds_read_b128 v[88:91], v175 offset:8832
	ds_read_b128 v[92:95], v175 offset:8896
	s_waitcnt lgkmcnt(7)
	v_mfma_f32_16x16x32_bf16 v[96:99], v[68:71], v[32:35], v[84:87]
	v_mfma_f32_16x16x32_bf16 v[68:71], v[68:71], v[16:19], v[84:87]
	s_waitcnt lgkmcnt(6)
	v_mfma_f32_16x16x32_bf16 v[96:99], v[72:75], v[4:7], v[96:99]
	v_mfma_f32_16x16x32_bf16 v[68:71], v[72:75], v[20:23], v[68:71]
	s_waitcnt lgkmcnt(5)
	v_mfma_f32_16x16x32_bf16 v[72:75], v[76:79], v[8:11], v[96:99]
	v_mfma_f32_16x16x32_bf16 v[68:71], v[76:79], v[24:27], v[68:71]
	s_waitcnt lgkmcnt(4)
	v_mfma_f32_16x16x32_bf16 v[72:75], v[80:83], v[12:15], v[72:75]
	v_mfma_f32_16x16x32_bf16 v[68:71], v[80:83], v[28:31], v[68:71]
	ds_read_b128 v[76:79], v175 offset:13056
	ds_read_b128 v[80:83], v175 offset:13120
	ds_read_b128 v[96:99], v175 offset:13184
	ds_read_b128 v[100:103], v175 offset:13248
	s_waitcnt lgkmcnt(7)
; DEVINL void attn_item(const Params& p, int item, char* smem, int wv) {
;     ...
;     LDV(vfa, 0); MMS(kfb, 3);
;     bf16x8 pf[2][2];
;     {
;       const unsigned long long msh = mw >> (fq * 4);
;       const int mlo = (int)(unsigned)msh, mhi = (int)(unsigned)(msh >> 32);
;       int mk[4][4];
; #pragma unroll
;       for (int j = 0; j < 4; ++j) {
;         mk[0][j] = __builtin_amdgcn_sbfe(mlo, j, 1); mk[1][j] = __builtin_amdgcn_sbfe(mlo, 16 + j, 1);
;         mk[2][j] = __builtin_amdgcn_sbfe(mhi, j, 1); mk[3][j] = __builtin_amdgcn_sbfe(mhi, 16 + j, 1);
;       }
; #pragma unroll
;       for (int hh = 0; hh < 2; ++hh) {
;         float mx = s[hh][0][0];
; #pragma unroll
;         for (int kq = 0; kq < 4; ++kq)
; #pragma unroll
;           for (int j = 0; j < 4; ++j) mx = fmaxf(mx, s[hh][kq][j]);
;         {
;           auto r1 = __builtin_amdgcn_permlane16_swap(__float_as_uint(mx), __float_as_uint(mx), false, false);
;           mx = fmaxf(__uint_as_float(r1[0]), __uint_as_float(r1[1]));
;           auto r2 = __builtin_amdgcn_permlane32_swap(__float_as_uint(mx), __float_as_uint(mx), false, false);
;           mx = fmaxf(__uint_as_float(r2[0]), __uint_as_float(r2[1]));
;         }
;         if (kt == 0 || __ballot(mx > 8.f)) {
;           const float delta = (kt == 0) ? mx : fmaxf(mx, 0.f);
;           const float alpha = fexp2(-delta);
;           mrun[hh] += delta;
;           lsum[hh] *= alpha;
; #pragma unroll
;           for (int dt = 0; dt < 8; ++dt) o[hh][dt] *= alpha;
; #pragma unroll
;           for (int kq = 0; kq < 4; ++kq)
; #pragma unroll
;             for (int j = 0; j < 4; ++j) s[hh][kq][j] -= delta;
;         }
;         float ps = 0.f;
;         float pv[4][4];
; #pragma unroll
;         for (int kq = 0; kq < 4; ++kq)
; #pragma unroll
;           for (int j = 0; j < 4; ++j) {
;             pv[kq][j] = __uint_as_float(__float_as_uint(fexp2(s[hh][kq][j])) & (unsigned)mk[kq][j]);
;             ps += pv[kq][j];
;           }
; #pragma unroll
;         for (int c2 = 0; c2 < 2; ++c2) {
;           u32x4 pw;
;           pw[0] = pk2(pv[2 * c2][0], pv[2 * c2][1]); pw[1] = pk2(pv[2 * c2][2], pv[2 * c2][3]);
;           pw[2] = pk2(pv[2 * c2 + 1][0], pv[2 * c2 + 1][1]); pw[3] = pk2(pv[2 * c2 + 1][2], pv[2 * c2 + 1][3]);
;           pf[hh][c2] = *(bf16x8*)&pw;
;         }
;         lsum[hh] += ps;
	v_mfma_f32_16x16x32_bf16 v[104:107], v[52:55], v[32:35], v[84:87]
	v_mfma_f32_16x16x32_bf16 v[52:55], v[52:55], v[16:19], v[84:87]
	s_waitcnt lgkmcnt(6)
	v_mfma_f32_16x16x32_bf16 v[104:107], v[56:59], v[4:7], v[104:107]
	v_mfma_f32_16x16x32_bf16 v[52:55], v[56:59], v[20:23], v[52:55]
	s_waitcnt lgkmcnt(5)
	v_mfma_f32_16x16x32_bf16 v[56:59], v[88:91], v[8:11], v[104:107]
	v_mfma_f32_16x16x32_bf16 v[52:55], v[88:91], v[24:27], v[52:55]
	s_waitcnt lgkmcnt(4)
	v_mfma_f32_16x16x32_bf16 v[88:91], v[92:95], v[12:15], v[56:59]
	v_mfma_f32_16x16x32_bf16 v[92:95], v[92:95], v[28:31], v[52:55]
	s_nop 0
	s_nop 2
	ds_read_b128 v[52:55], v177 offset:17408
	ds_read_b128 v[56:59], v177 offset:17472
	s_waitcnt lgkmcnt(5)
	v_mfma_f32_16x16x32_bf16 v[104:107], v[76:79], v[32:35], v[84:87]
	v_mfma_f32_16x16x32_bf16 v[76:79], v[76:79], v[16:19], v[84:87]
	s_waitcnt lgkmcnt(4)
	v_mfma_f32_16x16x32_bf16 v[84:87], v[80:83], v[4:7], v[104:107]
	v_mfma_f32_16x16x32_bf16 v[76:79], v[80:83], v[20:23], v[76:79]
	s_waitcnt lgkmcnt(3)
	v_mfma_f32_16x16x32_bf16 v[80:83], v[96:99], v[8:11], v[84:87]
	v_mfma_f32_16x16x32_bf16 v[76:79], v[96:99], v[24:27], v[76:79]
	s_waitcnt lgkmcnt(2)
	v_mfma_f32_16x16x32_bf16 v[80:83], v[100:103], v[12:15], v[80:83]
	v_mfma_f32_16x16x32_bf16 v[76:79], v[100:103], v[28:31], v[76:79]
	s_waitcnt vmcnt(5)
	v_lshrrev_b64 v[2:3], v174, v[2:3]
	v_bfe_i32 v0, v2, 0, 1
	v_bfe_i32 v86, v2, 16, 1
	v_bfe_i32 v87, v3, 0, 1
	v_bfe_i32 v96, v3, 16, 1
	v_bfe_i32 v97, v2, 1, 1
	v_bfe_i32 v98, v2, 17, 1
	v_bfe_i32 v99, v3, 1, 1
	v_bfe_i32 v104, v3, 17, 1
	v_bfe_i32 v100, v2, 2, 1
	v_bfe_i32 v101, v2, 18, 1
	v_bfe_i32 v105, v3, 2, 1
	v_bfe_i32 v106, v3, 18, 1
	v_bfe_i32 v102, v2, 3, 1
	v_bfe_i32 v103, v2, 19, 1
	v_bfe_i32 v107, v3, 3, 1
	v_bfe_i32 v108, v3, 19, 1
	v_max_f32_e32 v3, v60, v60
	v_max_f32_e32 v2, v3, v61
	v_max3_f32 v2, v2, v62, v63
	v_max3_f32 v2, v2, v72, v73
	v_max3_f32 v2, v2, v74, v75
	v_max3_f32 v2, v2, v88, v89
	v_max3_f32 v2, v2, v90, v91
	v_max3_f32 v2, v2, v80, v81
	v_max3_f32 v2, v2, v82, v83
	v_mov_b32_e32 v3, v2
	s_nop 1
	v_permlane16_swap_b32_e32 v2, v3
	v_max_f32_e32 v2, v2, v3
	v_mov_b32_e32 v3, v2
	s_nop 1
	v_permlane32_swap_b32_e32 v2, v3
	v_max_f32_e32 v3, v2, v3
	v_sub_f32_e32 v2, v80, v3
	v_sub_f32_e32 v61, v61, v3
	v_sub_f32_e32 v80, v81, v3
	v_sub_f32_e32 v81, v82, v3
	v_sub_f32_e32 v82, v83, v3
	v_sub_f32_e32 v83, v88, v3
	v_sub_f32_e32 v88, v90, v3
	v_exp_f32_e32 v90, v61
	v_exp_f32_e32 v115, v2
	v_max_f32_e32 v61, v64, v64
	v_max_f32_e32 v2, v61, v65
	v_max3_f32 v2, v2, v66, v67
	v_max3_f32 v2, v2, v68, v69
	v_max3_f32 v2, v2, v70, v71
	v_max3_f32 v2, v2, v92, v93
	v_max3_f32 v2, v2, v94, v95
	v_max3_f32 v2, v2, v76, v77
	v_max3_f32 v2, v2, v78, v79
	v_mov_b32_e32 v61, v2
	s_nop 1
	v_permlane16_swap_b32_e32 v2, v61
	v_max_f32_e32 v2, v2, v61
	v_mov_b32_e32 v61, v2
	s_nop 1
	v_permlane32_swap_b32_e32 v2, v61
	v_max_f32_e32 v2, v2, v61
	v_sub_f32_e32 v60, v60, v3
	v_sub_f32_e32 v64, v64, v2
	v_exp_f32_e32 v60, v60
	v_sub_f32_e32 v65, v65, v2
	v_exp_f32_e32 v64, v64
	v_sub_f32_e32 v62, v62, v3
	v_sub_f32_e32 v66, v66, v2
	v_exp_f32_e32 v65, v65
	v_sub_f32_e32 v85, v89, v3
	v_sub_f32_e32 v89, v91, v3
	v_sub_f32_e32 v63, v63, v3
	v_exp_f32_e32 v91, v62
	v_sub_f32_e32 v67, v67, v2
	v_exp_f32_e32 v66, v66
	v_sub_f32_e32 v72, v72, v3
	v_exp_f32_e32 v109, v63
	v_sub_f32_e32 v61, v68, v2
	v_sub_f32_e32 v62, v69, v2
	v_exp_f32_e32 v67, v67
	v_sub_f32_e32 v73, v73, v3
	v_exp_f32_e32 v72, v72
	v_exp_f32_e32 v113, v83
	v_exp_f32_e32 v125, v82
	v_sub_f32_e32 v82, v92, v2
	v_sub_f32_e32 v83, v93, v2
	v_sub_f32_e32 v63, v70, v2
	v_sub_f32_e32 v68, v71, v2
	v_exp_f32_e32 v70, v61
	v_exp_f32_e32 v71, v62
	v_and_b32_e32 v61, v0, v64
	v_and_b32_e32 v60, v0, v60
	v_and_b32_e32 v62, v97, v90
	v_sub_f32_e32 v74, v74, v3
	v_exp_f32_e32 v110, v73
	v_exp_f32_e32 v121, v80
	v_exp_f32_e32 v124, v81
	v_sub_f32_e32 v122, v76, v2
	v_sub_f32_e32 v126, v78, v2
	v_exp_f32_e32 v76, v63
	v_exp_f32_e32 v78, v68
	v_and_b32_e32 v63, v97, v65
	v_cvt_pk_bf16_f32 v68, v60, v62
	v_pk_add_f32 v[80:81], v[60:61], 0 op_sel_hi:[1,0]
	v_exp_f32_e32 v0, v82
	v_exp_f32_e32 v60, v83
	v_sub_f32_e32 v75, v75, v3
	v_exp_f32_e32 v111, v74
	v_and_b32_e32 v65, v100, v66
	v_and_b32_e32 v64, v100, v91
	v_pk_add_f32 v[80:81], v[80:81], v[62:63]
	v_exp_f32_e32 v112, v75
	v_and_b32_e32 v67, v102, v67
	v_and_b32_e32 v66, v102, v109
	v_pk_add_f32 v[80:81], v[80:81], v[64:65]
	v_sub_f32_e32 v93, v95, v2
	v_and_b32_e32 v73, v86, v70
	v_and_b32_e32 v72, v86, v72
	v_pk_add_f32 v[80:81], v[80:81], v[66:67]
	v_exp_f32_e32 v114, v85
	v_sub_f32_e32 v92, v94, v2
	v_and_b32_e32 v75, v98, v71
	v_and_b32_e32 v74, v98, v110
	v_pk_add_f32 v[80:81], v[80:81], v[72:73]
	v_and_b32_e32 v83, v87, v0
	v_and_b32_e32 v82, v87, v113
	v_and_b32_e32 v87, v99, v60
	v_exp_f32_e32 v60, v93
	v_exp_f32_e32 v88, v88
	v_sub_f32_e32 v123, v77, v2
	v_and_b32_e32 v77, v101, v76
	v_and_b32_e32 v76, v101, v111
	v_pk_add_f32 v[80:81], v[80:81], v[74:75]
	v_exp_f32_e32 v0, v92
	v_exp_f32_e32 v89, v89
	v_sub_f32_e32 v127, v79, v2
	v_and_b32_e32 v79, v103, v78
	v_and_b32_e32 v78, v103, v112
	v_pk_add_f32 v[80:81], v[80:81], v[76:77]
	v_exp_f32_e32 v62, v122
	v_pk_add_f32 v[80:81], v[80:81], v[78:79]
	v_cvt_pk_bf16_f32 v69, v64, v66
	v_and_b32_e32 v86, v99, v114
	v_exp_f32_e32 v64, v123
	v_cvt_pk_bf16_f32 v100, v61, v63
	v_cvt_pk_bf16_f32 v102, v73, v75
	v_and_b32_e32 v75, v107, v60
	v_pk_add_f32 v[60:61], v[80:81], v[82:83]
	v_cvt_pk_bf16_f32 v70, v72, v74
	v_exp_f32_e32 v66, v126
	v_and_b32_e32 v73, v105, v0
	v_and_b32_e32 v72, v105, v88
	v_pk_add_f32 v[60:61], v[60:61], v[86:87]
	v_exp_f32_e32 v90, v127
	v_and_b32_e32 v74, v107, v89
	v_pk_add_f32 v[60:61], v[60:61], v[72:73]
	v_cvt_pk_bf16_f32 v71, v76, v78
	v_cvt_pk_bf16_f32 v103, v77, v79
	v_and_b32_e32 v77, v96, v62
	v_and_b32_e32 v76, v96, v115
	v_pk_add_f32 v[60:61], v[60:61], v[74:75]
	v_and_b32_e32 v79, v104, v64
	v_and_b32_e32 v78, v104, v121
	v_pk_add_f32 v[60:61], v[60:61], v[76:77]
	v_and_b32_e32 v89, v106, v66
	v_and_b32_e32 v88, v106, v124
	v_pk_add_f32 v[60:61], v[60:61], v[78:79]
	v_and_b32_e32 v91, v108, v90
	v_and_b32_e32 v90, v108, v125
	v_pk_add_f32 v[60:61], v[60:61], v[88:89]
	s_nop 0
	v_exp_f32_e64 v84, -v3
	v_exp_f32_e64 v85, -v2
	v_cvt_pk_bf16_f32 v101, v65, v67
	v_pk_add_f32 v[80:81], v[60:61], v[90:91]
	ds_read_b128 v[60:63], v177 offset:19712
	ds_read_b128 v[64:67], v177 offset:19776
	v_pk_add_f32 v[2:3], v[2:3], 0 op_sel_hi:[1,0]
	v_pk_mul_f32 v[122:123], v[84:85], 0 op_sel_hi:[1,0]
	v_pk_fma_f32 v[160:161], v[84:85], 0, v[80:81] op_sel_hi:[1,0,1]
	v_mov_b32_e32 v126, v122
	v_mov_b32_e32 v127, v122
	v_mov_b32_e32 v128, v122
	v_mov_b32_e32 v129, v122
	v_cvt_pk_bf16_f32 v130, v82, v86
	v_cvt_pk_bf16_f32 v131, v72, v74
	v_cvt_pk_bf16_f32 v132, v76, v78
	v_cvt_pk_bf16_f32 v133, v88, v90
	v_mov_b32_e32 v122, v123
	v_mov_b32_e32 v124, v123
	v_mov_b32_e32 v125, v123
	v_cvt_pk_bf16_f32 v134, v83, v87
	v_cvt_pk_bf16_f32 v135, v73, v75
	v_cvt_pk_bf16_f32 v136, v77, v79
	v_cvt_pk_bf16_f32 v137, v89, v91
	s_waitcnt lgkmcnt(3)
; #define MMV(SRC, DT) do { __builtin_amdgcn_s_setprio(1); _Pragma("unroll") for (int c2 = 0; c2 < 2; ++c2) { o[0][DT] = mfma16(SRC[c2], pf[0][c2], o[0][DT]); o[1][DT] = mfma16(SRC[c2], pf[1][c2], o[1][DT]); } __builtin_amdgcn_s_setprio(0); } while (0)
; DEVINL void attn_item(const Params& p, int item, char* smem, int wv) {
;     ...
;     LDV(vfb, 1); MMV(vfa, 0);
;     LDV(vfa, 2); MMV(vfb, 1);
;     LDV(vfb, 3); MMV(vfa, 2);
;     LDV(vfa, 4); MMV(vfb, 3);
;     LDV(vfb, 5); MMV(vfa, 4);
;     LDV(vfa, 6); MMV(vfb, 5);
;     LDV(vfb, 7); MMV(vfa, 6);
;     MMV(vfb, 7);
	v_mfma_f32_16x16x32_bf16 v[72:75], v[52:55], v[68:71], v[126:129]
	v_mfma_f32_16x16x32_bf16 v[52:55], v[52:55], v[100:103], v[122:125]
	s_waitcnt lgkmcnt(2)
	v_mfma_f32_16x16x32_bf16 v[88:91], v[56:59], v[130:133], v[72:75]
	v_mfma_f32_16x16x32_bf16 v[52:55], v[56:59], v[134:137], v[52:55]
	s_nop 0
	s_nop 1
	ds_read_b128 v[72:75], v177 offset:22016
	ds_read_b128 v[76:79], v177 offset:22080
	s_waitcnt lgkmcnt(3)
	v_mfma_f32_16x16x32_bf16 v[56:59], v[60:63], v[68:71], v[126:129]
	v_mfma_f32_16x16x32_bf16 v[60:63], v[60:63], v[100:103], v[122:125]
	s_waitcnt lgkmcnt(2)
	v_mfma_f32_16x16x32_bf16 v[84:87], v[64:67], v[130:133], v[56:59]
	v_mfma_f32_16x16x32_bf16 v[56:59], v[64:67], v[134:137], v[60:63]
	s_nop 0
	ds_read_b128 v[64:67], v177 offset:24320
	ds_read_b128 v[80:83], v177 offset:24384
	s_waitcnt lgkmcnt(3)
	v_mfma_f32_16x16x32_bf16 v[60:63], v[72:75], v[68:71], v[126:129]
	v_mfma_f32_16x16x32_bf16 v[72:75], v[72:75], v[100:103], v[122:125]
	s_waitcnt lgkmcnt(2)
	v_mfma_f32_16x16x32_bf16 v[92:95], v[76:79], v[130:133], v[60:63]
	v_mfma_f32_16x16x32_bf16 v[60:63], v[76:79], v[134:137], v[72:75]
	s_nop 0
	s_nop 2
	ds_read_b128 v[72:75], v177 offset:26624
	ds_read_b128 v[76:79], v177 offset:26688
	s_waitcnt lgkmcnt(3)
	v_mfma_f32_16x16x32_bf16 v[96:99], v[64:67], v[68:71], v[126:129]
	v_mfma_f32_16x16x32_bf16 v[64:67], v[64:67], v[100:103], v[122:125]
	s_waitcnt lgkmcnt(2)
	v_mfma_f32_16x16x32_bf16 v[96:99], v[80:83], v[130:133], v[96:99]
	v_mfma_f32_16x16x32_bf16 v[64:67], v[80:83], v[134:137], v[64:67]
	s_nop 0
	ds_read_b128 v[80:83], v177 offset:28928
	ds_read_b128 v[112:115], v177 offset:28992
	s_waitcnt lgkmcnt(3)
	v_mfma_f32_16x16x32_bf16 v[104:107], v[72:75], v[68:71], v[126:129]
	v_mfma_f32_16x16x32_bf16 v[72:75], v[72:75], v[100:103], v[122:125]
	s_waitcnt lgkmcnt(2)
	v_mfma_f32_16x16x32_bf16 v[104:107], v[76:79], v[130:133], v[104:107]
	v_mfma_f32_16x16x32_bf16 v[72:75], v[76:79], v[134:137], v[72:75]
	s_nop 0
	ds_read_b128 v[138:141], v177 offset:31232
	ds_read_b128 v[142:145], v177 offset:31296
	s_waitcnt lgkmcnt(3)
	v_mfma_f32_16x16x32_bf16 v[76:79], v[80:83], v[68:71], v[126:129]
	v_mfma_f32_16x16x32_bf16 v[80:83], v[80:83], v[100:103], v[122:125]
	s_waitcnt lgkmcnt(2)
	v_mfma_f32_16x16x32_bf16 v[108:111], v[112:115], v[130:133], v[76:79]
	v_mfma_f32_16x16x32_bf16 v[76:79], v[112:115], v[134:137], v[80:83]
	s_nop 0
	ds_read_b128 v[146:149], v177 offset:33536
	ds_read_b128 v[150:153], v177 offset:33600
	s_waitcnt lgkmcnt(3)
	v_mfma_f32_16x16x32_bf16 v[80:83], v[138:141], v[68:71], v[126:129]
	v_mfma_f32_16x16x32_bf16 v[138:141], v[138:141], v[100:103], v[122:125]
	s_waitcnt lgkmcnt(2)
	v_mfma_f32_16x16x32_bf16 v[112:115], v[142:145], v[130:133], v[80:83]
	v_mfma_f32_16x16x32_bf16 v[80:83], v[142:145], v[134:137], v[138:141]
	s_waitcnt lgkmcnt(1)
	v_mfma_f32_16x16x32_bf16 v[68:71], v[146:149], v[68:71], v[126:129]
	v_mfma_f32_16x16x32_bf16 v[122:125], v[146:149], v[100:103], v[122:125]
	s_waitcnt lgkmcnt(0)
	v_mfma_f32_16x16x32_bf16 v[100:103], v[150:153], v[130:133], v[68:71]
	v_mfma_f32_16x16x32_bf16 v[68:71], v[150:153], v[134:137], v[122:125]
	s_cbranch_execz .LBB0_705
	s_branch .LBB0_706

; DEVINL float fexp2(float x) { return __builtin_amdgcn_exp2f(x); }
; #define LDK(DST, KQ) _Pragma("unroll") for (int kc = 0; kc < 4; ++kc) DST[kc] = *(const bf16x8*)(Ks + ((KQ) * 16 + fr) * 136 + kc * 32 + fq * 8)
; DEVINL void attn_item(const Params& p, int item, char* smem, int wv) {
;     ...
;     if (kt * 64 <= qlast) {
;     f32x4 s[2][4];
;     bf16x8 kfa[4], kfb[4];
;     bf16x8 vfa[2], vfb[2];
;     ...
;     LDK(kfa, 0);
;     LDK(kfb, 1); MMS(kfa, 0);
;     LDK(kfa, 2); MMS(kfb, 1);
;     LDK(kfb, 3); MMS(kfa, 2);
;     LDV(vfa, 0); MMS(kfb, 3);
;     bf16x8 pf[2][2];
;     {
;       const unsigned long long msh = mw >> (fq * 4);
;       const int mlo = (int)(unsigned)msh, mhi = (int)(unsigned)(msh >> 32);
;       int mk[4][4];
; #pragma unroll
;       for (int j = 0; j < 4; ++j) {
;         mk[0][j] = __builtin_amdgcn_sbfe(mlo, j, 1); mk[1][j] = __builtin_amdgcn_sbfe(mlo, 16 + j, 1);
;         mk[2][j] = __builtin_amdgcn_sbfe(mhi, j, 1); mk[3][j] = __builtin_amdgcn_sbfe(mhi, 16 + j, 1);
;       }
; #pragma unroll
;       for (int hh = 0; hh < 2; ++hh) {
;         float mx = s[hh][0][0];
; #pragma unroll
;         for (int kq = 0; kq < 4; ++kq)
; #pragma unroll
;           for (int j = 0; j < 4; ++j) mx = fmaxf(mx, s[hh][kq][j]);
;         {
;           auto r1 = __builtin_amdgcn_permlane16_swap(__float_as_uint(mx), __float_as_uint(mx), false, false);
;           mx = fmaxf(__uint_as_float(r1[0]), __uint_as_float(r1[1]));
;           auto r2 = __builtin_amdgcn_permlane32_swap(__float_as_uint(mx), __float_as_uint(mx), false, false);
;           mx = fmaxf(__uint_as_float(r2[0]), __uint_as_float(r2[1]));
;         }
;         if (kt == 0 || __ballot(mx > 8.f)) {
;           const float delta = (kt == 0) ? mx : fmaxf(mx, 0.f);
;           const float alpha = fexp2(-delta);
;           mrun[hh] += delta;
;           lsum[hh] *= alpha;
; #pragma unroll
;           for (int dt = 0; dt < 8; ++dt) o[hh][dt] *= alpha;
; #pragma unroll
;           for (int kq = 0; kq < 4; ++kq)
; #pragma unroll
;             for (int j = 0; j < 4; ++j) s[hh][kq][j] -= delta;
.LBB0_709:
	s_add_i32 s8, s6, 0xffffffa0
	s_cmp_gt_i32 s8, s1
	s_cbranch_scc1 .LBB0_715
	ds_read_b128 v[116:119], v175
	ds_read_b128 v[120:123], v175 offset:64
	ds_read_b128 v[124:127], v175 offset:128
	ds_read_b128 v[128:131], v175 offset:192
	ds_read_b128 v[132:135], v175 offset:4352
	ds_read_b128 v[140:143], v175 offset:4416
	ds_read_b128 v[144:147], v175 offset:4480
	ds_read_b128 v[178:181], v175 offset:4544
	v_xor_b32_e32 v182, 0x80000000, v3
	v_xor_b32_e32 v186, 0x80000000, v2
	v_mov_b32_e32 v183, v182
	v_mov_b32_e32 v184, v182
	v_mov_b32_e32 v185, v182
	v_mov_b32_e32 v187, v186
	v_mov_b32_e32 v188, v186
	v_mov_b32_e32 v189, v186
	s_waitcnt lgkmcnt(7)
	v_mfma_f32_16x16x32_bf16 v[136:139], v[116:119], v[32:35], v[182:185]
	v_mfma_f32_16x16x32_bf16 v[116:119], v[116:119], v[16:19], v[186:189]
	s_waitcnt lgkmcnt(6)
	v_mfma_f32_16x16x32_bf16 v[136:139], v[120:123], v[4:7], v[136:139]
	v_mfma_f32_16x16x32_bf16 v[116:119], v[120:123], v[20:23], v[116:119]
	s_waitcnt lgkmcnt(5)
	v_mfma_f32_16x16x32_bf16 v[120:123], v[124:127], v[8:11], v[136:139]
	v_mfma_f32_16x16x32_bf16 v[116:119], v[124:127], v[24:27], v[116:119]
	s_waitcnt lgkmcnt(4)
	v_mfma_f32_16x16x32_bf16 v[152:155], v[128:131], v[12:15], v[120:123]
	v_mfma_f32_16x16x32_bf16 v[136:139], v[128:131], v[28:31], v[116:119]
	s_nop 3
	ds_read_b128 v[116:119], v175 offset:8704
	ds_read_b128 v[120:123], v175 offset:8768
	ds_read_b128 v[124:127], v175 offset:8832
	ds_read_b128 v[128:131], v175 offset:8896
	s_waitcnt lgkmcnt(7)
	v_mfma_f32_16x16x32_bf16 v[148:151], v[132:135], v[32:35], v[182:185]
	v_mfma_f32_16x16x32_bf16 v[132:135], v[132:135], v[16:19], v[186:189]
	s_waitcnt lgkmcnt(6)
	v_mfma_f32_16x16x32_bf16 v[148:151], v[140:143], v[4:7], v[148:151]
	v_mfma_f32_16x16x32_bf16 v[132:135], v[140:143], v[20:23], v[132:135]
	s_waitcnt lgkmcnt(5)
	v_mfma_f32_16x16x32_bf16 v[140:143], v[144:147], v[8:11], v[148:151]
	v_mfma_f32_16x16x32_bf16 v[132:135], v[144:147], v[24:27], v[132:135]
	s_waitcnt lgkmcnt(4)
	v_mfma_f32_16x16x32_bf16 v[148:151], v[178:181], v[12:15], v[140:143]
	v_mfma_f32_16x16x32_bf16 v[132:135], v[178:181], v[28:31], v[132:135]
	ds_read_b128 v[144:147], v175 offset:13056
	ds_read_b128 v[178:181], v175 offset:13120
	ds_read_b128 v[190:193], v175 offset:13184
	ds_read_b128 v[194:197], v175 offset:13248
	s_waitcnt lgkmcnt(7)
	v_mfma_f32_16x16x32_bf16 v[140:143], v[116:119], v[32:35], v[182:185]
	v_mfma_f32_16x16x32_bf16 v[116:119], v[116:119], v[16:19], v[186:189]
	s_waitcnt lgkmcnt(6)
	v_mfma_f32_16x16x32_bf16 v[140:143], v[120:123], v[4:7], v[140:143]
	v_mfma_f32_16x16x32_bf16 v[116:119], v[120:123], v[20:23], v[116:119]
	s_waitcnt lgkmcnt(5)
	v_mfma_f32_16x16x32_bf16 v[120:123], v[124:127], v[8:11], v[140:143]
	v_mfma_f32_16x16x32_bf16 v[116:119], v[124:127], v[24:27], v[116:119]
	s_waitcnt lgkmcnt(4)
	v_mfma_f32_16x16x32_bf16 v[140:143], v[128:131], v[12:15], v[120:123]
	v_mfma_f32_16x16x32_bf16 v[124:127], v[128:131], v[28:31], v[116:119]
	s_nop 2
	s_nop 0
	ds_read_b128 v[116:119], v177 offset:17408
	ds_read_b128 v[120:123], v177 offset:17472
	s_waitcnt lgkmcnt(5)
	v_mfma_f32_16x16x32_bf16 v[128:131], v[144:147], v[32:35], v[182:185]
	v_mfma_f32_16x16x32_bf16 v[144:147], v[144:147], v[16:19], v[186:189]
	s_waitcnt lgkmcnt(4)
	v_mfma_f32_16x16x32_bf16 v[128:131], v[178:181], v[4:7], v[128:131]
	v_mfma_f32_16x16x32_bf16 v[144:147], v[178:181], v[20:23], v[144:147]
	s_waitcnt lgkmcnt(3)
	v_mfma_f32_16x16x32_bf16 v[128:131], v[190:193], v[8:11], v[128:131]
	v_mfma_f32_16x16x32_bf16 v[178:181], v[190:193], v[24:27], v[144:147]
	s_waitcnt lgkmcnt(2)
	v_mfma_f32_16x16x32_bf16 v[144:147], v[194:197], v[12:15], v[128:131]
	v_mfma_f32_16x16x32_bf16 v[128:131], v[194:197], v[28:31], v[178:181]
	s_nop 3
	s_nop 0
	v_max_f32_e32 v179, v152, v152
	v_max_f32_e32 v178, v179, v153
	v_max3_f32 v178, v178, v154, v155
	v_max3_f32 v178, v178, v148, v149
	v_max3_f32 v178, v178, v150, v151
	v_max3_f32 v178, v178, v140, v141
	v_max3_f32 v178, v178, v142, v143
	v_max3_f32 v178, v178, v144, v145
	v_max3_f32 v178, v178, v146, v147
	v_mov_b32_e32 v179, v178
	s_nop 1
	v_permlane16_swap_b32_e32 v178, v179
	v_max_f32_e32 v178, v178, v179
	v_mov_b32_e32 v179, v178
	s_nop 1
	v_permlane32_swap_b32_e32 v178, v179
	v_max_f32_e32 v178, v178, v179
	v_cmp_lt_f32_e32 vcc, s25, v178
	s_cbranch_vccz .LBB0_712
	v_max_f32_e32 v178, 0, v178
	v_exp_f32_e64 v180, -v178
	v_add_f32_e32 v3, v3, v178
	v_pk_add_f32 v[152:153], v[152:153], v[178:179] op_sel_hi:[1,0] neg_lo:[0,1] neg_hi:[0,1]
	v_pk_add_f32 v[154:155], v[154:155], v[178:179] op_sel_hi:[1,0] neg_lo:[0,1] neg_hi:[0,1]
	v_mul_f32_e32 v160, v160, v180
	v_pk_mul_f32 v[90:91], v[90:91], v[180:181] op_sel_hi:[1,0]
	v_pk_mul_f32 v[88:89], v[88:89], v[180:181] op_sel_hi:[1,0]
	v_pk_mul_f32 v[86:87], v[86:87], v[180:181] op_sel_hi:[1,0]
	v_pk_mul_f32 v[84:85], v[84:85], v[180:181] op_sel_hi:[1,0]
	v_pk_mul_f32 v[94:95], v[94:95], v[180:181] op_sel_hi:[1,0]
	v_pk_mul_f32 v[92:93], v[92:93], v[180:181] op_sel_hi:[1,0]
	v_pk_mul_f32 v[98:99], v[98:99], v[180:181] op_sel_hi:[1,0]
	v_pk_mul_f32 v[96:97], v[96:97], v[180:181] op_sel_hi:[1,0]
	v_pk_mul_f32 v[106:107], v[106:107], v[180:181] op_sel_hi:[1,0]
	v_pk_mul_f32 v[104:105], v[104:105], v[180:181] op_sel_hi:[1,0]
	v_pk_mul_f32 v[110:111], v[110:111], v[180:181] op_sel_hi:[1,0]
	v_pk_mul_f32 v[108:109], v[108:109], v[180:181] op_sel_hi:[1,0]
	v_pk_mul_f32 v[114:115], v[114:115], v[180:181] op_sel_hi:[1,0]
	v_pk_mul_f32 v[112:113], v[112:113], v[180:181] op_sel_hi:[1,0]
	v_pk_mul_f32 v[102:103], v[102:103], v[180:181] op_sel_hi:[1,0]
	v_pk_mul_f32 v[100:101], v[100:101], v[180:181] op_sel_hi:[1,0]
	v_pk_add_f32 v[148:149], v[148:149], v[178:179] op_sel_hi:[1,0] neg_lo:[0,1] neg_hi:[0,1]
	v_pk_add_f32 v[150:151], v[150:151], v[178:179] op_sel_hi:[1,0] neg_lo:[0,1] neg_hi:[0,1]
	v_pk_add_f32 v[140:141], v[140:141], v[178:179] op_sel_hi:[1,0] neg_lo:[0,1] neg_hi:[0,1]
	v_pk_add_f32 v[142:143], v[142:143], v[178:179] op_sel_hi:[1,0] neg_lo:[0,1] neg_hi:[0,1]
	v_pk_add_f32 v[144:145], v[144:145], v[178:179] op_sel_hi:[1,0] neg_lo:[0,1] neg_hi:[0,1]
	v_pk_add_f32 v[146:147], v[146:147], v[178:179] op_sel_hi:[1,0] neg_lo:[0,1] neg_hi:[0,1]
; DEVINL float fexp2(float x) { return __builtin_amdgcn_exp2f(x); }
; DEVINL void attn_item(const Params& p, int item, char* smem, int wv) {
;     ...
;       for (int hh = 0; hh < 2; ++hh) {
;         float mx = s[hh][0][0];
; #pragma unroll
;         for (int kq = 0; kq < 4; ++kq)
; #pragma unroll
;           for (int j = 0; j < 4; ++j) mx = fmaxf(mx, s[hh][kq][j]);
;         {
;           auto r1 = __builtin_amdgcn_permlane16_swap(__float_as_uint(mx), __float_as_uint(mx), false, false);
;           mx = fmaxf(__uint_as_float(r1[0]), __uint_as_float(r1[1]));
;           auto r2 = __builtin_amdgcn_permlane32_swap(__float_as_uint(mx), __float_as_uint(mx), false, false);
;           mx = fmaxf(__uint_as_float(r2[0]), __uint_as_float(r2[1]));
;         }
;         if (kt == 0 || __ballot(mx > 8.f)) {
;           const float delta = (kt == 0) ? mx : fmaxf(mx, 0.f);
;           const float alpha = fexp2(-delta);
;           mrun[hh] += delta;
;           lsum[hh] *= alpha;
; #pragma unroll
;           for (int dt = 0; dt < 8; ++dt) o[hh][dt] *= alpha;
; #pragma unroll
;           for (int kq = 0; kq < 4; ++kq)
; #pragma unroll
;             for (int j = 0; j < 4; ++j) s[hh][kq][j] -= delta;
.LBB0_712:
	v_max_f32_e32 v179, v136, v136
	v_max_f32_e32 v178, v179, v137
	v_max3_f32 v178, v178, v138, v139
	v_max3_f32 v178, v178, v132, v133
	v_max3_f32 v178, v178, v134, v135
	v_max3_f32 v178, v178, v124, v125
	v_max3_f32 v178, v178, v126, v127
	v_max3_f32 v178, v178, v128, v129
	v_max3_f32 v178, v178, v130, v131
	v_mov_b32_e32 v179, v178
	s_nop 1
	v_permlane16_swap_b32_e32 v178, v179
	v_max_f32_e32 v178, v178, v179
	v_mov_b32_e32 v179, v178
	s_nop 1
	v_permlane32_swap_b32_e32 v178, v179
	v_max_f32_e32 v178, v178, v179
	v_cmp_lt_f32_e32 vcc, s25, v178
	s_cbranch_vccz .LBB0_714
	v_max_f32_e32 v178, 0, v178
	v_exp_f32_e64 v180, -v178
	v_add_f32_e32 v2, v2, v178
	v_pk_add_f32 v[136:137], v[136:137], v[178:179] op_sel_hi:[1,0] neg_lo:[0,1] neg_hi:[0,1]
	v_pk_add_f32 v[138:139], v[138:139], v[178:179] op_sel_hi:[1,0] neg_lo:[0,1] neg_hi:[0,1]
	v_mul_f32_e32 v161, v161, v180
	v_pk_mul_f32 v[54:55], v[54:55], v[180:181] op_sel_hi:[1,0]
	v_pk_mul_f32 v[52:53], v[52:53], v[180:181] op_sel_hi:[1,0]
	v_pk_mul_f32 v[58:59], v[58:59], v[180:181] op_sel_hi:[1,0]
	v_pk_mul_f32 v[56:57], v[56:57], v[180:181] op_sel_hi:[1,0]
	v_pk_mul_f32 v[62:63], v[62:63], v[180:181] op_sel_hi:[1,0]
	v_pk_mul_f32 v[60:61], v[60:61], v[180:181] op_sel_hi:[1,0]
	v_pk_mul_f32 v[66:67], v[66:67], v[180:181] op_sel_hi:[1,0]
	v_pk_mul_f32 v[64:65], v[64:65], v[180:181] op_sel_hi:[1,0]
	v_pk_mul_f32 v[74:75], v[74:75], v[180:181] op_sel_hi:[1,0]
	v_pk_mul_f32 v[72:73], v[72:73], v[180:181] op_sel_hi:[1,0]
	v_pk_mul_f32 v[78:79], v[78:79], v[180:181] op_sel_hi:[1,0]
	v_pk_mul_f32 v[76:77], v[76:77], v[180:181] op_sel_hi:[1,0]
	v_pk_mul_f32 v[82:83], v[82:83], v[180:181] op_sel_hi:[1,0]
	v_pk_mul_f32 v[80:81], v[80:81], v[180:181] op_sel_hi:[1,0]
	v_pk_mul_f32 v[70:71], v[70:71], v[180:181] op_sel_hi:[1,0]
	v_pk_mul_f32 v[68:69], v[68:69], v[180:181] op_sel_hi:[1,0]
	v_pk_add_f32 v[132:133], v[132:133], v[178:179] op_sel_hi:[1,0] neg_lo:[0,1] neg_hi:[0,1]
	v_pk_add_f32 v[134:135], v[134:135], v[178:179] op_sel_hi:[1,0] neg_lo:[0,1] neg_hi:[0,1]
	v_pk_add_f32 v[124:125], v[124:125], v[178:179] op_sel_hi:[1,0] neg_lo:[0,1] neg_hi:[0,1]
	v_pk_add_f32 v[126:127], v[126:127], v[178:179] op_sel_hi:[1,0] neg_lo:[0,1] neg_hi:[0,1]
	v_pk_add_f32 v[128:129], v[128:129], v[178:179] op_sel_hi:[1,0] neg_lo:[0,1] neg_hi:[0,1]
	v_pk_add_f32 v[130:131], v[130:131], v[178:179] op_sel_hi:[1,0] neg_lo:[0,1] neg_hi:[0,1]

; #define LOADG(S, GRP) do { const u16* _k = kb + (size_t)(GRP) * 4096; \
;       _Pragma("unroll") for (int _i = 0; _i < 4; ++_i) { kf[S][2 * _i] = *(const bf16x8*)(_k + _i * 1024); kf[S][2 * _i + 1] = *(const bf16x8*)(_k + _i * 1024 + 32); } } while (0)
; DEVINL void phase_topk(const Params& p, int layer, char* smem, int wv, int rep) {
;     ...
;     {
;       int g = wid;
;       if (g < ng) LOADG(0, g);
;       for (; g < ng; g += 16) {
;         if (g + 8 < ng) LOADG(1, g + 8);
;         COMPUTEG(0, g);
;         if (g + 8 < ng) {
;           if (g + 16 < ng) LOADG(0, g + 16);
;           COMPUTEG(1, g + 8);
;         }
;       }
.LBB0_1496:
	v_mfma_f32_16x16x32_bf16 v[170:173], v[0:3], v[96:99], 0
	v_add_u32_e32 v169, 0xffff0800, v165
	v_mfma_f32_16x16x32_bf16 v[170:173], v[4:7], v[92:95], v[170:173]
	v_mfma_f32_16x16x32_bf16 v[178:181], v[0:3], v[88:91], 0
	s_nop 6
	v_max_f32_e32 v171, 0, v171
	v_max_f32_e32 v170, 0, v170
	v_mul_f32_e32 v174, v13, v171
	v_max_f32_e32 v172, 0, v172
	v_fmac_f32_e32 v174, v12, v170
	v_fmac_f32_e32 v174, v14, v172
	v_max_f32_e32 v170, 0, v173
	v_fmac_f32_e32 v174, v15, v170
	v_mfma_f32_16x16x32_bf16 v[170:173], v[4:7], v[84:87], v[178:181]
	v_mfma_f32_16x16x32_bf16 v[178:181], v[0:3], v[112:115], 0
	s_nop 6
	v_max_f32_e32 v171, 0, v171
	v_max_f32_e32 v170, 0, v170
	v_mul_f32_e32 v175, v13, v171
	v_fmac_f32_e32 v175, v12, v170
	v_max_f32_e32 v170, 0, v172
	v_fmac_f32_e32 v175, v14, v170
	v_max_f32_e32 v170, 0, v173
	v_fmac_f32_e32 v175, v15, v170
	v_mfma_f32_16x16x32_bf16 v[170:173], v[4:7], v[108:111], v[178:181]
	s_nop 0
	v_permlane16_swap_b32_e32 v174, v175
	v_add_f32_e32 v174, v174, v175
	v_mfma_f32_16x16x32_bf16 v[178:181], v[0:3], v[104:107], 0
	s_nop 3
	v_max_f32_e32 v171, 0, v171
	v_max_f32_e32 v170, 0, v170
	v_mul_f32_e32 v177, v13, v171
	v_fmac_f32_e32 v177, v12, v170
	v_max_f32_e32 v170, 0, v172
	v_fmac_f32_e32 v177, v14, v170
	v_max_f32_e32 v170, 0, v173
	v_fmac_f32_e32 v177, v15, v170
	v_mfma_f32_16x16x32_bf16 v[170:173], v[4:7], v[100:103], v[178:181]
	v_mfma_f32_16x16x32_bf16 v[178:181], v[16:19], v[88:91], 0
	s_nop 6
	v_max_f32_e32 v171, 0, v171
	v_max_f32_e32 v170, 0, v170
	v_mul_f32_e32 v171, v13, v171
	v_fmac_f32_e32 v171, v12, v170
	v_max_f32_e32 v170, 0, v172
	v_fmac_f32_e32 v171, v14, v170
	v_max_f32_e32 v170, 0, v173
	v_fmac_f32_e32 v171, v15, v170
	s_nop 1
	v_permlane16_swap_b32_e32 v177, v171
	v_add_f32_e32 v175, v177, v171
	v_mfma_f32_16x16x32_bf16 v[170:173], v[16:19], v[96:99], 0
	s_nop 0
	v_permlane32_swap_b32_e32 v174, v175
	v_add_f32_e32 v174, v174, v175
	v_mfma_f32_16x16x32_bf16 v[170:173], v[8:11], v[92:95], v[170:173]
	ds_write_b32 v169, v174
	s_nop 6
	v_max_f32_e32 v169, v170, v170
	v_max_f32_e32 v170, 0, v171
	v_max_f32_e32 v169, 0, v169
	v_mul_f32_e32 v174, v21, v170
	v_fmac_f32_e32 v174, v20, v169
	v_max_f32_e32 v169, 0, v172
	v_fmac_f32_e32 v174, v22, v169
	v_max_f32_e32 v169, v173, v173
	v_mfma_f32_16x16x32_bf16 v[170:173], v[8:11], v[84:87], v[178:181]
	v_max_f32_e32 v169, 0, v169
	v_fmac_f32_e32 v174, v23, v169
	v_mfma_f32_16x16x32_bf16 v[178:181], v[16:19], v[112:115], 0
	s_nop 4
	v_max_f32_e32 v169, v170, v170
	v_max_f32_e32 v170, 0, v171
	v_max_f32_e32 v169, 0, v169
	v_mul_f32_e32 v175, v21, v170
	v_fmac_f32_e32 v175, v20, v169
	v_max_f32_e32 v169, 0, v172
	v_fmac_f32_e32 v175, v22, v169
	v_max_f32_e32 v169, v173, v173
	v_mfma_f32_16x16x32_bf16 v[170:173], v[8:11], v[108:111], v[178:181]
	v_max_f32_e32 v169, 0, v169
	v_fmac_f32_e32 v175, v23, v169
	s_nop 1
	v_permlane16_swap_b32_e32 v174, v175
	v_mfma_f32_16x16x32_bf16 v[178:181], v[16:19], v[104:107], 0
	s_nop 1
	v_max_f32_e32 v169, v170, v170
	v_max_f32_e32 v170, 0, v171
	v_max_f32_e32 v169, 0, v169
	v_mul_f32_e32 v177, v21, v170
	v_fmac_f32_e32 v177, v20, v169
	v_max_f32_e32 v169, 0, v172
	v_fmac_f32_e32 v177, v22, v169
	v_max_f32_e32 v169, v173, v173
	v_mfma_f32_16x16x32_bf16 v[170:173], v[8:11], v[100:103], v[178:181]
	v_max_f32_e32 v169, 0, v169
	v_fmac_f32_e32 v177, v23, v169
	v_mfma_f32_16x16x32_bf16 v[178:181], v[24:27], v[88:91], 0
	s_nop 4
	v_max_f32_e32 v169, v170, v170
	v_max_f32_e32 v170, 0, v171
	v_max_f32_e32 v169, 0, v169
	v_mul_f32_e32 v170, v21, v170
	v_fmac_f32_e32 v170, v20, v169
	v_max_f32_e32 v169, 0, v172
	v_fmac_f32_e32 v170, v22, v169
	v_max_f32_e32 v169, 0, v173
	v_fmac_f32_e32 v170, v23, v169
	s_nop 1
	v_permlane16_swap_b32_e32 v177, v170
	v_add_f32_e32 v169, v174, v175
	v_add_f32_e32 v174, v177, v170
	v_mfma_f32_16x16x32_bf16 v[170:173], v[24:27], v[96:99], 0
	s_nop 0
	v_permlane32_swap_b32_e32 v169, v174
	v_add_f32_e32 v169, v169, v174
	v_mfma_f32_16x16x32_bf16 v[170:173], v[28:31], v[92:95], v[170:173]
	v_add_u32_e32 v174, 0xffff4800, v165
	ds_write_b32 v174, v169
	s_nop 5
	v_max_f32_e32 v169, v170, v170
	v_max_f32_e32 v170, 0, v171
	v_max_f32_e32 v169, 0, v169
	v_mul_f32_e32 v174, v37, v170
	v_fmac_f32_e32 v174, v36, v169
	v_max_f32_e32 v169, 0, v172
	v_fmac_f32_e32 v174, v38, v169
	v_max_f32_e32 v169, v173, v173
	v_mfma_f32_16x16x32_bf16 v[170:173], v[28:31], v[84:87], v[178:181]
	v_max_f32_e32 v169, 0, v169
	v_fmac_f32_e32 v174, v39, v169
	v_mfma_f32_16x16x32_bf16 v[178:181], v[24:27], v[112:115], 0
	s_nop 4
	v_max_f32_e32 v169, v170, v170
	v_max_f32_e32 v170, 0, v171
	v_max_f32_e32 v169, 0, v169
	v_mul_f32_e32 v175, v37, v170
	v_fmac_f32_e32 v175, v36, v169
	v_max_f32_e32 v169, 0, v172
	v_fmac_f32_e32 v175, v38, v169
	v_max_f32_e32 v169, v173, v173
	v_mfma_f32_16x16x32_bf16 v[170:173], v[28:31], v[108:111], v[178:181]
	v_max_f32_e32 v169, 0, v169
	v_fmac_f32_e32 v175, v39, v169
	s_nop 1
	v_permlane16_swap_b32_e32 v174, v175
	v_mfma_f32_16x16x32_bf16 v[178:181], v[24:27], v[104:107], 0
	s_nop 1
	v_max_f32_e32 v169, v170, v170
	v_max_f32_e32 v170, 0, v171
	v_max_f32_e32 v169, 0, v169
	v_mul_f32_e32 v177, v37, v170
	v_fmac_f32_e32 v177, v36, v169
	v_max_f32_e32 v169, 0, v172
	v_fmac_f32_e32 v177, v38, v169
	v_max_f32_e32 v169, v173, v173
	v_mfma_f32_16x16x32_bf16 v[170:173], v[28:31], v[100:103], v[178:181]
	v_max_f32_e32 v169, 0, v169
	v_fmac_f32_e32 v177, v39, v169
	v_mfma_f32_16x16x32_bf16 v[178:181], v[40:43], v[88:91], 0
	s_nop 4
	v_max_f32_e32 v169, v170, v170
	v_max_f32_e32 v170, 0, v171
	v_max_f32_e32 v169, 0, v169
	v_mul_f32_e32 v170, v37, v170
	v_fmac_f32_e32 v170, v36, v169
	v_max_f32_e32 v169, 0, v172
; #define LOADG(S, GRP) do { const u16* _k = kb + (size_t)(GRP) * 4096; \
;       _Pragma("unroll") for (int _i = 0; _i < 4; ++_i) { kf[S][2 * _i] = *(const bf16x8*)(_k + _i * 1024); kf[S][2 * _i + 1] = *(const bf16x8*)(_k + _i * 1024 + 32); } } while (0)
; DEVINL void phase_topk(const Params& p, int layer, char* smem, int wv, int rep) {
;     ...
;     {
;       int g = wid;
;       if (g < ng) LOADG(0, g);
;       for (; g < ng; g += 16) {
;         if (g + 8 < ng) LOADG(1, g + 8);
;         COMPUTEG(0, g);
;         if (g + 8 < ng) {
;           if (g + 16 < ng) LOADG(0, g + 16);
;           COMPUTEG(1, g + 8);
;         }
;       }
	v_fmac_f32_e32 v170, v38, v169
	v_max_f32_e32 v169, 0, v173
	v_fmac_f32_e32 v170, v39, v169
	s_nop 1
	v_permlane16_swap_b32_e32 v177, v170
	v_add_f32_e32 v169, v174, v175
	v_add_f32_e32 v174, v177, v170
	v_mfma_f32_16x16x32_bf16 v[170:173], v[40:43], v[96:99], 0
	s_nop 0
	v_permlane32_swap_b32_e32 v169, v174
	v_add_f32_e32 v169, v169, v174
	v_mfma_f32_16x16x32_bf16 v[170:173], v[32:35], v[92:95], v[170:173]
	v_add_u32_e32 v174, 0xffff8800, v165
	ds_write_b32 v174, v169
	s_nop 5
	v_max_f32_e32 v169, v170, v170
	v_max_f32_e32 v170, 0, v171
	v_max_f32_e32 v169, 0, v169
	v_mul_f32_e32 v174, v45, v170
	v_fmac_f32_e32 v174, v44, v169
	v_max_f32_e32 v169, 0, v172
	v_fmac_f32_e32 v174, v46, v169
	v_max_f32_e32 v169, v173, v173
	v_mfma_f32_16x16x32_bf16 v[170:173], v[32:35], v[84:87], v[178:181]
	v_max_f32_e32 v169, 0, v169
	v_fmac_f32_e32 v174, v47, v169
	v_mfma_f32_16x16x32_bf16 v[178:181], v[40:43], v[112:115], 0
	s_nop 4
	v_max_f32_e32 v169, v170, v170
	v_max_f32_e32 v170, 0, v171
	v_max_f32_e32 v169, 0, v169
	v_mul_f32_e32 v175, v45, v170
	v_fmac_f32_e32 v175, v44, v169
	v_max_f32_e32 v169, 0, v172
	v_fmac_f32_e32 v175, v46, v169
	v_max_f32_e32 v169, v173, v173
	v_mfma_f32_16x16x32_bf16 v[170:173], v[32:35], v[108:111], v[178:181]
	v_max_f32_e32 v169, 0, v169
	v_fmac_f32_e32 v175, v47, v169
	s_nop 1
	v_permlane16_swap_b32_e32 v174, v175
	v_mfma_f32_16x16x32_bf16 v[178:181], v[40:43], v[104:107], 0
	s_nop 1
	v_max_f32_e32 v169, v170, v170
	v_max_f32_e32 v170, 0, v171
	v_max_f32_e32 v169, 0, v169
	v_mul_f32_e32 v177, v45, v170
	v_fmac_f32_e32 v177, v44, v169
	v_max_f32_e32 v169, 0, v172
	v_fmac_f32_e32 v177, v46, v169
	v_max_f32_e32 v169, v173, v173
	v_mfma_f32_16x16x32_bf16 v[170:173], v[32:35], v[100:103], v[178:181]
	v_max_f32_e32 v169, 0, v169
	v_fmac_f32_e32 v177, v47, v169
	v_mfma_f32_16x16x32_bf16 v[178:181], v[52:55], v[88:91], 0
	s_nop 4
	v_max_f32_e32 v169, v170, v170
	v_max_f32_e32 v170, 0, v171
	v_max_f32_e32 v169, 0, v169
	v_mul_f32_e32 v170, v45, v170
	v_fmac_f32_e32 v170, v44, v169
	v_max_f32_e32 v169, 0, v172
	v_fmac_f32_e32 v170, v46, v169
	v_max_f32_e32 v169, 0, v173
	v_fmac_f32_e32 v170, v47, v169
	s_nop 1
	v_permlane16_swap_b32_e32 v177, v170
	v_add_f32_e32 v169, v174, v175
	v_add_f32_e32 v174, v177, v170
	v_mfma_f32_16x16x32_bf16 v[170:173], v[52:55], v[96:99], 0
	s_nop 0
	v_permlane32_swap_b32_e32 v169, v174
	v_add_f32_e32 v169, v169, v174
	v_mfma_f32_16x16x32_bf16 v[170:173], v[48:51], v[92:95], v[170:173]
	v_add_u32_e32 v174, 0xffffc800, v165
	ds_write_b32 v174, v169
	s_nop 5
	v_max_f32_e32 v169, v170, v170
	v_max_f32_e32 v170, 0, v171
	v_max_f32_e32 v169, 0, v169
	v_mul_f32_e32 v174, v57, v170
	v_fmac_f32_e32 v174, v56, v169
	v_max_f32_e32 v169, 0, v172
	v_fmac_f32_e32 v174, v58, v169
	v_max_f32_e32 v169, v173, v173
	v_mfma_f32_16x16x32_bf16 v[170:173], v[48:51], v[84:87], v[178:181]
	v_max_f32_e32 v169, 0, v169
	v_fmac_f32_e32 v174, v59, v169
	v_mfma_f32_16x16x32_bf16 v[178:181], v[52:55], v[112:115], 0
	s_nop 4
	v_max_f32_e32 v169, v170, v170
	v_max_f32_e32 v170, 0, v171
	v_max_f32_e32 v169, 0, v169
	v_mul_f32_e32 v175, v57, v170
	v_fmac_f32_e32 v175, v56, v169
	v_max_f32_e32 v169, 0, v172
	v_fmac_f32_e32 v175, v58, v169
	v_max_f32_e32 v169, v173, v173
	v_mfma_f32_16x16x32_bf16 v[170:173], v[48:51], v[108:111], v[178:181]
	v_max_f32_e32 v169, 0, v169
	v_fmac_f32_e32 v175, v59, v169
	s_nop 1
	v_permlane16_swap_b32_e32 v174, v175
	v_mfma_f32_16x16x32_bf16 v[178:181], v[52:55], v[104:107], 0
	s_nop 1
	v_max_f32_e32 v169, v170, v170
	v_max_f32_e32 v170, 0, v171
	v_max_f32_e32 v169, 0, v169
	v_mul_f32_e32 v177, v57, v170
	v_fmac_f32_e32 v177, v56, v169
	v_max_f32_e32 v169, 0, v172
	v_fmac_f32_e32 v177, v58, v169
	v_max_f32_e32 v169, v173, v173
	v_mfma_f32_16x16x32_bf16 v[170:173], v[48:51], v[100:103], v[178:181]
	v_max_f32_e32 v169, 0, v169
	v_fmac_f32_e32 v177, v59, v169
	v_mfma_f32_16x16x32_bf16 v[178:181], v[60:63], v[88:91], 0
	s_nop 4
	v_max_f32_e32 v169, v170, v170
	v_max_f32_e32 v170, 0, v171
	v_max_f32_e32 v169, 0, v169
	v_mul_f32_e32 v170, v57, v170
	v_fmac_f32_e32 v170, v56, v169
	v_max_f32_e32 v169, 0, v172
	v_fmac_f32_e32 v170, v58, v169
	v_max_f32_e32 v169, 0, v173
	v_fmac_f32_e32 v170, v59, v169
	s_nop 1
	v_permlane16_swap_b32_e32 v177, v170
	v_add_f32_e32 v169, v174, v175
	v_add_f32_e32 v174, v177, v170
	v_mfma_f32_16x16x32_bf16 v[170:173], v[60:63], v[96:99], 0
	s_nop 0
	v_permlane32_swap_b32_e32 v169, v174
	v_add_f32_e32 v169, v169, v174
	v_mfma_f32_16x16x32_bf16 v[170:173], v[64:67], v[92:95], v[170:173]
	s_nop 7
	v_max_f32_e32 v171, 0, v171
	v_max_f32_e32 v170, 0, v170
	v_mul_f32_e32 v174, v69, v171
	v_fmac_f32_e32 v174, v68, v170
	v_max_f32_e32 v170, 0, v172
	v_fmac_f32_e32 v174, v70, v170
	v_max_f32_e32 v170, 0, v173
	v_fmac_f32_e32 v174, v71, v170
	v_mfma_f32_16x16x32_bf16 v[170:173], v[64:67], v[84:87], v[178:181]
	v_mfma_f32_16x16x32_bf16 v[178:181], v[60:63], v[112:115], 0
	s_nop 6
	v_max_f32_e32 v171, 0, v171
	v_max_f32_e32 v170, 0, v170
	v_mul_f32_e32 v175, v69, v171
; #define LOADG(S, GRP) do { const u16* _k = kb + (size_t)(GRP) * 4096; \
;       _Pragma("unroll") for (int _i = 0; _i < 4; ++_i) { kf[S][2 * _i] = *(const bf16x8*)(_k + _i * 1024); kf[S][2 * _i + 1] = *(const bf16x8*)(_k + _i * 1024 + 32); } } while (0)
; DEVINL void phase_topk(const Params& p, int layer, char* smem, int wv, int rep) {
;     ...
;     {
;       int g = wid;
;       if (g < ng) LOADG(0, g);
;       for (; g < ng; g += 16) {
;         if (g + 8 < ng) LOADG(1, g + 8);
;         COMPUTEG(0, g);
;         if (g + 8 < ng) {
;           if (g + 16 < ng) LOADG(0, g + 16);
;           COMPUTEG(1, g + 8);
;         }
;       }
	v_fmac_f32_e32 v175, v68, v170
	v_max_f32_e32 v170, 0, v172
	v_fmac_f32_e32 v175, v70, v170
	v_max_f32_e32 v170, 0, v173
	v_fmac_f32_e32 v175, v71, v170
	v_mfma_f32_16x16x32_bf16 v[170:173], v[64:67], v[108:111], v[178:181]
	s_nop 0
	v_permlane16_swap_b32_e32 v174, v175
	v_add_f32_e32 v174, v174, v175
	v_mfma_f32_16x16x32_bf16 v[178:181], v[60:63], v[104:107], 0
	s_nop 3
	v_max_f32_e32 v171, 0, v171
	v_max_f32_e32 v170, 0, v170
	v_mul_f32_e32 v177, v69, v171
	v_fmac_f32_e32 v177, v68, v170
	v_max_f32_e32 v170, 0, v172
	v_fmac_f32_e32 v177, v70, v170
	v_max_f32_e32 v170, 0, v173
	v_fmac_f32_e32 v177, v71, v170
	v_mfma_f32_16x16x32_bf16 v[170:173], v[64:67], v[100:103], v[178:181]
	v_mfma_f32_16x16x32_bf16 v[178:181], v[72:75], v[88:91], 0
	s_nop 6
	v_max_f32_e32 v171, 0, v171
	v_max_f32_e32 v170, 0, v170
	v_mul_f32_e32 v171, v69, v171
	v_fmac_f32_e32 v171, v68, v170
	v_max_f32_e32 v170, 0, v172
	v_fmac_f32_e32 v171, v70, v170
	v_max_f32_e32 v170, 0, v173
	v_fmac_f32_e32 v171, v71, v170
	s_nop 1
	v_permlane16_swap_b32_e32 v177, v171
	v_add_f32_e32 v175, v177, v171
	v_mfma_f32_16x16x32_bf16 v[170:173], v[72:75], v[96:99], 0
	s_nop 0
	v_permlane32_swap_b32_e32 v174, v175
	v_add_f32_e32 v174, v174, v175
	v_mfma_f32_16x16x32_bf16 v[170:173], v[76:79], v[92:95], v[170:173]
	ds_write2st64_b32 v165, v169, v174 offset0:8 offset1:72
	s_nop 6
	v_max_f32_e32 v169, v170, v170
	v_max_f32_e32 v170, 0, v171
	v_max_f32_e32 v169, 0, v169
	v_mul_f32_e32 v174, v81, v170
	v_fmac_f32_e32 v174, v80, v169
	v_max_f32_e32 v169, 0, v172
	v_fmac_f32_e32 v174, v82, v169
	v_max_f32_e32 v169, v173, v173
	v_mfma_f32_16x16x32_bf16 v[170:173], v[76:79], v[84:87], v[178:181]
	v_max_f32_e32 v169, 0, v169
	v_fmac_f32_e32 v174, v83, v169
	v_mfma_f32_16x16x32_bf16 v[178:181], v[72:75], v[112:115], 0
	s_nop 4
	v_max_f32_e32 v169, v170, v170
	v_max_f32_e32 v170, 0, v171
	v_max_f32_e32 v169, 0, v169
	v_mul_f32_e32 v175, v81, v170
	v_fmac_f32_e32 v175, v80, v169
	v_max_f32_e32 v169, 0, v172
	v_fmac_f32_e32 v175, v82, v169
	v_max_f32_e32 v169, v173, v173
	v_mfma_f32_16x16x32_bf16 v[170:173], v[76:79], v[108:111], v[178:181]
	v_max_f32_e32 v169, 0, v169
	v_fmac_f32_e32 v175, v83, v169
	s_nop 1
	v_permlane16_swap_b32_e32 v174, v175
	v_mfma_f32_16x16x32_bf16 v[178:181], v[72:75], v[104:107], 0
	s_nop 1
	v_max_f32_e32 v169, v170, v170
	v_max_f32_e32 v170, 0, v171
	v_max_f32_e32 v169, 0, v169
	v_mul_f32_e32 v177, v81, v170
	v_fmac_f32_e32 v177, v80, v169
	v_max_f32_e32 v169, 0, v172
	v_fmac_f32_e32 v177, v82, v169
	v_max_f32_e32 v169, v173, v173
	v_mfma_f32_16x16x32_bf16 v[170:173], v[76:79], v[100:103], v[178:181]
	v_max_f32_e32 v169, 0, v169
	v_fmac_f32_e32 v177, v83, v169
	v_mfma_f32_16x16x32_bf16 v[178:181], v[116:119], v[88:91], 0
	s_nop 4
	v_max_f32_e32 v169, v170, v170
	v_max_f32_e32 v170, 0, v171
	v_max_f32_e32 v169, 0, v169
	v_mul_f32_e32 v170, v81, v170
	v_fmac_f32_e32 v170, v80, v169
	v_max_f32_e32 v169, 0, v172
	v_fmac_f32_e32 v170, v82, v169
	v_max_f32_e32 v169, 0, v173
	v_fmac_f32_e32 v170, v83, v169
	s_nop 1
	v_permlane16_swap_b32_e32 v177, v170
	v_add_f32_e32 v169, v174, v175
	v_add_f32_e32 v174, v177, v170
	v_mfma_f32_16x16x32_bf16 v[170:173], v[116:119], v[96:99], 0
	s_nop 0
	v_permlane32_swap_b32_e32 v169, v174
	v_add_f32_e32 v169, v169, v174
	v_mfma_f32_16x16x32_bf16 v[170:173], v[120:123], v[92:95], v[170:173]
	s_nop 7
	v_max_f32_e32 v171, 0, v171
	v_max_f32_e32 v170, 0, v170
	v_mul_f32_e32 v174, v149, v171
	v_fmac_f32_e32 v174, v148, v170
	v_max_f32_e32 v170, 0, v172
	v_fmac_f32_e32 v174, v150, v170
	v_max_f32_e32 v170, 0, v173
	v_fmac_f32_e32 v174, v151, v170
	v_mfma_f32_16x16x32_bf16 v[170:173], v[120:123], v[84:87], v[178:181]
	v_mfma_f32_16x16x32_bf16 v[178:181], v[116:119], v[112:115], 0
	s_nop 6
	v_max_f32_e32 v171, 0, v171
	v_max_f32_e32 v170, 0, v170
	v_mul_f32_e32 v175, v149, v171
	v_fmac_f32_e32 v175, v148, v170
	v_max_f32_e32 v170, 0, v172
	v_fmac_f32_e32 v175, v150, v170
	v_max_f32_e32 v170, 0, v173
	v_fmac_f32_e32 v175, v151, v170
	v_mfma_f32_16x16x32_bf16 v[170:173], v[120:123], v[108:111], v[178:181]
	s_nop 0
	v_permlane16_swap_b32_e32 v174, v175
	v_mfma_f32_16x16x32_bf16 v[178:181], v[116:119], v[104:107], 0
	s_nop 4
	v_max_f32_e32 v171, 0, v171
	v_max_f32_e32 v170, 0, v170
	v_mul_f32_e32 v177, v149, v171
	v_fmac_f32_e32 v177, v148, v170
	v_max_f32_e32 v170, 0, v172
	v_fmac_f32_e32 v177, v150, v170
	v_max_f32_e32 v170, 0, v173
	v_fmac_f32_e32 v177, v151, v170
	v_mfma_f32_16x16x32_bf16 v[170:173], v[120:123], v[100:103], v[178:181]
	s_nop 7
	v_max_f32_e32 v171, 0, v171
	v_max_f32_e32 v170, 0, v170
	v_mul_f32_e32 v171, v149, v171
	v_fmac_f32_e32 v171, v148, v170
	v_max_f32_e32 v170, 0, v172
	v_fmac_f32_e32 v171, v150, v170
	v_max_f32_e32 v170, 0, v173
	v_fmac_f32_e32 v171, v151, v170
	s_nop 1
	v_permlane16_swap_b32_e32 v177, v171
	v_add_f32_e32 v170, v174, v175
	v_add_f32_e32 v171, v177, v171
	s_nop 1
	v_permlane32_swap_b32_e32 v170, v171
	v_add_f32_e32 v170, v170, v171
	ds_write2st64_b32 v165, v169, v170 offset0:136 offset1:200

; #define LOADG(S, GRP) do { const u16* _k = kb + (size_t)(GRP) * 4096; \
;       _Pragma("unroll") for (int _i = 0; _i < 4; ++_i) { kf[S][2 * _i] = *(const bf16x8*)(_k + _i * 1024); kf[S][2 * _i + 1] = *(const bf16x8*)(_k + _i * 1024 + 32); } } while (0)
; DEVINL void phase_topk(const Params& p, int layer, char* smem, int wv, int rep) {
;     ...
;     {
;       int g = wid;
;       if (g < ng) LOADG(0, g);
;       for (; g < ng; g += 16) {
;         if (g + 8 < ng) LOADG(1, g + 8);
;         COMPUTEG(0, g);
;         if (g + 8 < ng) {
;           if (g + 16 < ng) LOADG(0, g + 16);
;           COMPUTEG(1, g + 8);
;         }
;       }
.LBB0_1500:
	s_waitcnt vmcnt(7)
	v_mfma_f32_16x16x32_bf16 v[170:173], v[0:3], v[124:127], 0
	v_add_u32_e32 v169, 0xffff0000, v165
	s_andn2_b64 vcc, exec, s[2:3]
	s_add_i32 s5, s5, 16
	s_waitcnt vmcnt(6)
	v_mfma_f32_16x16x32_bf16 v[170:173], v[4:7], v[128:131], v[170:173]
	s_waitcnt vmcnt(5)
	v_mfma_f32_16x16x32_bf16 v[178:181], v[0:3], v[132:135], 0
	s_nop 5
	v_max_f32_e32 v171, 0, v171
	v_max_f32_e32 v170, 0, v170
	v_mul_f32_e32 v174, v13, v171
	v_max_f32_e32 v172, 0, v172
	v_fmac_f32_e32 v174, v12, v170
	v_fmac_f32_e32 v174, v14, v172
	v_max_f32_e32 v170, 0, v173
	v_fmac_f32_e32 v174, v15, v170
	s_waitcnt vmcnt(4)
	v_mfma_f32_16x16x32_bf16 v[170:173], v[4:7], v[136:139], v[178:181]
	s_waitcnt vmcnt(0)
	v_mfma_f32_16x16x32_bf16 v[178:181], v[0:3], v[140:143], 0
	s_nop 5
	v_max_f32_e32 v171, 0, v171
	v_max_f32_e32 v170, 0, v170
	v_mul_f32_e32 v175, v13, v171
	v_fmac_f32_e32 v175, v12, v170
	v_max_f32_e32 v170, 0, v172
	v_fmac_f32_e32 v175, v14, v170
	v_max_f32_e32 v170, 0, v173
	v_fmac_f32_e32 v175, v15, v170
	v_mfma_f32_16x16x32_bf16 v[170:173], v[4:7], v[144:147], v[178:181]
	s_nop 0
	v_permlane16_swap_b32_e32 v174, v175
	v_add_f32_e32 v174, v174, v175
	v_mfma_f32_16x16x32_bf16 v[178:181], v[0:3], v[152:155], 0
	s_nop 3
	v_max_f32_e32 v171, 0, v171
	v_max_f32_e32 v170, 0, v170
	v_mul_f32_e32 v177, v13, v171
	v_fmac_f32_e32 v177, v12, v170
	v_max_f32_e32 v170, 0, v172
	v_fmac_f32_e32 v177, v14, v170
	v_max_f32_e32 v170, 0, v173
	v_fmac_f32_e32 v177, v15, v170
	v_mfma_f32_16x16x32_bf16 v[170:173], v[4:7], v[156:159], v[178:181]
	v_mfma_f32_16x16x32_bf16 v[178:181], v[16:19], v[132:135], 0
	s_nop 6
	v_max_f32_e32 v171, 0, v171
	v_max_f32_e32 v170, 0, v170
	v_mul_f32_e32 v171, v13, v171
	v_fmac_f32_e32 v171, v12, v170
	v_max_f32_e32 v170, 0, v172
	v_fmac_f32_e32 v171, v14, v170
	v_max_f32_e32 v170, 0, v173
	v_fmac_f32_e32 v171, v15, v170
	s_nop 1
	v_permlane16_swap_b32_e32 v177, v171
	v_add_f32_e32 v175, v177, v171
	v_mfma_f32_16x16x32_bf16 v[170:173], v[16:19], v[124:127], 0
	s_nop 0
	v_permlane32_swap_b32_e32 v174, v175
	v_add_f32_e32 v174, v174, v175
	v_mfma_f32_16x16x32_bf16 v[170:173], v[8:11], v[128:131], v[170:173]
	ds_write_b32 v169, v174
	s_nop 6
	v_max_f32_e32 v169, v170, v170
	v_max_f32_e32 v170, 0, v171
	v_max_f32_e32 v169, 0, v169
	v_mul_f32_e32 v174, v21, v170
	v_fmac_f32_e32 v174, v20, v169
	v_max_f32_e32 v169, 0, v172
	v_fmac_f32_e32 v174, v22, v169
	v_max_f32_e32 v169, v173, v173
	v_mfma_f32_16x16x32_bf16 v[170:173], v[8:11], v[136:139], v[178:181]
	v_max_f32_e32 v169, 0, v169
	v_fmac_f32_e32 v174, v23, v169
	v_mfma_f32_16x16x32_bf16 v[178:181], v[16:19], v[140:143], 0
	s_nop 4
	v_max_f32_e32 v169, v170, v170
	v_max_f32_e32 v170, 0, v171
	v_max_f32_e32 v169, 0, v169
	v_mul_f32_e32 v175, v21, v170
	v_fmac_f32_e32 v175, v20, v169
	v_max_f32_e32 v169, 0, v172
	v_fmac_f32_e32 v175, v22, v169
	v_max_f32_e32 v169, v173, v173
	v_mfma_f32_16x16x32_bf16 v[170:173], v[8:11], v[144:147], v[178:181]
	v_max_f32_e32 v169, 0, v169
	v_fmac_f32_e32 v175, v23, v169
	s_nop 1
	v_permlane16_swap_b32_e32 v174, v175
	v_mfma_f32_16x16x32_bf16 v[178:181], v[16:19], v[152:155], 0
	s_nop 1
	v_max_f32_e32 v169, v170, v170
	v_max_f32_e32 v170, 0, v171
	v_max_f32_e32 v169, 0, v169
	v_mul_f32_e32 v177, v21, v170
	v_fmac_f32_e32 v177, v20, v169
	v_max_f32_e32 v169, 0, v172
	v_fmac_f32_e32 v177, v22, v169
	v_max_f32_e32 v169, v173, v173
	v_mfma_f32_16x16x32_bf16 v[170:173], v[8:11], v[156:159], v[178:181]
	v_max_f32_e32 v169, 0, v169
	v_fmac_f32_e32 v177, v23, v169
	v_mfma_f32_16x16x32_bf16 v[178:181], v[24:27], v[132:135], 0
	s_nop 4
	v_max_f32_e32 v169, v170, v170
	v_max_f32_e32 v170, 0, v171
	v_max_f32_e32 v169, 0, v169
	v_mul_f32_e32 v170, v21, v170
	v_fmac_f32_e32 v170, v20, v169
	v_max_f32_e32 v169, 0, v172
	v_fmac_f32_e32 v170, v22, v169
	v_max_f32_e32 v169, 0, v173
	v_fmac_f32_e32 v170, v23, v169
	s_nop 1
	v_permlane16_swap_b32_e32 v177, v170
	v_add_f32_e32 v169, v174, v175
	v_add_f32_e32 v174, v177, v170
	v_mfma_f32_16x16x32_bf16 v[170:173], v[24:27], v[124:127], 0
	s_nop 0
	v_permlane32_swap_b32_e32 v169, v174
	v_add_f32_e32 v169, v169, v174
	v_mfma_f32_16x16x32_bf16 v[170:173], v[28:31], v[128:131], v[170:173]
	v_add_u32_e32 v174, 0xffff4000, v165
	ds_write_b32 v174, v169
	s_nop 5
	v_max_f32_e32 v169, v170, v170
	v_max_f32_e32 v170, 0, v171
	v_max_f32_e32 v169, 0, v169
	v_mul_f32_e32 v174, v37, v170
	v_fmac_f32_e32 v174, v36, v169
	v_max_f32_e32 v169, 0, v172
	v_fmac_f32_e32 v174, v38, v169
	v_max_f32_e32 v169, v173, v173
	v_mfma_f32_16x16x32_bf16 v[170:173], v[28:31], v[136:139], v[178:181]
	v_max_f32_e32 v169, 0, v169
	v_fmac_f32_e32 v174, v39, v169
	v_mfma_f32_16x16x32_bf16 v[178:181], v[24:27], v[140:143], 0
	s_nop 4
	v_max_f32_e32 v169, v170, v170
	v_max_f32_e32 v170, 0, v171
	v_max_f32_e32 v169, 0, v169
	v_mul_f32_e32 v175, v37, v170
	v_fmac_f32_e32 v175, v36, v169
	v_max_f32_e32 v169, 0, v172
	v_fmac_f32_e32 v175, v38, v169
	v_max_f32_e32 v169, v173, v173
	v_mfma_f32_16x16x32_bf16 v[170:173], v[28:31], v[144:147], v[178:181]
	v_max_f32_e32 v169, 0, v169
	v_fmac_f32_e32 v175, v39, v169
	s_nop 1
	v_permlane16_swap_b32_e32 v174, v175
	v_mfma_f32_16x16x32_bf16 v[178:181], v[24:27], v[152:155], 0
	s_nop 1
	v_max_f32_e32 v169, v170, v170
	v_max_f32_e32 v170, 0, v171
	v_max_f32_e32 v169, 0, v169
	v_mul_f32_e32 v177, v37, v170
	v_fmac_f32_e32 v177, v36, v169
	v_max_f32_e32 v169, 0, v172
	v_fmac_f32_e32 v177, v38, v169
	v_max_f32_e32 v169, v173, v173
	v_mfma_f32_16x16x32_bf16 v[170:173], v[28:31], v[156:159], v[178:181]
	v_max_f32_e32 v169, 0, v169
	v_fmac_f32_e32 v177, v39, v169
	v_mfma_f32_16x16x32_bf16 v[178:181], v[40:43], v[132:135], 0
; #define LOADG(S, GRP) do { const u16* _k = kb + (size_t)(GRP) * 4096; \
;       _Pragma("unroll") for (int _i = 0; _i < 4; ++_i) { kf[S][2 * _i] = *(const bf16x8*)(_k + _i * 1024); kf[S][2 * _i + 1] = *(const bf16x8*)(_k + _i * 1024 + 32); } } while (0)
; DEVINL void phase_topk(const Params& p, int layer, char* smem, int wv, int rep) {
;     ...
;     {
;       int g = wid;
;       if (g < ng) LOADG(0, g);
;       for (; g < ng; g += 16) {
;         if (g + 8 < ng) LOADG(1, g + 8);
;         COMPUTEG(0, g);
;         if (g + 8 < ng) {
;           if (g + 16 < ng) LOADG(0, g + 16);
;           COMPUTEG(1, g + 8);
;         }
;       }
	s_nop 4
	v_max_f32_e32 v169, v170, v170
	v_max_f32_e32 v170, 0, v171
	v_max_f32_e32 v169, 0, v169
	v_mul_f32_e32 v170, v37, v170
	v_fmac_f32_e32 v170, v36, v169
	v_max_f32_e32 v169, 0, v172
	v_fmac_f32_e32 v170, v38, v169
	v_max_f32_e32 v169, 0, v173
	v_fmac_f32_e32 v170, v39, v169
	s_nop 1
	v_permlane16_swap_b32_e32 v177, v170
	v_add_f32_e32 v169, v174, v175
	v_add_f32_e32 v174, v177, v170
	v_mfma_f32_16x16x32_bf16 v[170:173], v[40:43], v[124:127], 0
	s_nop 0
	v_permlane32_swap_b32_e32 v169, v174
	v_add_f32_e32 v169, v169, v174
	v_mfma_f32_16x16x32_bf16 v[170:173], v[32:35], v[128:131], v[170:173]
	v_add_u32_e32 v174, 0xffff8000, v165
	ds_write_b32 v174, v169
	s_nop 5
	v_max_f32_e32 v169, v170, v170
	v_max_f32_e32 v170, 0, v171
	v_max_f32_e32 v169, 0, v169
	v_mul_f32_e32 v174, v45, v170
	v_fmac_f32_e32 v174, v44, v169
	v_max_f32_e32 v169, 0, v172
	v_fmac_f32_e32 v174, v46, v169
	v_max_f32_e32 v169, v173, v173
	v_mfma_f32_16x16x32_bf16 v[170:173], v[32:35], v[136:139], v[178:181]
	v_max_f32_e32 v169, 0, v169
	v_fmac_f32_e32 v174, v47, v169
	v_mfma_f32_16x16x32_bf16 v[178:181], v[40:43], v[140:143], 0
	s_nop 4
	v_max_f32_e32 v169, v170, v170
	v_max_f32_e32 v170, 0, v171
	v_max_f32_e32 v169, 0, v169
	v_mul_f32_e32 v175, v45, v170
	v_fmac_f32_e32 v175, v44, v169
	v_max_f32_e32 v169, 0, v172
	v_fmac_f32_e32 v175, v46, v169
	v_max_f32_e32 v169, v173, v173
	v_mfma_f32_16x16x32_bf16 v[170:173], v[32:35], v[144:147], v[178:181]
	v_max_f32_e32 v169, 0, v169
	v_fmac_f32_e32 v175, v47, v169
	s_nop 1
	v_permlane16_swap_b32_e32 v174, v175
	v_mfma_f32_16x16x32_bf16 v[178:181], v[40:43], v[152:155], 0
	s_nop 1
	v_max_f32_e32 v169, v170, v170
	v_max_f32_e32 v170, 0, v171
	v_max_f32_e32 v169, 0, v169
	v_mul_f32_e32 v177, v45, v170
	v_fmac_f32_e32 v177, v44, v169
	v_max_f32_e32 v169, 0, v172
	v_fmac_f32_e32 v177, v46, v169
	v_max_f32_e32 v169, v173, v173
	v_mfma_f32_16x16x32_bf16 v[170:173], v[32:35], v[156:159], v[178:181]
	v_max_f32_e32 v169, 0, v169
	v_fmac_f32_e32 v177, v47, v169
	v_mfma_f32_16x16x32_bf16 v[178:181], v[52:55], v[132:135], 0
	s_nop 4
	v_max_f32_e32 v169, v170, v170
	v_max_f32_e32 v170, 0, v171
	v_max_f32_e32 v169, 0, v169
	v_mul_f32_e32 v170, v45, v170
	v_fmac_f32_e32 v170, v44, v169
	v_max_f32_e32 v169, 0, v172
	v_fmac_f32_e32 v170, v46, v169
	v_max_f32_e32 v169, 0, v173
	v_fmac_f32_e32 v170, v47, v169
	s_nop 1
	v_permlane16_swap_b32_e32 v177, v170
	v_add_f32_e32 v169, v174, v175
	v_add_f32_e32 v174, v177, v170
	v_mfma_f32_16x16x32_bf16 v[170:173], v[52:55], v[124:127], 0
	s_nop 0
	v_permlane32_swap_b32_e32 v169, v174
	v_add_f32_e32 v169, v169, v174
	v_mfma_f32_16x16x32_bf16 v[170:173], v[48:51], v[128:131], v[170:173]
	v_add_u32_e32 v174, 0xffffc000, v165
	ds_write_b32 v174, v169
	s_nop 5
	v_max_f32_e32 v169, v170, v170
	v_max_f32_e32 v170, 0, v171
	v_max_f32_e32 v169, 0, v169
	v_mul_f32_e32 v174, v57, v170
	v_fmac_f32_e32 v174, v56, v169
	v_max_f32_e32 v169, 0, v172
	v_fmac_f32_e32 v174, v58, v169
	v_max_f32_e32 v169, v173, v173
	v_mfma_f32_16x16x32_bf16 v[170:173], v[48:51], v[136:139], v[178:181]
	v_max_f32_e32 v169, 0, v169
	v_fmac_f32_e32 v174, v59, v169
	v_mfma_f32_16x16x32_bf16 v[178:181], v[52:55], v[140:143], 0
	s_nop 4
	v_max_f32_e32 v169, v170, v170
	v_max_f32_e32 v170, 0, v171
	v_max_f32_e32 v169, 0, v169
	v_mul_f32_e32 v175, v57, v170
	v_fmac_f32_e32 v175, v56, v169
	v_max_f32_e32 v169, 0, v172
	v_fmac_f32_e32 v175, v58, v169
	v_max_f32_e32 v169, v173, v173
	v_mfma_f32_16x16x32_bf16 v[170:173], v[48:51], v[144:147], v[178:181]
	v_max_f32_e32 v169, 0, v169
	v_fmac_f32_e32 v175, v59, v169
	s_nop 1
	v_permlane16_swap_b32_e32 v174, v175
	v_mfma_f32_16x16x32_bf16 v[178:181], v[52:55], v[152:155], 0
	s_nop 1
	v_max_f32_e32 v169, v170, v170
	v_max_f32_e32 v170, 0, v171
	v_max_f32_e32 v169, 0, v169
	v_mul_f32_e32 v177, v57, v170
	v_fmac_f32_e32 v177, v56, v169
	v_max_f32_e32 v169, 0, v172
	v_fmac_f32_e32 v177, v58, v169
	v_max_f32_e32 v169, v173, v173
	v_mfma_f32_16x16x32_bf16 v[170:173], v[48:51], v[156:159], v[178:181]
	v_max_f32_e32 v169, 0, v169
	v_fmac_f32_e32 v177, v59, v169
	v_mfma_f32_16x16x32_bf16 v[178:181], v[60:63], v[132:135], 0
	s_nop 4
	v_max_f32_e32 v169, v170, v170
	v_max_f32_e32 v170, 0, v171
	v_max_f32_e32 v169, 0, v169
	v_mul_f32_e32 v170, v57, v170
	v_fmac_f32_e32 v170, v56, v169
	v_max_f32_e32 v169, 0, v172
	v_fmac_f32_e32 v170, v58, v169
	v_max_f32_e32 v169, 0, v173
	v_fmac_f32_e32 v170, v59, v169
	s_nop 1
	v_permlane16_swap_b32_e32 v177, v170
	v_add_f32_e32 v169, v174, v175
	v_add_f32_e32 v174, v177, v170
	v_mfma_f32_16x16x32_bf16 v[170:173], v[60:63], v[124:127], 0
	s_nop 0
	v_permlane32_swap_b32_e32 v169, v174
	v_add_f32_e32 v169, v169, v174
	v_mfma_f32_16x16x32_bf16 v[170:173], v[64:67], v[128:131], v[170:173]
	s_nop 7
	v_max_f32_e32 v171, 0, v171
	v_max_f32_e32 v170, 0, v170
	v_mul_f32_e32 v174, v69, v171
	v_fmac_f32_e32 v174, v68, v170
	v_max_f32_e32 v170, 0, v172
	v_fmac_f32_e32 v174, v70, v170
	v_max_f32_e32 v170, 0, v173
	v_fmac_f32_e32 v174, v71, v170
	v_mfma_f32_16x16x32_bf16 v[170:173], v[64:67], v[136:139], v[178:181]
	v_mfma_f32_16x16x32_bf16 v[178:181], v[60:63], v[140:143], 0
	s_nop 6
	v_max_f32_e32 v171, 0, v171
	v_max_f32_e32 v170, 0, v170
	v_mul_f32_e32 v175, v69, v171
	v_fmac_f32_e32 v175, v68, v170
	v_max_f32_e32 v170, 0, v172
	v_fmac_f32_e32 v175, v70, v170
	v_max_f32_e32 v170, 0, v173
	v_fmac_f32_e32 v175, v71, v170
	v_mfma_f32_16x16x32_bf16 v[170:173], v[64:67], v[144:147], v[178:181]
	s_nop 0
; #define LOADG(S, GRP) do { const u16* _k = kb + (size_t)(GRP) * 4096; \
;       _Pragma("unroll") for (int _i = 0; _i < 4; ++_i) { kf[S][2 * _i] = *(const bf16x8*)(_k + _i * 1024); kf[S][2 * _i + 1] = *(const bf16x8*)(_k + _i * 1024 + 32); } } while (0)
; DEVINL void phase_topk(const Params& p, int layer, char* smem, int wv, int rep) {
;     ...
;     {
;       int g = wid;
;       if (g < ng) LOADG(0, g);
;       for (; g < ng; g += 16) {
;         if (g + 8 < ng) LOADG(1, g + 8);
;         COMPUTEG(0, g);
;         if (g + 8 < ng) {
;           if (g + 16 < ng) LOADG(0, g + 16);
;           COMPUTEG(1, g + 8);
;         }
;       }
	v_permlane16_swap_b32_e32 v174, v175
	v_add_f32_e32 v174, v174, v175
	v_mfma_f32_16x16x32_bf16 v[178:181], v[60:63], v[152:155], 0
	s_nop 3
	v_max_f32_e32 v171, 0, v171
	v_max_f32_e32 v170, 0, v170
	v_mul_f32_e32 v177, v69, v171
	v_fmac_f32_e32 v177, v68, v170
	v_max_f32_e32 v170, 0, v172
	v_fmac_f32_e32 v177, v70, v170
	v_max_f32_e32 v170, 0, v173
	v_fmac_f32_e32 v177, v71, v170
	v_mfma_f32_16x16x32_bf16 v[170:173], v[64:67], v[156:159], v[178:181]
	v_mfma_f32_16x16x32_bf16 v[178:181], v[72:75], v[132:135], 0
	s_nop 6
	v_max_f32_e32 v171, 0, v171
	v_max_f32_e32 v170, 0, v170
	v_mul_f32_e32 v171, v69, v171
	v_fmac_f32_e32 v171, v68, v170
	v_max_f32_e32 v170, 0, v172
	v_fmac_f32_e32 v171, v70, v170
	v_max_f32_e32 v170, 0, v173
	v_fmac_f32_e32 v171, v71, v170
	s_nop 1
	v_permlane16_swap_b32_e32 v177, v171
	v_add_f32_e32 v175, v177, v171
	v_mfma_f32_16x16x32_bf16 v[170:173], v[72:75], v[124:127], 0
	s_nop 0
	v_permlane32_swap_b32_e32 v174, v175
	v_add_f32_e32 v174, v174, v175
	v_mfma_f32_16x16x32_bf16 v[170:173], v[76:79], v[128:131], v[170:173]
	ds_write2st64_b32 v165, v169, v174 offset1:64
	s_nop 6
	v_max_f32_e32 v169, v170, v170
	v_max_f32_e32 v170, 0, v171
	v_max_f32_e32 v169, 0, v169
	v_mul_f32_e32 v174, v81, v170
	v_fmac_f32_e32 v174, v80, v169
	v_max_f32_e32 v169, 0, v172
	v_fmac_f32_e32 v174, v82, v169
	v_max_f32_e32 v169, v173, v173
	v_mfma_f32_16x16x32_bf16 v[170:173], v[76:79], v[136:139], v[178:181]
	v_max_f32_e32 v169, 0, v169
	v_fmac_f32_e32 v174, v83, v169
	v_mfma_f32_16x16x32_bf16 v[178:181], v[72:75], v[140:143], 0
	s_nop 4
	v_max_f32_e32 v169, v170, v170
	v_max_f32_e32 v170, 0, v171
	v_max_f32_e32 v169, 0, v169
	v_mul_f32_e32 v175, v81, v170
	v_fmac_f32_e32 v175, v80, v169
	v_max_f32_e32 v169, 0, v172
	v_fmac_f32_e32 v175, v82, v169
	v_max_f32_e32 v169, v173, v173
	v_mfma_f32_16x16x32_bf16 v[170:173], v[76:79], v[144:147], v[178:181]
	v_max_f32_e32 v169, 0, v169
	v_fmac_f32_e32 v175, v83, v169
	s_nop 1
	v_permlane16_swap_b32_e32 v174, v175
	v_mfma_f32_16x16x32_bf16 v[178:181], v[72:75], v[152:155], 0
	s_nop 1
	v_max_f32_e32 v169, v170, v170
	v_max_f32_e32 v170, 0, v171
	v_max_f32_e32 v169, 0, v169
	v_mul_f32_e32 v177, v81, v170
	v_fmac_f32_e32 v177, v80, v169
	v_max_f32_e32 v169, 0, v172
	v_fmac_f32_e32 v177, v82, v169
	v_max_f32_e32 v169, v173, v173
	v_mfma_f32_16x16x32_bf16 v[170:173], v[76:79], v[156:159], v[178:181]
	v_max_f32_e32 v169, 0, v169
	v_fmac_f32_e32 v177, v83, v169
	v_mfma_f32_16x16x32_bf16 v[178:181], v[116:119], v[132:135], 0
	s_nop 4
	v_max_f32_e32 v169, v170, v170
	v_max_f32_e32 v170, 0, v171
	v_max_f32_e32 v169, 0, v169
	v_mul_f32_e32 v170, v81, v170
	v_fmac_f32_e32 v170, v80, v169
	v_max_f32_e32 v169, 0, v172
	v_fmac_f32_e32 v170, v82, v169
	v_max_f32_e32 v169, 0, v173
	v_fmac_f32_e32 v170, v83, v169
	s_nop 1
	v_permlane16_swap_b32_e32 v177, v170
	v_add_f32_e32 v169, v174, v175
	v_add_f32_e32 v174, v177, v170
	v_mfma_f32_16x16x32_bf16 v[170:173], v[116:119], v[124:127], 0
	s_nop 0
	v_permlane32_swap_b32_e32 v169, v174
	v_add_f32_e32 v169, v169, v174
	v_mfma_f32_16x16x32_bf16 v[170:173], v[120:123], v[128:131], v[170:173]
	s_nop 7
	v_max_f32_e32 v171, 0, v171
	v_max_f32_e32 v170, 0, v170
	v_mul_f32_e32 v174, v149, v171
	v_fmac_f32_e32 v174, v148, v170
	v_max_f32_e32 v170, 0, v172
	v_fmac_f32_e32 v174, v150, v170
	v_max_f32_e32 v170, 0, v173
	v_fmac_f32_e32 v174, v151, v170
	v_mfma_f32_16x16x32_bf16 v[170:173], v[120:123], v[136:139], v[178:181]
	v_mfma_f32_16x16x32_bf16 v[178:181], v[116:119], v[140:143], 0
	s_nop 6
	v_max_f32_e32 v171, 0, v171
	v_max_f32_e32 v170, 0, v170
	v_mul_f32_e32 v175, v149, v171
	v_fmac_f32_e32 v175, v148, v170
	v_max_f32_e32 v170, 0, v172
	v_fmac_f32_e32 v175, v150, v170
	v_max_f32_e32 v170, 0, v173
	v_fmac_f32_e32 v175, v151, v170
	v_mfma_f32_16x16x32_bf16 v[170:173], v[120:123], v[144:147], v[178:181]
	s_nop 0
	v_permlane16_swap_b32_e32 v174, v175
	v_mfma_f32_16x16x32_bf16 v[178:181], v[116:119], v[152:155], 0
	s_nop 4
	v_max_f32_e32 v171, 0, v171
	v_max_f32_e32 v170, 0, v170
	v_mul_f32_e32 v177, v149, v171
	v_fmac_f32_e32 v177, v148, v170
	v_max_f32_e32 v170, 0, v172
	v_fmac_f32_e32 v177, v150, v170
	v_max_f32_e32 v170, 0, v173
	v_fmac_f32_e32 v177, v151, v170
	v_mfma_f32_16x16x32_bf16 v[170:173], v[120:123], v[156:159], v[178:181]
	s_nop 7
	v_max_f32_e32 v171, 0, v171
	v_max_f32_e32 v170, 0, v170
	v_mul_f32_e32 v171, v149, v171
	v_fmac_f32_e32 v171, v148, v170
	v_max_f32_e32 v170, 0, v172
	v_fmac_f32_e32 v171, v150, v170
	v_max_f32_e32 v170, 0, v173
	v_fmac_f32_e32 v171, v151, v170
	s_nop 1
	v_permlane16_swap_b32_e32 v177, v171
	v_add_f32_e32 v170, v174, v175
	v_add_f32_e32 v171, v177, v171
	s_nop 1
	v_permlane32_swap_b32_e32 v170, v171
	v_add_f32_e32 v170, v170, v171
	ds_write2st64_b32 v165, v169, v170 offset0:128 offset1:192
	s_cbranch_vccnz .LBB0_1497
	s_cmp_gt_i32 s5, s6
	s_cbranch_scc1 .LBB0_1496
	v_add_co_u32_e32 v132, vcc, 0xfffff000, v166
	s_nop 1
	v_addc_co_u32_e32 v133, vcc, -1, v167, vcc
	global_load_dwordx4 v[124:127], v[132:133], off offset:-2112
	global_load_dwordx4 v[128:131], v[132:133], off offset:-2048
	s_nop 0
	global_load_dwordx4 v[132:135], v[132:133], off offset:-64
	s_nop 0
	global_load_dwordx4 v[136:139], v[166:167], off offset:-4096
	global_load_dwordx4 v[140:143], v[166:167], off offset:-2112
	global_load_dwordx4 v[144:147], v[166:167], off offset:-2048
	global_load_dwordx4 v[152:155], v[166:167], off offset:-64
	global_load_dwordx4 v[156:159], v[166:167], off
	s_branch .LBB0_1496

; #define LDK(DST, KQ) _Pragma("unroll") for (int kc = 0; kc < 4; ++kc) DST[kc] = *(const bf16x8*)(Ks + ((KQ) * 16 + fr) * 136 + kc * 32 + fq * 8)
; DEVINL void attn_item(const Params& p, int item, char* smem, int wv) {
;     ...
;   const size_t qtok = (size_t)b * SEQ + q0 + wid * 16 + fr;
;   bf16x8 qf[2][4];
; #pragma unroll
;   for (int hh = 0; hh < 2; ++hh)
; #pragma unroll
;     for (int kc = 0; kc < 4; ++kc)
;       qf[hh][kc] = *(const bf16x8*)(hb + qtok * HS + 2560 + (kvh * 2 + hh) * 128 + kc * 32 + fq * 8);
;   f32x4 o[2][8];
; #pragma unroll
;   for (int hh = 0; hh < 2; ++hh)
; #pragma unroll
;     for (int dt = 0; dt < 8; ++dt) o[hh][dt] = f32x4{0.f, 0.f, 0.f, 0.f};
;   float mrun[2] = {0.f, 0.f}, lsum[2] = {0.f, 0.f};
;   unsigned long long mw_next = bits[qtok * 64];
;   u32x4 rk[2], rv[2];
;   const u16* kg = hb + ((size_t)b * SEQ + (tid >> 4)) * HS + 3584 + kvh * 128 + (tid & 15) * 8;
;   const u16* vg = vT + ((size_t)(b * 4 + kvh) * 128 + (tid >> 3)) * SEQ + (tid & 7) * 8;
; #pragma unroll
;   for (int i = 0; i < 2; ++i) {
;     rk[i] = *(const u32x4*)(kg + (size_t)(32 * i) * HS);
;     rv[i] = *(const u32x4*)(vg + (size_t)(64 * i) * SEQ);
;   }
;   for (int kt = 0; kt < ntile; ++kt) {
; #pragma unroll
;     for (int i = 0; i < 2; ++i) {
;       *(u32x4*)(Ks + ((tid >> 4) + 32 * i) * 136 + (tid & 15) * 8) = rk[i];
;       *(u32x4*)(Vs + ((tid >> 3) + 64 * i) * 72 + (tid & 7) * 8) = rv[i];
;     }
;     __syncthreads();
;     if (kt + 1 < ntile) {
; #pragma unroll
;       for (int i = 0; i < 2; ++i) {
;         rk[i] = *(const u32x4*)(kg + (size_t)((kt + 1) * 64 + 32 * i) * HS);
;         rv[i] = *(const u32x4*)(vg + (size_t)(64 * i) * SEQ + (kt + 1) * 64);
;       }
;     }
;     const unsigned long long mw = mw_next;
;     if (kt + 1 < ntile) mw_next = bits[qtok * 64 + kt + 1];
;     if (kt * 64 <= qlast) {
;     f32x4 s[2][4];
;     bf16x8 kfa[4], kfb[4];
;     bf16x8 vfa[2], vfb[2];
;     ...
;     LDK(kfa, 0);
;     LDK(kfb, 1); MMS(kfa, 0);
;     LDK(kfa, 2); MMS(kfb, 1);
;     LDK(kfb, 3); MMS(kfa, 2);
;     LDV(vfa, 0); MMS(kfb, 3);
.Lprio_skip_a1:
	s_and_b32 s34, s3, 0x3000
	v_and_b32_e32 v60, 15, v120
	s_and_b32 s2, s7, -16
	s_add_i32 s10, s6, s34
	s_ashr_i32 s3, s2, 31
	v_or_b32_e32 v0, s10, v60
	v_lshl_add_u64 v[156:157], v[0:1], 0, s[2:3]
	v_mov_b64_e32 v[2:3], s[62:63]
	v_mad_u64_u32 v[4:5], s[2:3], v156, s22, v[2:3]
	s_and_b32 s5, s1, 3
	v_mad_i32_i24 v5, v157, s22, v5
	v_and_b32_e32 v0, 48, v120
	v_lshl_add_u64 v[4:5], v[4:5], 0, v[0:1]
	s_lshl_b32 s10, s5, 9
	v_ashrrev_i32_e32 v14, 4, v120
	v_lshl_add_u64 v[8:9], v[4:5], 0, s[10:11]
	v_add_u32_e32 v4, s34, v14
	s_lshl_b32 s18, s5, 8
	s_mov_b32 s19, s11
	v_mad_i64_i32 v[2:3], s[2:3], v4, s22, v[2:3]
	v_lshlrev_b32_e32 v6, 4, v120
	v_lshl_add_u64 v[2:3], v[2:3], 0, s[18:19]
	v_and_b32_e32 v10, 0xf0, v6
	v_mov_b32_e32 v11, v1
	v_lshl_add_u64 v[116:117], v[2:3], 0, v[10:11]
	s_lshl_b32 s1, s1, 7
	v_ashrrev_i32_e32 v2, 3, v120
	s_and_b32 s10, s1, 0x780
	v_ashrrev_i32_e32 v3, 31, v2
	v_lshl_add_u64 v[4:5], v[2:3], 0, s[10:11]
	v_lshlrev_b64 v[4:5], 13, v[4:5]
	v_lshl_add_u64 v[4:5], s[40:41], 0, v[4:5]
	v_and_b32_e32 v12, 0x70, v6
	v_mov_b32_e32 v13, v1
	v_lshl_add_u64 v[158:159], v[4:5], 0, v[12:13]
	v_add_co_u32_e32 v4, vcc, s23, v116
	global_load_dwordx4 v[36:39], v[158:159], off
	s_nop 0
	v_addc_co_u32_e32 v5, vcc, 0, v117, vcc
	v_add_co_u32_e32 v6, vcc, s24, v116
	v_mul_lo_u32 v2, v2, s27
	s_nop 0
	v_addc_co_u32_e32 v7, vcc, 0, v117, vcc
	global_load_dwordx4 v[40:43], v[4:5], off offset:3072
	global_load_dwordx4 v[44:47], v[6:7], off offset:3072
	v_add_co_u32_e32 v52, vcc, s25, v158
	v_add_u32_e32 v11, 0, v12
	s_nop 0
	v_addc_co_u32_e32 v53, vcc, 0, v159, vcc
	global_load_dwordx4 v[48:51], v[52:53], off
	v_mul_lo_u32 v3, v14, s26
	v_add_u32_e32 v10, 0, v10
	v_and_b32_e32 v173, 64, v12
	v_bfe_u32 v11, v12, 4, 1
	v_lshl_or_b32 v173, v11, 5, v173
	v_bfe_u32 v11, v12, 5, 1
	v_lshl_or_b32 v173, v11, 3, v173
	v_add_u32_e32 v173, v173, v2
	v_add_co_u32_e64 v2, s[2:3], s23, v8
	v_lshl_add_u64 v[28:29], v[8:9], 0, s[12:13]
	v_add_u32_e32 v172, v10, v3
	v_lshlrev_b64 v[118:119], 9, v[156:157]
	v_add_co_u32_e32 v54, vcc, 0xa1000, v116
	v_addc_co_u32_e64 v3, s[2:3], 0, v9, s[2:3]
	global_load_dwordx4 v[4:7], v[28:29], off offset:64
	v_lshl_add_u64 v[56:57], s[38:39], 0, v[118:119]
	v_addc_co_u32_e32 v55, vcc, 0, v117, vcc
	global_load_dwordx4 v[8:11], v[28:29], off offset:128
	global_load_dwordx4 v[12:15], v[28:29], off offset:192
	global_load_dwordx4 v[16:19], v[28:29], off offset:256
	global_load_dwordx4 v[20:23], v[28:29], off offset:320
	global_load_dwordx4 v[24:27], v[28:29], off offset:384
	s_nop 0
	global_load_dwordx4 v[28:31], v[28:29], off offset:448
	s_nop 0
	global_load_dwordx4 v[32:35], v[2:3], off offset:1024
	s_nop 0
	global_load_dwordx2 v[2:3], v[56:57], off
	v_add_co_u32_e32 v58, vcc, 0xf1000, v116
	s_add_i32 s1, s7, s6
	s_nop 0
	v_addc_co_u32_e32 v59, vcc, 0, v117, vcc
	s_cmp_gt_i32 s1, -1
	s_mov_b64 s[2:3], -1
	s_waitcnt vmcnt(11)
	ds_write_b128 v172, v[40:43]
	ds_write_b64 v173, v[36:37] offset:17408
	ds_write_b64 v173, v[38:39] offset:17424
	s_waitcnt vmcnt(10)
	ds_write_b128 v172, v[44:47] offset:8704
	s_waitcnt vmcnt(9)
	ds_write_b64 v173, v[48:49] offset:26624
	ds_write_b64 v173, v[50:51] offset:26640
	s_waitcnt lgkmcnt(0)
	s_barrier
	global_load_dwordx4 v[44:47], v[58:59], off offset:3072
	global_load_dwordx4 v[36:39], v[54:55], off offset:3072
	global_load_dwordx4 v[48:51], v[52:53], off offset:128
	global_load_dwordx4 v[40:43], v[158:159], off offset:128
	global_load_dwordx2 v[162:163], v[56:57], off offset:8
	v_mad_u32_u24 v52, v60, s26, 0
	v_lshlrev_b32_e32 v53, 7, v60
	v_lshrrev_b32_e32 v54, 2, v120
	v_sub_u32_e32 v53, v52, v53
	v_and_b32_e32 v174, 12, v54
	v_add_u32_e32 v175, v52, v0
	v_lshl_add_u32 v177, v174, 2, v53
	s_cbranch_scc0 .LBB0_1726
	ds_read_b128 v[52:55], v175
	ds_read_b128 v[56:59], v175 offset:64
	ds_read_b128 v[60:63], v175 offset:128
	ds_read_b128 v[64:67], v175 offset:192
	ds_read_b128 v[68:71], v175 offset:4352
	ds_read_b128 v[72:75], v175 offset:4416
	ds_read_b128 v[76:79], v175 offset:4480
	ds_read_b128 v[80:83], v175 offset:4544
	s_mov_b32 s6, s4
	s_mov_b32 s7, s4
	s_mov_b32 s5, s4
	v_mov_b64_e32 v[86:87], s[6:7]
	v_mov_b64_e32 v[84:85], s[4:5]
	s_waitcnt vmcnt(6) lgkmcnt(7)
	s_nop 0
	v_mfma_f32_16x16x32_bf16 v[88:91], v[52:55], v[32:35], v[84:87]
	v_mfma_f32_16x16x32_bf16 v[52:55], v[52:55], v[16:19], v[84:87]
	s_waitcnt lgkmcnt(6)
	v_mfma_f32_16x16x32_bf16 v[88:91], v[56:59], v[4:7], v[88:91]
	v_mfma_f32_16x16x32_bf16 v[52:55], v[56:59], v[20:23], v[52:55]
	s_waitcnt lgkmcnt(5)
	v_mfma_f32_16x16x32_bf16 v[56:59], v[60:63], v[8:11], v[88:91]
	v_mfma_f32_16x16x32_bf16 v[52:55], v[60:63], v[24:27], v[52:55]
	s_waitcnt lgkmcnt(4)
	v_mfma_f32_16x16x32_bf16 v[60:63], v[64:67], v[12:15], v[56:59]
	v_mfma_f32_16x16x32_bf16 v[64:67], v[64:67], v[28:31], v[52:55]
	s_nop 3
	ds_read_b128 v[52:55], v175 offset:8704
	ds_read_b128 v[56:59], v175 offset:8768
	ds_read_b128 v[88:91], v175 offset:8832
	ds_read_b128 v[92:95], v175 offset:8896
	s_waitcnt lgkmcnt(7)
	v_mfma_f32_16x16x32_bf16 v[96:99], v[68:71], v[32:35], v[84:87]
	v_mfma_f32_16x16x32_bf16 v[68:71], v[68:71], v[16:19], v[84:87]
	s_waitcnt lgkmcnt(6)
	v_mfma_f32_16x16x32_bf16 v[96:99], v[72:75], v[4:7], v[96:99]
	v_mfma_f32_16x16x32_bf16 v[68:71], v[72:75], v[20:23], v[68:71]
	s_waitcnt lgkmcnt(5)
	v_mfma_f32_16x16x32_bf16 v[72:75], v[76:79], v[8:11], v[96:99]
	v_mfma_f32_16x16x32_bf16 v[68:71], v[76:79], v[24:27], v[68:71]
	s_waitcnt lgkmcnt(4)
	v_mfma_f32_16x16x32_bf16 v[72:75], v[80:83], v[12:15], v[72:75]
	v_mfma_f32_16x16x32_bf16 v[68:71], v[80:83], v[28:31], v[68:71]
	ds_read_b128 v[76:79], v175 offset:13056
	ds_read_b128 v[80:83], v175 offset:13120
	ds_read_b128 v[96:99], v175 offset:13184
	ds_read_b128 v[100:103], v175 offset:13248
	s_waitcnt lgkmcnt(7)
; DEVINL void attn_item(const Params& p, int item, char* smem, int wv) {
;     ...
;     LDK(kfb, 1); MMS(kfa, 0);
;     LDK(kfa, 2); MMS(kfb, 1);
;     LDK(kfb, 3); MMS(kfa, 2);
;     LDV(vfa, 0); MMS(kfb, 3);
;     bf16x8 pf[2][2];
;     {
;       const unsigned long long msh = mw >> (fq * 4);
;       const int mlo = (int)(unsigned)msh, mhi = (int)(unsigned)(msh >> 32);
;       int mk[4][4];
; #pragma unroll
;       for (int j = 0; j < 4; ++j) {
;         mk[0][j] = __builtin_amdgcn_sbfe(mlo, j, 1); mk[1][j] = __builtin_amdgcn_sbfe(mlo, 16 + j, 1);
;         mk[2][j] = __builtin_amdgcn_sbfe(mhi, j, 1); mk[3][j] = __builtin_amdgcn_sbfe(mhi, 16 + j, 1);
;       }
; #pragma unroll
;       for (int hh = 0; hh < 2; ++hh) {
;         float mx = s[hh][0][0];
; #pragma unroll
;         for (int kq = 0; kq < 4; ++kq)
; #pragma unroll
;           for (int j = 0; j < 4; ++j) mx = fmaxf(mx, s[hh][kq][j]);
;         {
;           auto r1 = __builtin_amdgcn_permlane16_swap(__float_as_uint(mx), __float_as_uint(mx), false, false);
;           mx = fmaxf(__uint_as_float(r1[0]), __uint_as_float(r1[1]));
;           auto r2 = __builtin_amdgcn_permlane32_swap(__float_as_uint(mx), __float_as_uint(mx), false, false);
;           mx = fmaxf(__uint_as_float(r2[0]), __uint_as_float(r2[1]));
;         }
;         if (kt == 0 || __ballot(mx > 8.f)) {
;           const float delta = (kt == 0) ? mx : fmaxf(mx, 0.f);
;           const float alpha = fexp2(-delta);
;           mrun[hh] += delta;
;           lsum[hh] *= alpha;
; #pragma unroll
;           for (int dt = 0; dt < 8; ++dt) o[hh][dt] *= alpha;
; #pragma unroll
;           for (int kq = 0; kq < 4; ++kq)
; #pragma unroll
;             for (int j = 0; j < 4; ++j) s[hh][kq][j] -= delta;
;         }
;         float ps = 0.f;
;         float pv[4][4];
; #pragma unroll
;         for (int kq = 0; kq < 4; ++kq)
; #pragma unroll
;           for (int j = 0; j < 4; ++j) {
;             pv[kq][j] = __uint_as_float(__float_as_uint(fexp2(s[hh][kq][j])) & (unsigned)mk[kq][j]);
;             ps += pv[kq][j];
;           }
; #pragma unroll
;         for (int c2 = 0; c2 < 2; ++c2) {
;           u32x4 pw;
;           pw[0] = pk2(pv[2 * c2][0], pv[2 * c2][1]); pw[1] = pk2(pv[2 * c2][2], pv[2 * c2][3]);
;           pw[2] = pk2(pv[2 * c2 + 1][0], pv[2 * c2 + 1][1]); pw[3] = pk2(pv[2 * c2 + 1][2], pv[2 * c2 + 1][3]);
;           pf[hh][c2] = *(bf16x8*)&pw;
	v_mfma_f32_16x16x32_bf16 v[104:107], v[52:55], v[32:35], v[84:87]
	v_mfma_f32_16x16x32_bf16 v[52:55], v[52:55], v[16:19], v[84:87]
	s_waitcnt lgkmcnt(6)
	v_mfma_f32_16x16x32_bf16 v[104:107], v[56:59], v[4:7], v[104:107]
	v_mfma_f32_16x16x32_bf16 v[52:55], v[56:59], v[20:23], v[52:55]
	s_waitcnt lgkmcnt(5)
	v_mfma_f32_16x16x32_bf16 v[56:59], v[88:91], v[8:11], v[104:107]
	v_mfma_f32_16x16x32_bf16 v[52:55], v[88:91], v[24:27], v[52:55]
	s_waitcnt lgkmcnt(4)
	v_mfma_f32_16x16x32_bf16 v[88:91], v[92:95], v[12:15], v[56:59]
	v_mfma_f32_16x16x32_bf16 v[92:95], v[92:95], v[28:31], v[52:55]
	s_nop 0
	s_nop 2
	ds_read_b128 v[52:55], v177 offset:17408
	ds_read_b128 v[56:59], v177 offset:17472
	s_waitcnt lgkmcnt(5)
	v_mfma_f32_16x16x32_bf16 v[104:107], v[76:79], v[32:35], v[84:87]
	v_mfma_f32_16x16x32_bf16 v[76:79], v[76:79], v[16:19], v[84:87]
	s_waitcnt lgkmcnt(4)
	v_mfma_f32_16x16x32_bf16 v[84:87], v[80:83], v[4:7], v[104:107]
	v_mfma_f32_16x16x32_bf16 v[76:79], v[80:83], v[20:23], v[76:79]
	s_waitcnt lgkmcnt(3)
	v_mfma_f32_16x16x32_bf16 v[80:83], v[96:99], v[8:11], v[84:87]
	v_mfma_f32_16x16x32_bf16 v[76:79], v[96:99], v[24:27], v[76:79]
	s_waitcnt lgkmcnt(2)
	v_mfma_f32_16x16x32_bf16 v[80:83], v[100:103], v[12:15], v[80:83]
	v_mfma_f32_16x16x32_bf16 v[76:79], v[100:103], v[28:31], v[76:79]
	s_waitcnt vmcnt(5)
	v_lshrrev_b64 v[2:3], v174, v[2:3]
	v_bfe_i32 v0, v2, 0, 1
	v_bfe_i32 v86, v2, 16, 1
	v_bfe_i32 v87, v3, 0, 1
	v_bfe_i32 v96, v3, 16, 1
	v_bfe_i32 v97, v2, 1, 1
	v_bfe_i32 v98, v2, 17, 1
	v_bfe_i32 v99, v3, 1, 1
	v_bfe_i32 v104, v3, 17, 1
	v_bfe_i32 v100, v2, 2, 1
	v_bfe_i32 v101, v2, 18, 1
	v_bfe_i32 v105, v3, 2, 1
	v_bfe_i32 v106, v3, 18, 1
	v_bfe_i32 v102, v2, 3, 1
	v_bfe_i32 v103, v2, 19, 1
	v_bfe_i32 v107, v3, 3, 1
	v_bfe_i32 v108, v3, 19, 1
	v_max_f32_e32 v3, v60, v60
	v_max_f32_e32 v2, v3, v61
	v_max3_f32 v2, v2, v62, v63
	v_max3_f32 v2, v2, v72, v73
	v_max3_f32 v2, v2, v74, v75
	v_max3_f32 v2, v2, v88, v89
	v_max3_f32 v2, v2, v90, v91
	v_max3_f32 v2, v2, v80, v81
	v_max3_f32 v2, v2, v82, v83
	v_mov_b32_e32 v3, v2
	s_nop 1
	v_permlane16_swap_b32_e32 v2, v3
	v_max_f32_e32 v2, v2, v3
	v_mov_b32_e32 v3, v2
	s_nop 1
	v_permlane32_swap_b32_e32 v2, v3
	v_max_f32_e32 v3, v2, v3
	v_sub_f32_e32 v2, v80, v3
	v_sub_f32_e32 v61, v61, v3
	v_sub_f32_e32 v80, v81, v3
	v_sub_f32_e32 v81, v82, v3
	v_sub_f32_e32 v82, v83, v3
	v_sub_f32_e32 v83, v88, v3
	v_sub_f32_e32 v88, v90, v3
	v_exp_f32_e32 v90, v61
	v_exp_f32_e32 v115, v2
	v_max_f32_e32 v61, v64, v64
	v_max_f32_e32 v2, v61, v65
	v_max3_f32 v2, v2, v66, v67
	v_max3_f32 v2, v2, v68, v69
	v_max3_f32 v2, v2, v70, v71
	v_max3_f32 v2, v2, v92, v93
	v_max3_f32 v2, v2, v94, v95
	v_max3_f32 v2, v2, v76, v77
	v_max3_f32 v2, v2, v78, v79
	v_mov_b32_e32 v61, v2
	s_nop 1
	v_permlane16_swap_b32_e32 v2, v61
	v_max_f32_e32 v2, v2, v61
	v_mov_b32_e32 v61, v2
	s_nop 1
	v_permlane32_swap_b32_e32 v2, v61
	v_max_f32_e32 v2, v2, v61
	v_sub_f32_e32 v60, v60, v3
	v_sub_f32_e32 v64, v64, v2
	v_exp_f32_e32 v60, v60
	v_sub_f32_e32 v65, v65, v2
	v_exp_f32_e32 v64, v64
	v_sub_f32_e32 v62, v62, v3
	v_sub_f32_e32 v66, v66, v2
	v_exp_f32_e32 v65, v65
	v_sub_f32_e32 v85, v89, v3
	v_sub_f32_e32 v89, v91, v3
	v_sub_f32_e32 v63, v63, v3
	v_exp_f32_e32 v91, v62
	v_sub_f32_e32 v67, v67, v2
	v_exp_f32_e32 v66, v66
	v_sub_f32_e32 v72, v72, v3
	v_exp_f32_e32 v109, v63
	v_sub_f32_e32 v61, v68, v2
	v_sub_f32_e32 v62, v69, v2
	v_exp_f32_e32 v67, v67
	v_sub_f32_e32 v73, v73, v3
	v_exp_f32_e32 v72, v72
	v_exp_f32_e32 v113, v83
	v_exp_f32_e32 v125, v82
	v_sub_f32_e32 v82, v92, v2
	v_sub_f32_e32 v83, v93, v2
	v_sub_f32_e32 v63, v70, v2
	v_sub_f32_e32 v68, v71, v2
	v_exp_f32_e32 v70, v61
	v_exp_f32_e32 v71, v62
	v_and_b32_e32 v61, v0, v64
	v_and_b32_e32 v60, v0, v60
	v_and_b32_e32 v62, v97, v90
	v_sub_f32_e32 v74, v74, v3
	v_exp_f32_e32 v110, v73
	v_exp_f32_e32 v121, v80
	v_exp_f32_e32 v124, v81
	v_sub_f32_e32 v122, v76, v2
	v_sub_f32_e32 v126, v78, v2
	v_exp_f32_e32 v76, v63
	v_exp_f32_e32 v78, v68
	v_and_b32_e32 v63, v97, v65
	v_cvt_pk_bf16_f32 v68, v60, v62
	v_pk_add_f32 v[80:81], v[60:61], 0 op_sel_hi:[1,0]
	v_exp_f32_e32 v0, v82
	v_exp_f32_e32 v60, v83
	v_sub_f32_e32 v75, v75, v3
	v_exp_f32_e32 v111, v74
	v_and_b32_e32 v65, v100, v66
	v_and_b32_e32 v64, v100, v91
	v_pk_add_f32 v[80:81], v[80:81], v[62:63]
	v_exp_f32_e32 v112, v75
	v_and_b32_e32 v67, v102, v67
	v_and_b32_e32 v66, v102, v109
	v_pk_add_f32 v[80:81], v[80:81], v[64:65]
	v_sub_f32_e32 v93, v95, v2
	v_and_b32_e32 v73, v86, v70
	v_and_b32_e32 v72, v86, v72
	v_pk_add_f32 v[80:81], v[80:81], v[66:67]
	v_exp_f32_e32 v114, v85
	v_sub_f32_e32 v92, v94, v2
	v_and_b32_e32 v75, v98, v71
	v_and_b32_e32 v74, v98, v110
	v_pk_add_f32 v[80:81], v[80:81], v[72:73]
	v_and_b32_e32 v83, v87, v0
	v_and_b32_e32 v82, v87, v113
	v_and_b32_e32 v87, v99, v60
	v_exp_f32_e32 v60, v93
	v_exp_f32_e32 v88, v88
	v_sub_f32_e32 v123, v77, v2
	v_and_b32_e32 v77, v101, v76
	v_and_b32_e32 v76, v101, v111
	v_pk_add_f32 v[80:81], v[80:81], v[74:75]
	v_exp_f32_e32 v0, v92
	v_exp_f32_e32 v89, v89
	v_sub_f32_e32 v127, v79, v2
	v_and_b32_e32 v79, v103, v78
	v_and_b32_e32 v78, v103, v112
	v_pk_add_f32 v[80:81], v[80:81], v[76:77]
	v_exp_f32_e32 v62, v122
	v_pk_add_f32 v[80:81], v[80:81], v[78:79]
	v_cvt_pk_bf16_f32 v69, v64, v66
	v_and_b32_e32 v86, v99, v114
	v_exp_f32_e32 v64, v123
	v_cvt_pk_bf16_f32 v100, v61, v63
	v_cvt_pk_bf16_f32 v102, v73, v75
	v_and_b32_e32 v75, v107, v60
	v_pk_add_f32 v[60:61], v[80:81], v[82:83]
	v_cvt_pk_bf16_f32 v70, v72, v74
	v_exp_f32_e32 v66, v126
	v_and_b32_e32 v73, v105, v0
	v_and_b32_e32 v72, v105, v88
	v_pk_add_f32 v[60:61], v[60:61], v[86:87]
	v_exp_f32_e32 v90, v127
	v_and_b32_e32 v74, v107, v89
	v_pk_add_f32 v[60:61], v[60:61], v[72:73]
	v_cvt_pk_bf16_f32 v71, v76, v78
	v_cvt_pk_bf16_f32 v103, v77, v79
	v_and_b32_e32 v77, v96, v62
	v_and_b32_e32 v76, v96, v115
	v_pk_add_f32 v[60:61], v[60:61], v[74:75]
	v_and_b32_e32 v79, v104, v64
	v_and_b32_e32 v78, v104, v121
	v_pk_add_f32 v[60:61], v[60:61], v[76:77]
	v_and_b32_e32 v89, v106, v66
	v_and_b32_e32 v88, v106, v124
	v_pk_add_f32 v[60:61], v[60:61], v[78:79]
	v_and_b32_e32 v91, v108, v90
	v_and_b32_e32 v90, v108, v125
	v_pk_add_f32 v[60:61], v[60:61], v[88:89]
	s_nop 0
	v_exp_f32_e64 v84, -v3
	v_exp_f32_e64 v85, -v2
	v_cvt_pk_bf16_f32 v101, v65, v67
	v_pk_add_f32 v[80:81], v[60:61], v[90:91]
	ds_read_b128 v[60:63], v177 offset:19712
	ds_read_b128 v[64:67], v177 offset:19776
	v_pk_add_f32 v[2:3], v[2:3], 0 op_sel_hi:[1,0]
	v_pk_mul_f32 v[122:123], v[84:85], 0 op_sel_hi:[1,0]
	v_pk_fma_f32 v[160:161], v[84:85], 0, v[80:81] op_sel_hi:[1,0,1]
	v_mov_b32_e32 v126, v122
	v_mov_b32_e32 v127, v122
	v_mov_b32_e32 v128, v122
	v_mov_b32_e32 v129, v122
	v_cvt_pk_bf16_f32 v130, v82, v86
	v_cvt_pk_bf16_f32 v131, v72, v74
	v_cvt_pk_bf16_f32 v132, v76, v78
	v_cvt_pk_bf16_f32 v133, v88, v90
	v_mov_b32_e32 v122, v123
	v_mov_b32_e32 v124, v123
	v_mov_b32_e32 v125, v123
	v_cvt_pk_bf16_f32 v134, v83, v87
	v_cvt_pk_bf16_f32 v135, v73, v75
	v_cvt_pk_bf16_f32 v136, v77, v79
	v_cvt_pk_bf16_f32 v137, v89, v91
	s_waitcnt lgkmcnt(3)
; #define MMV(SRC, DT) do { __builtin_amdgcn_s_setprio(1); _Pragma("unroll") for (int c2 = 0; c2 < 2; ++c2) { o[0][DT] = mfma16(SRC[c2], pf[0][c2], o[0][DT]); o[1][DT] = mfma16(SRC[c2], pf[1][c2], o[1][DT]); } __builtin_amdgcn_s_setprio(0); } while (0)
; DEVINL void attn_item(const Params& p, int item, char* smem, int wv) {
;     ...
;     LDV(vfb, 1); MMV(vfa, 0);
;     LDV(vfa, 2); MMV(vfb, 1);
;     LDV(vfb, 3); MMV(vfa, 2);
;     LDV(vfa, 4); MMV(vfb, 3);
;     LDV(vfb, 5); MMV(vfa, 4);
;     LDV(vfa, 6); MMV(vfb, 5);
;     LDV(vfb, 7); MMV(vfa, 6);
;     MMV(vfb, 7);
	v_mfma_f32_16x16x32_bf16 v[72:75], v[52:55], v[68:71], v[126:129]
	v_mfma_f32_16x16x32_bf16 v[52:55], v[52:55], v[100:103], v[122:125]
	s_waitcnt lgkmcnt(2)
	v_mfma_f32_16x16x32_bf16 v[88:91], v[56:59], v[130:133], v[72:75]
	v_mfma_f32_16x16x32_bf16 v[52:55], v[56:59], v[134:137], v[52:55]
	s_nop 0
	s_nop 1
	ds_read_b128 v[72:75], v177 offset:22016
	ds_read_b128 v[76:79], v177 offset:22080
	s_waitcnt lgkmcnt(3)
	v_mfma_f32_16x16x32_bf16 v[56:59], v[60:63], v[68:71], v[126:129]
	v_mfma_f32_16x16x32_bf16 v[60:63], v[60:63], v[100:103], v[122:125]
	s_waitcnt lgkmcnt(2)
	v_mfma_f32_16x16x32_bf16 v[84:87], v[64:67], v[130:133], v[56:59]
	v_mfma_f32_16x16x32_bf16 v[56:59], v[64:67], v[134:137], v[60:63]
	s_nop 0
	ds_read_b128 v[64:67], v177 offset:24320
	ds_read_b128 v[80:83], v177 offset:24384
	s_waitcnt lgkmcnt(3)
	v_mfma_f32_16x16x32_bf16 v[60:63], v[72:75], v[68:71], v[126:129]
	v_mfma_f32_16x16x32_bf16 v[72:75], v[72:75], v[100:103], v[122:125]
	s_waitcnt lgkmcnt(2)
	v_mfma_f32_16x16x32_bf16 v[92:95], v[76:79], v[130:133], v[60:63]
	v_mfma_f32_16x16x32_bf16 v[60:63], v[76:79], v[134:137], v[72:75]
	s_nop 0
	s_nop 2
	ds_read_b128 v[72:75], v177 offset:26624
	ds_read_b128 v[76:79], v177 offset:26688
	s_waitcnt lgkmcnt(3)
	v_mfma_f32_16x16x32_bf16 v[96:99], v[64:67], v[68:71], v[126:129]
	v_mfma_f32_16x16x32_bf16 v[64:67], v[64:67], v[100:103], v[122:125]
	s_waitcnt lgkmcnt(2)
	v_mfma_f32_16x16x32_bf16 v[96:99], v[80:83], v[130:133], v[96:99]
	v_mfma_f32_16x16x32_bf16 v[64:67], v[80:83], v[134:137], v[64:67]
	s_nop 0
	ds_read_b128 v[80:83], v177 offset:28928
	ds_read_b128 v[112:115], v177 offset:28992
	s_waitcnt lgkmcnt(3)
	v_mfma_f32_16x16x32_bf16 v[104:107], v[72:75], v[68:71], v[126:129]
	v_mfma_f32_16x16x32_bf16 v[72:75], v[72:75], v[100:103], v[122:125]
	s_waitcnt lgkmcnt(2)
	v_mfma_f32_16x16x32_bf16 v[104:107], v[76:79], v[130:133], v[104:107]
	v_mfma_f32_16x16x32_bf16 v[72:75], v[76:79], v[134:137], v[72:75]
	s_nop 0
	ds_read_b128 v[138:141], v177 offset:31232
	ds_read_b128 v[142:145], v177 offset:31296
	s_waitcnt lgkmcnt(3)
	v_mfma_f32_16x16x32_bf16 v[76:79], v[80:83], v[68:71], v[126:129]
	v_mfma_f32_16x16x32_bf16 v[80:83], v[80:83], v[100:103], v[122:125]
	s_waitcnt lgkmcnt(2)
	v_mfma_f32_16x16x32_bf16 v[108:111], v[112:115], v[130:133], v[76:79]
	v_mfma_f32_16x16x32_bf16 v[76:79], v[112:115], v[134:137], v[80:83]
	s_nop 0
	ds_read_b128 v[146:149], v177 offset:33536
	ds_read_b128 v[150:153], v177 offset:33600
	s_waitcnt lgkmcnt(3)
	v_mfma_f32_16x16x32_bf16 v[80:83], v[138:141], v[68:71], v[126:129]
	v_mfma_f32_16x16x32_bf16 v[138:141], v[138:141], v[100:103], v[122:125]
	s_waitcnt lgkmcnt(2)
	v_mfma_f32_16x16x32_bf16 v[112:115], v[142:145], v[130:133], v[80:83]
	v_mfma_f32_16x16x32_bf16 v[80:83], v[142:145], v[134:137], v[138:141]
	s_waitcnt lgkmcnt(1)
	v_mfma_f32_16x16x32_bf16 v[68:71], v[146:149], v[68:71], v[126:129]
	v_mfma_f32_16x16x32_bf16 v[122:125], v[146:149], v[100:103], v[122:125]
	s_waitcnt lgkmcnt(0)
	v_mfma_f32_16x16x32_bf16 v[100:103], v[150:153], v[130:133], v[68:71]
	v_mfma_f32_16x16x32_bf16 v[68:71], v[150:153], v[134:137], v[122:125]
	s_cbranch_execz .LBB0_1727
	s_branch .LBB0_1728

; DEVINL float fexp2(float x) { return __builtin_amdgcn_exp2f(x); }
; #define LDK(DST, KQ) _Pragma("unroll") for (int kc = 0; kc < 4; ++kc) DST[kc] = *(const bf16x8*)(Ks + ((KQ) * 16 + fr) * 136 + kc * 32 + fq * 8)
; DEVINL void attn_item(const Params& p, int item, char* smem, int wv) {
;     ...
;     if (kt * 64 <= qlast) {
;     f32x4 s[2][4];
;     bf16x8 kfa[4], kfb[4];
;     bf16x8 vfa[2], vfb[2];
;     ...
;     LDK(kfa, 0);
;     LDK(kfb, 1); MMS(kfa, 0);
;     LDK(kfa, 2); MMS(kfb, 1);
;     LDK(kfb, 3); MMS(kfa, 2);
;     LDV(vfa, 0); MMS(kfb, 3);
;     bf16x8 pf[2][2];
;     {
;       const unsigned long long msh = mw >> (fq * 4);
;       const int mlo = (int)(unsigned)msh, mhi = (int)(unsigned)(msh >> 32);
;       int mk[4][4];
; #pragma unroll
;       for (int j = 0; j < 4; ++j) {
;         mk[0][j] = __builtin_amdgcn_sbfe(mlo, j, 1); mk[1][j] = __builtin_amdgcn_sbfe(mlo, 16 + j, 1);
;         mk[2][j] = __builtin_amdgcn_sbfe(mhi, j, 1); mk[3][j] = __builtin_amdgcn_sbfe(mhi, 16 + j, 1);
;       }
; #pragma unroll
;       for (int hh = 0; hh < 2; ++hh) {
;         float mx = s[hh][0][0];
; #pragma unroll
;         for (int kq = 0; kq < 4; ++kq)
; #pragma unroll
;           for (int j = 0; j < 4; ++j) mx = fmaxf(mx, s[hh][kq][j]);
;         {
;           auto r1 = __builtin_amdgcn_permlane16_swap(__float_as_uint(mx), __float_as_uint(mx), false, false);
;           mx = fmaxf(__uint_as_float(r1[0]), __uint_as_float(r1[1]));
;           auto r2 = __builtin_amdgcn_permlane32_swap(__float_as_uint(mx), __float_as_uint(mx), false, false);
;           mx = fmaxf(__uint_as_float(r2[0]), __uint_as_float(r2[1]));
;         }
;         if (kt == 0 || __ballot(mx > 8.f)) {
;           const float delta = (kt == 0) ? mx : fmaxf(mx, 0.f);
;           const float alpha = fexp2(-delta);
;           mrun[hh] += delta;
;           lsum[hh] *= alpha;
; #pragma unroll
;           for (int dt = 0; dt < 8; ++dt) o[hh][dt] *= alpha;
; #pragma unroll
;           for (int kq = 0; kq < 4; ++kq)
; #pragma unroll
;             for (int j = 0; j < 4; ++j) s[hh][kq][j] -= delta;
.LBB0_1731:
	s_add_i32 s6, s3, 0xffffffa0
	s_cmp_gt_i32 s6, s1
	s_cbranch_scc1 .LBB0_1737
	ds_read_b128 v[116:119], v175
	ds_read_b128 v[120:123], v175 offset:64
	ds_read_b128 v[124:127], v175 offset:128
	ds_read_b128 v[128:131], v175 offset:192
	ds_read_b128 v[132:135], v175 offset:4352
	ds_read_b128 v[140:143], v175 offset:4416
	ds_read_b128 v[144:147], v175 offset:4480
	ds_read_b128 v[178:181], v175 offset:4544
	v_xor_b32_e32 v182, 0x80000000, v3
	v_xor_b32_e32 v186, 0x80000000, v2
	v_mov_b32_e32 v183, v182
	v_mov_b32_e32 v184, v182
	v_mov_b32_e32 v185, v182
	v_mov_b32_e32 v187, v186
	v_mov_b32_e32 v188, v186
	v_mov_b32_e32 v189, v186
	s_waitcnt lgkmcnt(7)
	v_mfma_f32_16x16x32_bf16 v[136:139], v[116:119], v[32:35], v[182:185]
	v_mfma_f32_16x16x32_bf16 v[116:119], v[116:119], v[16:19], v[186:189]
	s_waitcnt lgkmcnt(6)
	v_mfma_f32_16x16x32_bf16 v[136:139], v[120:123], v[4:7], v[136:139]
	v_mfma_f32_16x16x32_bf16 v[116:119], v[120:123], v[20:23], v[116:119]
	s_waitcnt lgkmcnt(5)
	v_mfma_f32_16x16x32_bf16 v[120:123], v[124:127], v[8:11], v[136:139]
	v_mfma_f32_16x16x32_bf16 v[116:119], v[124:127], v[24:27], v[116:119]
	s_waitcnt lgkmcnt(4)
	v_mfma_f32_16x16x32_bf16 v[152:155], v[128:131], v[12:15], v[120:123]
	v_mfma_f32_16x16x32_bf16 v[136:139], v[128:131], v[28:31], v[116:119]
	s_nop 3
	ds_read_b128 v[116:119], v175 offset:8704
	ds_read_b128 v[120:123], v175 offset:8768
	ds_read_b128 v[124:127], v175 offset:8832
	ds_read_b128 v[128:131], v175 offset:8896
	s_waitcnt lgkmcnt(7)
	v_mfma_f32_16x16x32_bf16 v[148:151], v[132:135], v[32:35], v[182:185]
	v_mfma_f32_16x16x32_bf16 v[132:135], v[132:135], v[16:19], v[186:189]
	s_waitcnt lgkmcnt(6)
	v_mfma_f32_16x16x32_bf16 v[148:151], v[140:143], v[4:7], v[148:151]
	v_mfma_f32_16x16x32_bf16 v[132:135], v[140:143], v[20:23], v[132:135]
	s_waitcnt lgkmcnt(5)
	v_mfma_f32_16x16x32_bf16 v[140:143], v[144:147], v[8:11], v[148:151]
	v_mfma_f32_16x16x32_bf16 v[132:135], v[144:147], v[24:27], v[132:135]
	s_waitcnt lgkmcnt(4)
	v_mfma_f32_16x16x32_bf16 v[148:151], v[178:181], v[12:15], v[140:143]
	v_mfma_f32_16x16x32_bf16 v[132:135], v[178:181], v[28:31], v[132:135]
	ds_read_b128 v[144:147], v175 offset:13056
	ds_read_b128 v[178:181], v175 offset:13120
	ds_read_b128 v[190:193], v175 offset:13184
	ds_read_b128 v[194:197], v175 offset:13248
	s_waitcnt lgkmcnt(7)
	v_mfma_f32_16x16x32_bf16 v[140:143], v[116:119], v[32:35], v[182:185]
	v_mfma_f32_16x16x32_bf16 v[116:119], v[116:119], v[16:19], v[186:189]
	s_waitcnt lgkmcnt(6)
	v_mfma_f32_16x16x32_bf16 v[140:143], v[120:123], v[4:7], v[140:143]
	v_mfma_f32_16x16x32_bf16 v[116:119], v[120:123], v[20:23], v[116:119]
	s_waitcnt lgkmcnt(5)
	v_mfma_f32_16x16x32_bf16 v[120:123], v[124:127], v[8:11], v[140:143]
	v_mfma_f32_16x16x32_bf16 v[116:119], v[124:127], v[24:27], v[116:119]
	s_waitcnt lgkmcnt(4)
	v_mfma_f32_16x16x32_bf16 v[140:143], v[128:131], v[12:15], v[120:123]
	v_mfma_f32_16x16x32_bf16 v[124:127], v[128:131], v[28:31], v[116:119]
	s_nop 2
	s_nop 0
	ds_read_b128 v[116:119], v177 offset:17408
	ds_read_b128 v[120:123], v177 offset:17472
	s_waitcnt lgkmcnt(5)
	v_mfma_f32_16x16x32_bf16 v[128:131], v[144:147], v[32:35], v[182:185]
	v_mfma_f32_16x16x32_bf16 v[144:147], v[144:147], v[16:19], v[186:189]
	s_waitcnt lgkmcnt(4)
	v_mfma_f32_16x16x32_bf16 v[128:131], v[178:181], v[4:7], v[128:131]
	v_mfma_f32_16x16x32_bf16 v[144:147], v[178:181], v[20:23], v[144:147]
	s_waitcnt lgkmcnt(3)
	v_mfma_f32_16x16x32_bf16 v[128:131], v[190:193], v[8:11], v[128:131]
	v_mfma_f32_16x16x32_bf16 v[178:181], v[190:193], v[24:27], v[144:147]
	s_waitcnt lgkmcnt(2)
	v_mfma_f32_16x16x32_bf16 v[144:147], v[194:197], v[12:15], v[128:131]
	v_mfma_f32_16x16x32_bf16 v[128:131], v[194:197], v[28:31], v[178:181]
	s_nop 3
	s_nop 0
	v_max_f32_e32 v179, v152, v152
	v_max_f32_e32 v178, v179, v153
	v_max3_f32 v178, v178, v154, v155
	v_max3_f32 v178, v178, v148, v149
	v_max3_f32 v178, v178, v150, v151
	v_max3_f32 v178, v178, v140, v141
	v_max3_f32 v178, v178, v142, v143
	v_max3_f32 v178, v178, v144, v145
	v_max3_f32 v178, v178, v146, v147
	v_mov_b32_e32 v179, v178
	s_nop 1
	v_permlane16_swap_b32_e32 v178, v179
	v_max_f32_e32 v178, v178, v179
	v_mov_b32_e32 v179, v178
	s_nop 1
	v_permlane32_swap_b32_e32 v178, v179
	v_max_f32_e32 v178, v178, v179
	v_cmp_lt_f32_e32 vcc, s28, v178
	s_cbranch_vccz .LBB0_1734
	v_max_f32_e32 v178, 0, v178
	v_exp_f32_e64 v180, -v178
	v_add_f32_e32 v3, v3, v178
	v_pk_add_f32 v[152:153], v[152:153], v[178:179] op_sel_hi:[1,0] neg_lo:[0,1] neg_hi:[0,1]
	v_pk_add_f32 v[154:155], v[154:155], v[178:179] op_sel_hi:[1,0] neg_lo:[0,1] neg_hi:[0,1]
	v_mul_f32_e32 v160, v160, v180
	v_pk_mul_f32 v[90:91], v[90:91], v[180:181] op_sel_hi:[1,0]
	v_pk_mul_f32 v[88:89], v[88:89], v[180:181] op_sel_hi:[1,0]
	v_pk_mul_f32 v[86:87], v[86:87], v[180:181] op_sel_hi:[1,0]
	v_pk_mul_f32 v[84:85], v[84:85], v[180:181] op_sel_hi:[1,0]
	v_pk_mul_f32 v[94:95], v[94:95], v[180:181] op_sel_hi:[1,0]
	v_pk_mul_f32 v[92:93], v[92:93], v[180:181] op_sel_hi:[1,0]
	v_pk_mul_f32 v[98:99], v[98:99], v[180:181] op_sel_hi:[1,0]
	v_pk_mul_f32 v[96:97], v[96:97], v[180:181] op_sel_hi:[1,0]
	v_pk_mul_f32 v[106:107], v[106:107], v[180:181] op_sel_hi:[1,0]
	v_pk_mul_f32 v[104:105], v[104:105], v[180:181] op_sel_hi:[1,0]
	v_pk_mul_f32 v[110:111], v[110:111], v[180:181] op_sel_hi:[1,0]
	v_pk_mul_f32 v[108:109], v[108:109], v[180:181] op_sel_hi:[1,0]
	v_pk_mul_f32 v[114:115], v[114:115], v[180:181] op_sel_hi:[1,0]
	v_pk_mul_f32 v[112:113], v[112:113], v[180:181] op_sel_hi:[1,0]
	v_pk_mul_f32 v[102:103], v[102:103], v[180:181] op_sel_hi:[1,0]
	v_pk_mul_f32 v[100:101], v[100:101], v[180:181] op_sel_hi:[1,0]
	v_pk_add_f32 v[148:149], v[148:149], v[178:179] op_sel_hi:[1,0] neg_lo:[0,1] neg_hi:[0,1]
	v_pk_add_f32 v[150:151], v[150:151], v[178:179] op_sel_hi:[1,0] neg_lo:[0,1] neg_hi:[0,1]
	v_pk_add_f32 v[140:141], v[140:141], v[178:179] op_sel_hi:[1,0] neg_lo:[0,1] neg_hi:[0,1]
	v_pk_add_f32 v[142:143], v[142:143], v[178:179] op_sel_hi:[1,0] neg_lo:[0,1] neg_hi:[0,1]
	v_pk_add_f32 v[144:145], v[144:145], v[178:179] op_sel_hi:[1,0] neg_lo:[0,1] neg_hi:[0,1]
	v_pk_add_f32 v[146:147], v[146:147], v[178:179] op_sel_hi:[1,0] neg_lo:[0,1] neg_hi:[0,1]
; DEVINL float fexp2(float x) { return __builtin_amdgcn_exp2f(x); }
; DEVINL void attn_item(const Params& p, int item, char* smem, int wv) {
;     ...
;       for (int hh = 0; hh < 2; ++hh) {
;         float mx = s[hh][0][0];
; #pragma unroll
;         for (int kq = 0; kq < 4; ++kq)
; #pragma unroll
;           for (int j = 0; j < 4; ++j) mx = fmaxf(mx, s[hh][kq][j]);
;         {
;           auto r1 = __builtin_amdgcn_permlane16_swap(__float_as_uint(mx), __float_as_uint(mx), false, false);
;           mx = fmaxf(__uint_as_float(r1[0]), __uint_as_float(r1[1]));
;           auto r2 = __builtin_amdgcn_permlane32_swap(__float_as_uint(mx), __float_as_uint(mx), false, false);
;           mx = fmaxf(__uint_as_float(r2[0]), __uint_as_float(r2[1]));
;         }
;         if (kt == 0 || __ballot(mx > 8.f)) {
;           const float delta = (kt == 0) ? mx : fmaxf(mx, 0.f);
;           const float alpha = fexp2(-delta);
;           mrun[hh] += delta;
;           lsum[hh] *= alpha;
; #pragma unroll
;           for (int dt = 0; dt < 8; ++dt) o[hh][dt] *= alpha;
; #pragma unroll
;           for (int kq = 0; kq < 4; ++kq)
; #pragma unroll
;             for (int j = 0; j < 4; ++j) s[hh][kq][j] -= delta;
.LBB0_1734:
	v_max_f32_e32 v179, v136, v136
	v_max_f32_e32 v178, v179, v137
	v_max3_f32 v178, v178, v138, v139
	v_max3_f32 v178, v178, v132, v133
	v_max3_f32 v178, v178, v134, v135
	v_max3_f32 v178, v178, v124, v125
	v_max3_f32 v178, v178, v126, v127
	v_max3_f32 v178, v178, v128, v129
	v_max3_f32 v178, v178, v130, v131
	v_mov_b32_e32 v179, v178
	s_nop 1
	v_permlane16_swap_b32_e32 v178, v179
	v_max_f32_e32 v178, v178, v179
	v_mov_b32_e32 v179, v178
	s_nop 1
	v_permlane32_swap_b32_e32 v178, v179
	v_max_f32_e32 v178, v178, v179
	v_cmp_lt_f32_e32 vcc, s28, v178
	s_cbranch_vccz .LBB0_1736
	v_max_f32_e32 v178, 0, v178
	v_exp_f32_e64 v180, -v178
	v_add_f32_e32 v2, v2, v178
	v_pk_add_f32 v[136:137], v[136:137], v[178:179] op_sel_hi:[1,0] neg_lo:[0,1] neg_hi:[0,1]
	v_pk_add_f32 v[138:139], v[138:139], v[178:179] op_sel_hi:[1,0] neg_lo:[0,1] neg_hi:[0,1]
	v_mul_f32_e32 v161, v161, v180
	v_pk_mul_f32 v[54:55], v[54:55], v[180:181] op_sel_hi:[1,0]
	v_pk_mul_f32 v[52:53], v[52:53], v[180:181] op_sel_hi:[1,0]
	v_pk_mul_f32 v[58:59], v[58:59], v[180:181] op_sel_hi:[1,0]
	v_pk_mul_f32 v[56:57], v[56:57], v[180:181] op_sel_hi:[1,0]
	v_pk_mul_f32 v[62:63], v[62:63], v[180:181] op_sel_hi:[1,0]
	v_pk_mul_f32 v[60:61], v[60:61], v[180:181] op_sel_hi:[1,0]
	v_pk_mul_f32 v[66:67], v[66:67], v[180:181] op_sel_hi:[1,0]
	v_pk_mul_f32 v[64:65], v[64:65], v[180:181] op_sel_hi:[1,0]
	v_pk_mul_f32 v[74:75], v[74:75], v[180:181] op_sel_hi:[1,0]
	v_pk_mul_f32 v[72:73], v[72:73], v[180:181] op_sel_hi:[1,0]
	v_pk_mul_f32 v[78:79], v[78:79], v[180:181] op_sel_hi:[1,0]
	v_pk_mul_f32 v[76:77], v[76:77], v[180:181] op_sel_hi:[1,0]
	v_pk_mul_f32 v[82:83], v[82:83], v[180:181] op_sel_hi:[1,0]
	v_pk_mul_f32 v[80:81], v[80:81], v[180:181] op_sel_hi:[1,0]
	v_pk_mul_f32 v[70:71], v[70:71], v[180:181] op_sel_hi:[1,0]
	v_pk_mul_f32 v[68:69], v[68:69], v[180:181] op_sel_hi:[1,0]
	v_pk_add_f32 v[132:133], v[132:133], v[178:179] op_sel_hi:[1,0] neg_lo:[0,1] neg_hi:[0,1]
	v_pk_add_f32 v[134:135], v[134:135], v[178:179] op_sel_hi:[1,0] neg_lo:[0,1] neg_hi:[0,1]
	v_pk_add_f32 v[124:125], v[124:125], v[178:179] op_sel_hi:[1,0] neg_lo:[0,1] neg_hi:[0,1]
	v_pk_add_f32 v[126:127], v[126:127], v[178:179] op_sel_hi:[1,0] neg_lo:[0,1] neg_hi:[0,1]
	v_pk_add_f32 v[128:129], v[128:129], v[178:179] op_sel_hi:[1,0] neg_lo:[0,1] neg_hi:[0,1]
	v_pk_add_f32 v[130:131], v[130:131], v[178:179] op_sel_hi:[1,0] neg_lo:[0,1] neg_hi:[0,1]
